# prep gate loops: hipcc's packed v_pk_fma/mul/add_f32 split into scalar pairs (packed f32 is slower than two scalar ops here); bit-identical
# baseline (speedup 1.0000x reference)
; DI float bf2f(bf16_t b) { return __uint_as_float(((unsigned)b) << 16); }
; DI unsigned pk2(float lo, float hi) { f32x2 v = {lo, hi}; bfv2 b = __builtin_convertvector(v, bfv2); return __builtin_bit_cast(unsigned, b); }
; DI void prep_load(PrepIn& I, const Params& p, int j, int item, int tid) {
;     ...
;     const int c = item >> 2, h = item & 3; const size_t row0 = (size_t)c * 64;
;     const int dir = tid >> 8, kk = tid & 255;
;     { const int t = tid >> 3, sg = tid & 7; I.rr = *(const u32x2*)(H + (row0 + t) * HE + 8192 + sg * 4); }
;     const float* wgf = p.in[9]; const float* wgb = p.in[11]; const float* bgf = p.in[10]; const float* bgb = p.in[12];
;     const float* wg = (dir ? wgb : wgf) + (size_t)j * 16 * 1024 + h * 256 + kk;
; #pragma unroll
;     for (int i = 0; i < 16; ++i) I.w[i] = wg[i * 1024];
;     I.bias = (dir ? bgb : bgf)[j * 1024 + h * 256 + kk];
; #pragma unroll
;     for (int it = 0; it < 4; ++it) { const int idx = it * 512 + tid; const int t = idx >> 5, seg = idx & 31;
;         I.q[it] = *(const u32x4*)(H + (row0 + t) * HE + 2048 + h * 256 + seg * 8);
;         I.k[it] = *(const u32x4*)(H + (row0 + t) * HE + h * 256 + seg * 8);
;         I.v[it] = *(const u32x4*)(H + (row0 + t) * HE + 1024 + h * 256 + seg * 8); }
; DI void phase_prep(const Params& p, int j, unsigned char* lds) {
;     ...
;         ((float*)(p.ws + WS_DD))[(size_t)(item * 2 + dir) * 256 + kk] = dlast;
;         { const int nitem = item + (int)gridDim.x; prep_load(I, p, j, nitem < NCH * 4 ? nitem : item, tid); }
;         {
;             bf16_t* KHp = (bf16_t*)(p.ws + WS_KH) + (size_t)(item * 2 + dir) * 16384;
;             const int w8 = kk >> 5, r = kk & 31;
; #pragma unroll
;             for (int tg = 0; tg < 8; ++tg) {
;                 float val[8];
; #pragma unroll
;                 for (int i = 0; i < 8; ++i) val[i] = bf2f(kt[(dir * 64 + 8 * tg + i) * 264 + kk]) * dlast;
;                 u32x4 pk; pk.x = pk2(val[0], val[1]); pk.y = pk2(val[2], val[3]); pk.z = pk2(val[4], val[5]); pk.w = pk2(val[6], val[7]);
;                 const int s = tg >> 1, hh = tg & 1;
;                 *(u32x4*)(KHp + ((w8 * 4 + s) * 64 + hh * 32 + r) * 8) = pk;
.LBB0_353:
	s_or_b64 exec, exec, s[56:57]
	s_lshl_b32 s58, s54, 1
	s_add_i32 s81, s54, s71
	s_cmpk_lt_i32 s81, 0x820
	s_cselect_b64 s[56:57], -1, 0
	s_and_b64 s[60:61], s[56:57], exec
	v_add_u32_e32 v116, s58, v1
	s_cselect_b32 s52, s81, s54
	v_ashrrev_i32_e32 v117, 31, v116
	s_ashr_i32 s60, s52, 2
	v_lshlrev_b64 v[18:19], 10, v[116:117]
	s_ashr_i32 s61, s60, 31
	v_lshl_add_u64 v[18:19], v[94:95], 0, v[18:19]
	s_lshl_b64 s[60:61], s[60:61], 6
	global_store_dword v[18:19], v112, off
	v_lshl_add_u64 v[18:19], s[60:61], 0, v[66:67]
	v_mov_b64_e32 v[38:39], s[50:51]
	v_mad_u64_u32 v[20:21], s[82:83], v18, s33, v[38:39]
	v_mad_i32_i24 v21, v19, s33, v21
	v_lshl_add_u64 v[18:19], v[20:21], 0, v[68:69]
	s_lshl_b32 s52, s52, 8
	v_add_co_u32_e32 v18, vcc, s62, v18
	s_and_b32 s55, s52, 0x300
	s_nop 0
	v_addc_co_u32_e32 v19, vcc, 0, v19, vcc
	s_lshl_b32 s52, s55, 2
	global_load_dwordx2 v[114:115], v[18:19], off
	v_lshl_add_u64 v[18:19], v[96:97], 0, s[52:53]
	v_add_co_u32_e32 v20, vcc, s64, v18
	s_lshl_b32 s52, s55, 1
	s_nop 0
	v_addc_co_u32_e32 v21, vcc, 0, v19, vcc
	v_add_co_u32_e32 v22, vcc, s62, v18
	v_mov_b32_e32 v101, v69
	s_nop 0
	v_addc_co_u32_e32 v23, vcc, 0, v19, vcc
	v_add_co_u32_e32 v24, vcc, s65, v18
	v_lshlrev_b64 v[116:117], 15, v[116:117]
	s_nop 0
	v_addc_co_u32_e32 v25, vcc, 0, v19, vcc
	v_add_co_u32_e32 v26, vcc, s66, v18
	s_ashr_i32 s59, s58, 31
	s_nop 0
	v_addc_co_u32_e32 v27, vcc, 0, v19, vcc
	global_load_dword v76, v[20:21], off offset:-4096
	global_load_dword v83, v[20:21], off
	global_load_dword v77, v[22:23], off offset:-4096
	global_load_dword v74, v[22:23], off
	global_load_dword v78, v[24:25], off offset:-4096
	global_load_dword v75, v[24:25], off
	global_load_dword v79, v[26:27], off offset:-4096
	global_load_dword v80, v[26:27], off
	v_add_co_u32_e32 v20, vcc, s67, v18
	s_nop 1
	v_addc_co_u32_e32 v21, vcc, 0, v19, vcc
	v_add_co_u32_e32 v22, vcc, s68, v18
	s_nop 1
	v_addc_co_u32_e32 v23, vcc, 0, v19, vcc
	v_add_co_u32_e32 v24, vcc, s69, v18
	s_nop 1
	v_addc_co_u32_e32 v25, vcc, 0, v19, vcc
	global_load_dword v90, v[20:21], off offset:-4096
	global_load_dword v81, v[20:21], off
	global_load_dword v91, v[22:23], off offset:-4096
	global_load_dword v88, v[22:23], off
	global_load_dword v92, v[24:25], off offset:-4096
	global_load_dword v89, v[24:25], off
	v_add_co_u32_e32 v20, vcc, s70, v18
	s_nop 1
	v_addc_co_u32_e32 v21, vcc, 0, v19, vcc
	global_load_dword v85, v[18:19], off
	global_load_dword v93, v[20:21], off
	v_or_b32_sdwa v18, s55, v254 dst_sel:DWORD dst_unused:UNUSED_PAD src0_sel:DWORD src1_sel:BYTE_0
	v_lshlrev_b32_e32 v18, 2, v18
	v_mov_b32_e32 v19, v69
	v_lshl_add_u64 v[18:19], v[70:71], 0, v[18:19]
	global_load_dword v123, v[18:19], off
	v_or_b32_e32 v18, s60, v72
	v_mad_u64_u32 v[18:19], s[82:83], v18, s33, v[38:39]
	v_mad_i32_i24 v19, s61, v73, v19
	v_lshl_add_u64 v[18:19], v[18:19], 0, s[52:53]
	v_lshl_add_u64 v[22:23], v[18:19], 0, v[100:101]
	v_add_co_u32_e32 v24, vcc, s63, v22
	global_load_dwordx4 v[18:21], v[22:23], off
	global_load_dwordx4 v[50:53], v[22:23], off offset:2048
	v_or_b32_e32 v22, s60, v82
	v_addc_co_u32_e32 v25, vcc, 0, v23, vcc
	v_mad_u64_u32 v[22:23], s[82:83], v22, s33, v[38:39]
	v_mad_i32_i24 v23, s61, v73, v23
	v_lshl_add_u64 v[22:23], v[22:23], 0, s[52:53]
	v_lshl_add_u64 v[34:35], v[22:23], 0, v[100:101]
	v_add_co_u32_e32 v30, vcc, s63, v34
	s_nop 1
	v_addc_co_u32_e32 v31, vcc, 0, v35, vcc
	global_load_dwordx4 v[22:25], v[24:25], off
	s_nop 0
	global_load_dwordx4 v[26:29], v[34:35], off
	s_nop 0
	global_load_dwordx4 v[30:33], v[30:31], off
	s_nop 0
	global_load_dwordx4 v[54:57], v[34:35], off offset:2048
	v_or_b32_e32 v34, s60, v84
	v_mad_u64_u32 v[34:35], s[82:83], v34, s33, v[38:39]
	v_mad_i32_i24 v35, s61, v73, v35
	v_lshl_add_u64 v[34:35], v[34:35], 0, s[52:53]
	v_lshl_add_u64 v[40:41], v[34:35], 0, v[100:101]
	v_add_co_u32_e32 v42, vcc, s63, v40
	global_load_dwordx4 v[34:37], v[40:41], off
	global_load_dwordx4 v[58:61], v[40:41], off offset:2048
	v_addc_co_u32_e32 v43, vcc, 0, v41, vcc
	v_lshl_add_u64 v[40:41], s[60:61], 0, v[86:87]
	v_mad_u64_u32 v[38:39], s[60:61], v40, s33, v[38:39]
	v_mad_i32_i24 v39, v41, s33, v39
	v_lshl_add_u64 v[38:39], v[38:39], 0, s[52:53]
	v_lshl_add_u64 v[62:63], v[38:39], 0, v[100:101]
	v_add_co_u32_e32 v46, vcc, s63, v62
	s_lshl_b64 s[60:61], s[58:59], 15
	s_nop 0
	v_addc_co_u32_e32 v47, vcc, 0, v63, vcc
	global_load_dwordx4 v[38:41], v[42:43], off
	s_nop 0
	global_load_dwordx4 v[42:45], v[62:63], off
	s_nop 0
	global_load_dwordx4 v[46:49], v[46:47], off
	s_nop 0
	global_load_dwordx4 v[62:65], v[62:63], off offset:2048
	ds_read_u16 v101, v134
	ds_read_u16 v103, v134 offset:528
	ds_read_u16 v105, v134 offset:1056
	ds_read_u16 v107, v134 offset:1584
	ds_read_u16 v109, v134 offset:2112
	ds_read_u16 v111, v134 offset:2640
	ds_read_u16 v162, v134 offset:3168
	s_waitcnt lgkmcnt(4)
	v_lshlrev_b32_e32 v156, 16, v105
	s_waitcnt lgkmcnt(3)
	v_lshlrev_b32_e32 v157, 16, v107
	v_lshlrev_b32_e32 v119, 16, v103
	ds_read_u16 v103, v134 offset:33264
	v_lshlrev_b32_e32 v118, 16, v101
	v_mul_f32_e32 v159, v112, v157
	v_mul_f32_e32 v158, v112, v156
	s_waitcnt lgkmcnt(2)
	v_lshlrev_b32_e32 v157, 16, v111
	v_lshlrev_b32_e32 v156, 16, v109
	ds_read_u16 v101, v134 offset:3696
	ds_read_u16 v105, v134 offset:4224
	ds_read_u16 v107, v134 offset:4752
	ds_read_u16 v109, v134 offset:5280
	ds_read_u16 v111, v134 offset:5808
	ds_read_u16 v164, v134 offset:6336
	ds_read_u16 v165, v134 offset:6864
	ds_read_u16 v166, v134 offset:7392
	v_mul_f32_e32 v161, v112, v157
	v_mul_f32_e32 v160, v112, v156
	s_waitcnt lgkmcnt(7)
; DI float bf2f(bf16_t b) { return __uint_as_float(((unsigned)b) << 16); }
; DI unsigned pk2(float lo, float hi) { f32x2 v = {lo, hi}; bfv2 b = __builtin_convertvector(v, bfv2); return __builtin_bit_cast(unsigned, b); }
; DI void phase_prep(const Params& p, int j, unsigned char* lds) {
;     ...
;             for (int tg = 0; tg < 8; ++tg) {
;                 float val[8];
; #pragma unroll
;                 for (int i = 0; i < 8; ++i) val[i] = bf2f(kt[(dir * 64 + 8 * tg + i) * 264 + kk]) * dlast;
;                 u32x4 pk; pk.x = pk2(val[0], val[1]); pk.y = pk2(val[2], val[3]); pk.z = pk2(val[4], val[5]); pk.w = pk2(val[6], val[7]);
;                 const int s = tg >> 1, hh = tg & 1;
;                 *(u32x4*)(KHp + ((w8 * 4 + s) * 64 + hh * 32 + r) * 8) = pk;
	v_lshlrev_b32_e32 v157, 16, v101
	v_lshlrev_b32_e32 v156, 16, v162
	v_mul_f32_e32 v119, v112, v119
	v_mul_f32_e32 v118, v112, v118
	v_mul_f32_e32 v163, v112, v157
	v_mul_f32_e32 v162, v112, v156
	v_cvt_pk_bf16_f32 v156, v118, v119
	v_cvt_pk_bf16_f32 v157, v158, v159
	v_cvt_pk_bf16_f32 v158, v160, v161
	v_cvt_pk_bf16_f32 v159, v162, v163
	v_lshl_add_u64 v[160:161], v[98:99], 0, v[116:117]
	global_store_dwordx4 v[160:161], v[156:159], off
	s_waitcnt lgkmcnt(5)
	v_lshlrev_b32_e32 v117, 16, v107
	v_lshlrev_b32_e32 v116, 16, v105
	s_waitcnt lgkmcnt(3)
	v_lshlrev_b32_e32 v119, 16, v111
	v_lshlrev_b32_e32 v118, 16, v109
	s_waitcnt lgkmcnt(1)
	v_lshlrev_b32_e32 v157, 16, v165
	v_lshlrev_b32_e32 v156, 16, v164
	ds_read_u16 v101, v134 offset:7920
	ds_read_u16 v105, v134 offset:8448
	ds_read_u16 v107, v134 offset:8976
	ds_read_u16 v109, v134 offset:9504
	ds_read_u16 v111, v134 offset:10032
	ds_read_u16 v162, v134 offset:10560
	ds_read_u16 v163, v134 offset:11088
	ds_read_u16 v164, v134 offset:11616
	s_waitcnt lgkmcnt(7)
	v_lshlrev_b32_e32 v159, 16, v101
	v_lshlrev_b32_e32 v158, 16, v166
	v_mul_f32_e32 v117, v112, v117
	v_mul_f32_e32 v116, v112, v116
	v_mul_f32_e32 v119, v112, v119
	v_mul_f32_e32 v118, v112, v118
	v_mul_f32_e32 v157, v112, v157
	v_mul_f32_e32 v156, v112, v156
	v_mul_f32_e32 v159, v112, v159
	v_mul_f32_e32 v158, v112, v158
	v_cvt_pk_bf16_f32 v116, v116, v117
	v_cvt_pk_bf16_f32 v117, v118, v119
	v_cvt_pk_bf16_f32 v118, v156, v157
	v_cvt_pk_bf16_f32 v119, v158, v159
	global_store_dwordx4 v[160:161], v[116:119], off offset:512
	s_waitcnt lgkmcnt(1)
	v_lshlrev_b32_e32 v157, 16, v163
	v_lshlrev_b32_e32 v156, 16, v162
	v_lshlrev_b32_e32 v117, 16, v107
	v_lshlrev_b32_e32 v116, 16, v105
	v_lshlrev_b32_e32 v119, 16, v111
	v_lshlrev_b32_e32 v118, 16, v109
	ds_read_u16 v101, v134 offset:12144
	ds_read_u16 v105, v134 offset:12672
	ds_read_u16 v107, v134 offset:13200
	ds_read_u16 v109, v134 offset:13728
	ds_read_u16 v111, v134 offset:14256
	ds_read_u16 v162, v134 offset:14784
	ds_read_u16 v163, v134 offset:15312
	ds_read_u16 v165, v134 offset:15840
	s_waitcnt lgkmcnt(7)
	v_lshlrev_b32_e32 v159, 16, v101
	v_lshlrev_b32_e32 v158, 16, v164
	v_mul_f32_e32 v117, v112, v117
	v_mul_f32_e32 v116, v112, v116
	v_mul_f32_e32 v119, v112, v119
	v_mul_f32_e32 v118, v112, v118
	v_mul_f32_e32 v157, v112, v157
	v_mul_f32_e32 v156, v112, v156
	v_mul_f32_e32 v159, v112, v159
	v_mul_f32_e32 v158, v112, v158
	v_cvt_pk_bf16_f32 v116, v116, v117
	v_cvt_pk_bf16_f32 v117, v118, v119
	v_cvt_pk_bf16_f32 v118, v156, v157
	v_cvt_pk_bf16_f32 v119, v158, v159
	global_store_dwordx4 v[160:161], v[116:119], off offset:1024
	s_waitcnt lgkmcnt(1)
	v_lshlrev_b32_e32 v157, 16, v163
	v_lshlrev_b32_e32 v156, 16, v162
	v_lshlrev_b32_e32 v117, 16, v107
	v_lshlrev_b32_e32 v116, 16, v105
	v_lshlrev_b32_e32 v119, 16, v111
	v_lshlrev_b32_e32 v118, 16, v109
	ds_read_u16 v101, v134 offset:16368
	ds_read_u16 v105, v134 offset:16896
	ds_read_u16 v107, v134 offset:17424
	ds_read_u16 v109, v134 offset:17952
	ds_read_u16 v111, v134 offset:18480
	ds_read_u16 v162, v134 offset:19008
	ds_read_u16 v163, v134 offset:19536
	ds_read_u16 v164, v134 offset:20064
	s_waitcnt lgkmcnt(7)
	v_lshlrev_b32_e32 v159, 16, v101
	v_lshlrev_b32_e32 v158, 16, v165
	v_mul_f32_e32 v117, v112, v117
	v_mul_f32_e32 v116, v112, v116
	v_mul_f32_e32 v119, v112, v119
	v_mul_f32_e32 v118, v112, v118
	v_mul_f32_e32 v157, v112, v157
	v_mul_f32_e32 v156, v112, v156
	v_mul_f32_e32 v159, v112, v159
	v_mul_f32_e32 v158, v112, v158
	v_cvt_pk_bf16_f32 v116, v116, v117
	v_cvt_pk_bf16_f32 v117, v118, v119
	v_cvt_pk_bf16_f32 v118, v156, v157
	v_cvt_pk_bf16_f32 v119, v158, v159
	global_store_dwordx4 v[160:161], v[116:119], off offset:1536
	s_waitcnt lgkmcnt(1)
	v_lshlrev_b32_e32 v157, 16, v163
	v_lshlrev_b32_e32 v156, 16, v162
	v_lshlrev_b32_e32 v117, 16, v107
	v_lshlrev_b32_e32 v116, 16, v105
	v_lshlrev_b32_e32 v119, 16, v111
	v_lshlrev_b32_e32 v118, 16, v109
	ds_read_u16 v101, v134 offset:20592
	ds_read_u16 v105, v134 offset:21120
	ds_read_u16 v107, v134 offset:21648
	ds_read_u16 v109, v134 offset:22176
	ds_read_u16 v111, v134 offset:22704
	ds_read_u16 v162, v134 offset:23232
	ds_read_u16 v163, v134 offset:23760
	ds_read_u16 v165, v134 offset:24288
	s_waitcnt lgkmcnt(7)
	v_lshlrev_b32_e32 v159, 16, v101
	v_lshlrev_b32_e32 v158, 16, v164
	v_mul_f32_e32 v117, v112, v117
	v_mul_f32_e32 v116, v112, v116
	v_mul_f32_e32 v119, v112, v119
	v_mul_f32_e32 v118, v112, v118
	v_mul_f32_e32 v157, v112, v157
	v_mul_f32_e32 v156, v112, v156
	v_mul_f32_e32 v159, v112, v159
	v_mul_f32_e32 v158, v112, v158
	v_cvt_pk_bf16_f32 v116, v116, v117
	v_cvt_pk_bf16_f32 v117, v118, v119
	v_cvt_pk_bf16_f32 v118, v156, v157
	v_cvt_pk_bf16_f32 v119, v158, v159
	global_store_dwordx4 v[160:161], v[116:119], off offset:2048
	s_waitcnt lgkmcnt(1)
	v_lshlrev_b32_e32 v157, 16, v163
	v_lshlrev_b32_e32 v156, 16, v162
	v_lshlrev_b32_e32 v117, 16, v107
	v_lshlrev_b32_e32 v116, 16, v105
	v_lshlrev_b32_e32 v119, 16, v111
	v_lshlrev_b32_e32 v118, 16, v109
	ds_read_u16 v101, v134 offset:24816
	ds_read_u16 v105, v134 offset:25344
	ds_read_u16 v107, v134 offset:25872
	ds_read_u16 v109, v134 offset:26400
	ds_read_u16 v111, v134 offset:26928
	ds_read_u16 v162, v134 offset:27456
	ds_read_u16 v163, v134 offset:27984
	ds_read_u16 v164, v134 offset:28512
	s_waitcnt lgkmcnt(7)
	v_lshlrev_b32_e32 v159, 16, v101
	v_lshlrev_b32_e32 v158, 16, v165
	v_mul_f32_e32 v117, v112, v117
	v_mul_f32_e32 v116, v112, v116
	v_mul_f32_e32 v119, v112, v119
	v_mul_f32_e32 v118, v112, v118
	v_mul_f32_e32 v157, v112, v157
	v_mul_f32_e32 v156, v112, v156
	v_mul_f32_e32 v159, v112, v159
	v_mul_f32_e32 v158, v112, v158
	v_cvt_pk_bf16_f32 v116, v116, v117
	v_cvt_pk_bf16_f32 v117, v118, v119
	v_cvt_pk_bf16_f32 v118, v156, v157
	v_cvt_pk_bf16_f32 v119, v158, v159
	global_store_dwordx4 v[160:161], v[116:119], off offset:2560
	s_waitcnt lgkmcnt(1)
; DI float bf2f(bf16_t b) { return __uint_as_float(((unsigned)b) << 16); }
; DI unsigned pk2(float lo, float hi) { f32x2 v = {lo, hi}; bfv2 b = __builtin_convertvector(v, bfv2); return __builtin_bit_cast(unsigned, b); }
; DI void phase_prep(const Params& p, int j, unsigned char* lds) {
;     ...
;             for (int tg = 0; tg < 8; ++tg) {
;                 float val[8];
; #pragma unroll
;                 for (int i = 0; i < 8; ++i) val[i] = bf2f(kt[(dir * 64 + 8 * tg + i) * 264 + kk]) * dlast;
;                 u32x4 pk; pk.x = pk2(val[0], val[1]); pk.y = pk2(val[2], val[3]); pk.z = pk2(val[4], val[5]); pk.w = pk2(val[6], val[7]);
;                 const int s = tg >> 1, hh = tg & 1;
;                 *(u32x4*)(KHp + ((w8 * 4 + s) * 64 + hh * 32 + r) * 8) = pk;
;     ...
;         {
;             bf16_t* QTp = (bf16_t*)(p.ws + WS_U) + (size_t)(item * 2) * 16384;
; #pragma unroll
;             for (int it = 0; it < 8; ++it) {
;                 const int idx = it * 512 + tid; const int d2 = idx >> 11, f = (idx >> 6) & 31, ln = idx & 63;
;                 const int w8 = f >> 2, mb = (f >> 1) & 1, s = f & 1, rr = ln & 31, hh = ln >> 5;
;                 const bf16_t* sp = qt + (d2 * 64 + 32 * mb + rr) * 264 + 32 * w8 + 16 * s + 4 * hh;
;                 const u32x2 lo = *(const u32x2*)sp, hi = *(const u32x2*)(sp + 8);
;                 u32x4 o; o.x = lo.x; o.y = lo.y; o.z = hi.x; o.w = hi.y;
;                 *(u32x4*)(QTp + (size_t)d2 * 16384 + (f * 64 + ln) * 8) = o;
;             }
;         }
;         float amask[4][4];
;         {
;             const int d2 = wave >> 2, wd = wave & 3, fr = lane & 15, fq = lane >> 4;
;             f32x4 acc[4];
; #pragma unroll
;             for (int nb = 0; nb < 4; ++nb) acc[nb] = (f32x4){0.f, 0.f, 0.f, 0.f};
;             const bf16_t* qb = qt + (d2 * 64 + 16 * wd + fr) * 264 + 8 * fq;
;             const bf16_t* kb = kt + (d2 * 64 + fr) * 264 + 8 * fq;
; #pragma unroll
;             for (int ks = 0; ks < 8; ++ks) {
;                 const bf16x8 a = *(const bf16x8*)(qb + 32 * ks);
; #pragma unroll
;                 for (int nb = 0; nb < 4; ++nb) { const bf16x8 b = *(const bf16x8*)(kb + nb * 16 * 264 + 32 * ks); acc[nb] = __builtin_amdgcn_mfma_f32_16x16x32_bf16(a, b, acc[nb], 0, 0, 0); }
	v_lshlrev_b32_e32 v157, 16, v163
	v_lshlrev_b32_e32 v156, 16, v162
	v_lshlrev_b32_e32 v117, 16, v107
	v_lshlrev_b32_e32 v116, 16, v105
	v_lshlrev_b32_e32 v119, 16, v111
	v_lshlrev_b32_e32 v118, 16, v109
	ds_read_u16 v101, v134 offset:29040
	ds_read_u16 v105, v134 offset:29568
	ds_read_u16 v107, v134 offset:30096
	ds_read_u16 v109, v134 offset:30624
	ds_read_u16 v111, v134 offset:31152
	ds_read_u16 v162, v134 offset:31680
	ds_read_u16 v163, v134 offset:32208
	ds_read_u16 v165, v134 offset:32736
	s_waitcnt lgkmcnt(7)
	v_lshlrev_b32_e32 v159, 16, v101
	v_lshlrev_b32_e32 v158, 16, v164
	v_mul_f32_e32 v117, v112, v117
	v_mul_f32_e32 v116, v112, v116
	v_mul_f32_e32 v119, v112, v119
	v_mul_f32_e32 v118, v112, v118
	v_mul_f32_e32 v157, v112, v157
	v_mul_f32_e32 v156, v112, v156
	v_mul_f32_e32 v159, v112, v159
	v_mul_f32_e32 v158, v112, v158
	v_cvt_pk_bf16_f32 v116, v116, v117
	v_cvt_pk_bf16_f32 v117, v118, v119
	v_cvt_pk_bf16_f32 v118, v156, v157
	v_cvt_pk_bf16_f32 v119, v158, v159
	global_store_dwordx4 v[160:161], v[116:119], off offset:3072
	s_waitcnt lgkmcnt(1)
	v_lshlrev_b32_e32 v157, 16, v163
	v_lshlrev_b32_e32 v156, 16, v162
	v_lshlrev_b32_e32 v117, 16, v107
	v_lshlrev_b32_e32 v116, 16, v105
	v_lshlrev_b32_e32 v119, 16, v111
	v_lshlrev_b32_e32 v118, 16, v109
	v_lshlrev_b32_e32 v159, 16, v103
	s_waitcnt lgkmcnt(0)
	v_lshlrev_b32_e32 v158, 16, v165
	v_mul_f32_e32 v117, v112, v117
	v_mul_f32_e32 v116, v112, v116
	v_mul_f32_e32 v119, v112, v119
	v_mul_f32_e32 v118, v112, v118
	v_mul_f32_e32 v157, v112, v157
	v_mul_f32_e32 v156, v112, v156
	v_mul_f32_e32 v159, v112, v159
	v_mul_f32_e32 v158, v112, v158
	v_cvt_pk_bf16_f32 v116, v116, v117
	v_cvt_pk_bf16_f32 v117, v118, v119
	v_cvt_pk_bf16_f32 v118, v156, v157
	v_cvt_pk_bf16_f32 v119, v158, v159
	global_store_dwordx4 v[160:161], v[116:119], off offset:3584
	s_barrier
	ds_read_b128 v[116:119], v121 offset:8192
	ds_read_b128 v[156:159], v122
	ds_read_b128 v[160:163], v121 offset:8256
	ds_read_b128 v[164:167], v122 offset:64
	ds_read_b128 v[168:171], v122 offset:8448
	ds_read_b128 v[172:175], v122 offset:8512
	s_waitcnt lgkmcnt(4)
	v_mfma_f32_16x16x32_bf16 v[156:159], v[116:119], v[156:159], 0
	ds_read_b128 v[176:179], v122 offset:16896
	ds_read_b128 v[180:183], v122 offset:16960
	ds_read_b128 v[184:187], v122 offset:25344
	ds_read_b128 v[188:191], v122 offset:25408
	v_add_u32_e32 v101, 0x2000, v135
	s_waitcnt lgkmcnt(5)
	v_mfma_f32_16x16x32_bf16 v[168:171], v[116:119], v[168:171], 0
	s_add_u32 s60, s72, s60
	s_addc_u32 s61, s73, s61
	v_mov_b32_e32 v105, v69
	v_mfma_f32_16x16x32_bf16 v[156:159], v[160:163], v[164:167], v[156:159]
	v_mov_b32_e32 v107, v69
	s_add_u32 s82, s60, 0x8000
	s_addc_u32 s83, s61, 0
	s_waitcnt lgkmcnt(4)
	v_mfma_f32_16x16x32_bf16 v[164:167], v[160:163], v[172:175], v[168:171]
	ds_read_b128 v[172:175], v121 offset:8320
	v_mov_b32_e32 v109, v69
	v_mov_b32_e32 v111, v69
	s_waitcnt lgkmcnt(4)
	v_mfma_f32_16x16x32_bf16 v[176:179], v[116:119], v[176:179], 0
	s_lshl_b64 s[58:59], s[58:59], 13
	s_add_u32 s58, s74, s58
	v_mov_b32_e32 v103, v69
	s_waitcnt lgkmcnt(2)
	v_mfma_f32_16x16x32_bf16 v[116:119], v[116:119], v[184:187], 0
	s_addc_u32 s59, s75, s59
	s_ashr_i32 s55, s54, 31
	s_lshl_b64 s[54:55], s[54:55], 15
	v_mfma_f32_16x16x32_bf16 v[168:171], v[160:163], v[180:183], v[176:179]
	s_add_u32 s54, s76, s54
	s_addc_u32 s55, s77, s55
	s_waitcnt lgkmcnt(1)
	v_mfma_f32_16x16x32_bf16 v[116:119], v[160:163], v[188:191], v[116:119]
	ds_read_b128 v[160:163], v122 offset:128
	ds_read_b128 v[176:179], v121 offset:8384
	ds_read_b128 v[180:183], v122 offset:192
	s_waitcnt lgkmcnt(2)
	v_mfma_f32_16x16x32_bf16 v[156:159], v[172:175], v[160:163], v[156:159]
	ds_read_b128 v[160:163], v122 offset:8576
	ds_read_b128 v[184:187], v122 offset:8640
	s_waitcnt lgkmcnt(1)
	v_mfma_f32_16x16x32_bf16 v[160:163], v[172:175], v[160:163], v[164:167]
	s_nop 2
	ds_read_b128 v[164:167], v122 offset:17024
	ds_read_b128 v[188:191], v122 offset:17088
	s_waitcnt lgkmcnt(1)
	v_mfma_f32_16x16x32_bf16 v[164:167], v[172:175], v[164:167], v[168:171]
	s_nop 2
	ds_read_b128 v[168:171], v122 offset:25472
	ds_read_b128 v[192:195], v122 offset:25536
	s_waitcnt lgkmcnt(1)
	v_mfma_f32_16x16x32_bf16 v[116:119], v[172:175], v[168:171], v[116:119]
	ds_read_b128 v[168:171], v121 offset:8448
	ds_read_b128 v[172:175], v122 offset:256
	v_mfma_f32_16x16x32_bf16 v[156:159], v[176:179], v[180:183], v[156:159]
	v_mfma_f32_16x16x32_bf16 v[160:163], v[176:179], v[184:187], v[160:163]
	v_mfma_f32_16x16x32_bf16 v[164:167], v[176:179], v[188:191], v[164:167]
	s_waitcnt lgkmcnt(2)
	v_mfma_f32_16x16x32_bf16 v[116:119], v[176:179], v[192:195], v[116:119]
	ds_read_b128 v[176:179], v122 offset:8704
	ds_read_b128 v[180:183], v121 offset:8512
	ds_read_b128 v[184:187], v122 offset:320
	s_waitcnt lgkmcnt(3)
	v_mfma_f32_16x16x32_bf16 v[156:159], v[168:171], v[172:175], v[156:159]
	ds_read_b128 v[172:175], v122 offset:17152
	ds_read_b128 v[188:191], v122 offset:8768
	s_waitcnt lgkmcnt(4)
	v_mfma_f32_16x16x32_bf16 v[160:163], v[168:171], v[176:179], v[160:163]
	ds_read_b128 v[176:179], v122 offset:25600
	ds_read_b128 v[192:195], v122 offset:17216
	s_waitcnt lgkmcnt(3)
	v_mfma_f32_16x16x32_bf16 v[164:167], v[168:171], v[172:175], v[164:167]
	ds_read2_b64 v[172:175], v101 offset1:2
	ds_read2_b64 v[196:199], v150 offset1:2
	ds_read_b128 v[200:203], v122 offset:25664
	v_add_u32_e32 v101, 0xa000, v135
	s_waitcnt lgkmcnt(2)
	global_store_dwordx4 v102, v[172:175], s[60:61]
	v_mfma_f32_16x16x32_bf16 v[116:119], v[168:171], v[176:179], v[116:119]
	ds_read2_b64 v[168:171], v151 offset1:2
	s_waitcnt lgkmcnt(2)
	global_store_dwordx4 v140, v[196:199], s[60:61]
	s_waitcnt lgkmcnt(0)
; DI void phase_prep(const Params& p, int j, unsigned char* lds) {
;     ...
;         {
;             bf16_t* QTp = (bf16_t*)(p.ws + WS_U) + (size_t)(item * 2) * 16384;
; #pragma unroll
;             for (int it = 0; it < 8; ++it) {
;                 const int idx = it * 512 + tid; const int d2 = idx >> 11, f = (idx >> 6) & 31, ln = idx & 63;
;                 const int w8 = f >> 2, mb = (f >> 1) & 1, s = f & 1, rr = ln & 31, hh = ln >> 5;
;                 const bf16_t* sp = qt + (d2 * 64 + 32 * mb + rr) * 264 + 32 * w8 + 16 * s + 4 * hh;
;                 const u32x2 lo = *(const u32x2*)sp, hi = *(const u32x2*)(sp + 8);
;                 u32x4 o; o.x = lo.x; o.y = lo.y; o.z = hi.x; o.w = hi.y;
;                 *(u32x4*)(QTp + (size_t)d2 * 16384 + (f * 64 + ln) * 8) = o;
;             }
;         }
;         float amask[4][4];
;         {
;             const int d2 = wave >> 2, wd = wave & 3, fr = lane & 15, fq = lane >> 4;
;             f32x4 acc[4];
; #pragma unroll
;             for (int nb = 0; nb < 4; ++nb) acc[nb] = (f32x4){0.f, 0.f, 0.f, 0.f};
;             const bf16_t* qb = qt + (d2 * 64 + 16 * wd + fr) * 264 + 8 * fq;
;             const bf16_t* kb = kt + (d2 * 64 + fr) * 264 + 8 * fq;
; #pragma unroll
;             for (int ks = 0; ks < 8; ++ks) {
;                 const bf16x8 a = *(const bf16x8*)(qb + 32 * ks);
; #pragma unroll
;                 for (int nb = 0; nb < 4; ++nb) { const bf16x8 b = *(const bf16x8*)(kb + nb * 16 * 264 + 32 * ks); acc[nb] = __builtin_amdgcn_mfma_f32_16x16x32_bf16(a, b, acc[nb], 0, 0, 0); }
;             }
; #pragma unroll
;             for (int nb = 0; nb < 4; ++nb)
; #pragma unroll
;                 for (int jx = 0; jx < 4; ++jx) {
;                     const int i = 16 * wd + 4 * fq + jx, jt = 16 * nb + fr;
;                     const bool keep = d2 ? (jt >= i) : (jt <= i);
;                     amask[nb][jx] = keep ? acc[nb][jx] : 0.f;
;                 }
;         }
	global_store_dwordx4 v141, v[168:171], s[60:61]
	ds_read_b128 v[172:175], v121 offset:8576
	ds_read2_b64 v[168:171], v152 offset1:2
	v_lshl_add_u64 v[176:177], s[60:61], 0, v[104:105]
	v_mfma_f32_16x16x32_bf16 v[164:167], v[180:183], v[192:195], v[164:167]
	v_lshl_add_u64 v[192:193], v[176:177], 0, v[106:107]
	ds_read_b128 v[176:179], v122 offset:384
	v_mfma_f32_16x16x32_bf16 v[156:159], v[180:183], v[184:187], v[156:159]
	v_mfma_f32_16x16x32_bf16 v[160:163], v[180:183], v[188:191], v[160:163]
	v_mfma_f32_16x16x32_bf16 v[116:119], v[180:183], v[200:203], v[116:119]
	ds_read_b128 v[180:183], v122 offset:8832
	ds_read_b128 v[184:187], v121 offset:8640
	ds_read_b128 v[188:191], v122 offset:448
	s_waitcnt lgkmcnt(4)
	global_store_dwordx4 v[192:193], v[168:171], off
	s_waitcnt lgkmcnt(3)
	v_mfma_f32_16x16x32_bf16 v[156:159], v[172:175], v[176:179], v[156:159]
	ds_read_b128 v[168:171], v122 offset:17280
	ds_read_b128 v[176:179], v122 offset:8896
	s_waitcnt lgkmcnt(4)
	v_mfma_f32_16x16x32_bf16 v[160:163], v[172:175], v[180:183], v[160:163]
	ds_read_b128 v[180:183], v122 offset:25728
	ds_read_b128 v[192:195], v122 offset:17344
	ds_read_b128 v[196:199], v122 offset:25792
	s_waitcnt lgkmcnt(4)
	v_mfma_f32_16x16x32_bf16 v[164:167], v[172:175], v[168:171], v[164:167]
	ds_read2_b64 v[168:171], v101 offset0:128 offset1:130
	s_waitcnt lgkmcnt(3)
	v_mfma_f32_16x16x32_bf16 v[116:119], v[172:175], v[180:183], v[116:119]
	ds_read2_b64 v[172:175], v153 offset0:128 offset1:130
	ds_read2_b64 v[180:183], v154 offset0:128 offset1:130
	s_waitcnt lgkmcnt(2)
	global_store_dwordx4 v102, v[168:171], s[82:83]
	s_waitcnt lgkmcnt(1)
	global_store_dwordx4 v142, v[172:175], s[82:83]
	s_waitcnt lgkmcnt(0)
	global_store_dwordx4 v143, v[180:183], s[82:83]
	v_mfma_f32_16x16x32_bf16 v[156:159], v[184:187], v[188:191], v[156:159]
	ds_read2_b64 v[168:171], v155 offset1:2
	v_lshl_add_u64 v[172:173], s[60:61], 0, v[108:109]
	v_lshl_add_u64 v[172:173], v[172:173], 0, v[110:111]
	v_mfma_f32_16x16x32_bf16 v[160:163], v[184:187], v[176:179], v[160:163]
	s_waitcnt lgkmcnt(0)
	global_store_dwordx4 v[172:173], v[168:171], off
	s_nop 1
	v_cvt_pk_bf16_f32 v101, v156, s0
	v_mfma_f32_16x16x32_bf16 v[164:167], v[184:187], v[192:195], v[164:167]
	v_cvt_pk_bf16_f32 v105, v157, s0
	v_cvt_pk_bf16_f32 v107, v158, s0
	v_cvt_pk_bf16_f32 v109, v159, s0
	v_mfma_f32_16x16x32_bf16 v[116:119], v[184:187], v[196:199], v[116:119]
	v_cvt_pk_bf16_f32 v111, v160, s0
	v_cvt_pk_bf16_f32 v112, v161, s0
	v_cvt_pk_bf16_f32 v156, v162, s0
	v_cvt_pk_bf16_f32 v157, v163, s0
	v_cvt_pk_bf16_f32 v158, v164, s0
	v_cvt_pk_bf16_f32 v159, v165, s0
	v_cvt_pk_bf16_f32 v160, v166, s0
	v_cvt_pk_bf16_f32 v161, v167, s0
	v_cvt_pk_bf16_f32 v116, v116, s0
	v_cvt_pk_bf16_f32 v117, v117, s0
	v_cvt_pk_bf16_f32 v118, v118, s0
	v_cvt_pk_bf16_f32 v119, v119, s0
	v_cndmask_b32_e64 v101, 0, v101, s[6:7]
	v_cndmask_b32_e64 v105, 0, v105, s[8:9]
	v_cndmask_b32_e64 v107, 0, v107, s[10:11]
	v_cndmask_b32_e64 v109, 0, v109, s[12:13]
	v_cndmask_b32_e64 v111, 0, v111, s[14:15]
	v_cndmask_b32_e64 v112, 0, v112, s[16:17]
	v_cndmask_b32_e64 v156, 0, v156, s[18:19]
	v_cndmask_b32_e64 v157, 0, v157, s[20:21]
	v_cndmask_b32_e64 v158, 0, v158, s[22:23]
	v_cndmask_b32_e64 v159, 0, v159, s[24:25]
	v_cndmask_b32_e64 v160, 0, v160, s[26:27]
	v_cndmask_b32_e64 v161, 0, v161, s[28:29]
	v_cndmask_b32_e64 v116, 0, v116, s[30:31]
	v_cndmask_b32_e64 v117, 0, v117, s[34:35]
	v_cndmask_b32_e64 v118, 0, v118, s[36:37]
	v_cndmask_b32_e64 v119, 0, v119, s[38:39]
	s_barrier
; DI bf16_t f2bf(float f) { return (bf16_t)(pk2(f, 0.f) & 0xffffu); }
; DI void phase_prep(const Params& p, int j, unsigned char* lds) {
;     ...
;         {
; #pragma unroll
;             for (int it = 0; it < 4; ++it) { const int idx = it * 512 + tid; const int t = idx >> 5, seg = idx & 31; *(u32x4*)(qt + t * 264 + seg * 8) = vcur[it]; }
;         }
;         {
;             const int d2 = wave >> 2, wd = wave & 3, fr = lane & 15, fq = lane >> 4;
; #pragma unroll
;             for (int nb = 0; nb < 4; ++nb)
; #pragma unroll
;                 for (int jx = 0; jx < 4; ++jx) {
;                     const int i = 16 * wd + 4 * fq + jx, jt = 16 * nb + fr;
;                     const int mb = i >> 5, r = i & 31, hh = (jt >> 3) & 1, jj = jt & 7;
;                     kt[d2 * 4096 + ((nb * 2 + mb) * 64 + hh * 32 + r) * 8 + jj] = f2bf(amask[nb][jx]);
;                 }
;         }
;         __syncthreads();
;         {
;             bf16_t* AMp = (bf16_t*)(p.ws + WS_AM) + (size_t)(item * 2) * 4096;
;             *(u32x4*)(AMp + tid * 8) = *(const u32x4*)(kt + tid * 8);
;             *(u32x4*)(AMp + 4096 + tid * 8) = *(const u32x4*)(kt + 4096 + tid * 8);
;         }
;         {
;             bf16_t* VTp = (bf16_t*)(p.ws + WS_VT) + (size_t)item * 16384;
; #pragma unroll
;             for (int it = 0; it < 4; ++it) {
;                 const int idx = it * 512 + tid; const int f = idx >> 6, ln = idx & 63; const int sl = f >> 2, s = f & 3, rr = ln & 31, hh = ln >> 5;
;                 const bf16_t* sp = qt + (16 * s + 8 * hh) * 264 + 32 * sl + rr;
;                 unsigned e[8];
; #pragma unroll
;                 for (int jj = 0; jj < 8; ++jj) e[jj] = sp[jj * 264];
;                 u32x4 o; o.x = e[0] | (e[1] << 16); o.y = e[2] | (e[3] << 16); o.z = e[4] | (e[5] << 16); o.w = e[6] | (e[7] << 16);
;                 *(u32x4*)(VTp + (f * 64 + ln) * 8) = o;
;             }
;         }
;         __syncthreads();
	ds_write_b128 v144, v[2:5] offset:8192
	ds_write_b128 v145, v[6:9] offset:8192
	ds_write_b128 v146, v[10:13] offset:8192
	ds_write_b128 v147, v[14:17] offset:8192
	ds_write_b16 v148, v101
	ds_write_b16 v148, v105 offset:16
	ds_write_b16 v148, v107 offset:32
	ds_write_b16 v148, v109 offset:48
	ds_write_b16 v148, v111 offset:2048
	ds_write_b16 v148, v112 offset:2064
	ds_write_b16 v148, v156 offset:2080
	ds_write_b16 v148, v157 offset:2096
	ds_write_b16 v148, v158 offset:4096
	ds_write_b16 v148, v159 offset:4112
	ds_write_b16 v148, v160 offset:4128
	ds_write_b16 v148, v161 offset:4144
	ds_write_b16 v148, v116 offset:6144
	ds_write_b16 v148, v117 offset:6160
	ds_write_b16 v148, v118 offset:6176
	ds_write_b16 v148, v119 offset:6192
	s_waitcnt lgkmcnt(0)
	s_barrier
	ds_read_b128 v[2:5], v124
	ds_read_b128 v[6:9], v125
	v_lshl_add_u64 v[10:11], s[58:59], 0, v[102:103]
	s_waitcnt vmcnt(16)
	v_mov_b64_e32 v[14:15], v[62:63]
	v_mov_b64_e32 v[16:17], v[64:65]
	s_waitcnt lgkmcnt(1)
	global_store_dwordx4 v102, v[2:5], s[58:59]
	s_nop 1
	v_add_co_u32_e32 v2, vcc, s64, v10
	s_nop 1
	v_addc_co_u32_e32 v3, vcc, 0, v11, vcc
	s_waitcnt lgkmcnt(0)
	global_store_dwordx4 v[2:3], v[6:9], off
	ds_read_u16 v2, v136 offset:8192
	ds_read_u16 v3, v136 offset:8720
	ds_read_u16 v4, v136 offset:9248
	ds_read_u16 v5, v136 offset:9776
	ds_read_u16 v6, v136 offset:10304
	ds_read_u16 v7, v136 offset:10832
	ds_read_u16 v8, v136 offset:11360
	ds_read_u16 v9, v136 offset:11888
	s_waitcnt lgkmcnt(6)
	v_lshl_or_b32 v2, v3, 16, v2
	s_waitcnt lgkmcnt(4)
	v_lshl_or_b32 v3, v5, 16, v4
	s_waitcnt lgkmcnt(2)
	v_lshl_or_b32 v4, v7, 16, v6
	s_and_b64 vcc, s[56:57], exec
	s_waitcnt lgkmcnt(0)
	v_lshl_or_b32 v5, v9, 16, v8
	ds_read_u16 v6, v137 offset:8192
	ds_read_u16 v7, v137 offset:8720
	ds_read_u16 v8, v137 offset:9248
	ds_read_u16 v9, v137 offset:9776
	ds_read_u16 v10, v137 offset:10304
	ds_read_u16 v11, v137 offset:10832
	ds_read_u16 v12, v137 offset:11360
	ds_read_u16 v13, v137 offset:11888
	global_store_dwordx4 v102, v[2:5], s[54:55]
	s_waitcnt lgkmcnt(6)
	s_nop 0
	v_lshl_or_b32 v2, v7, 16, v6
	s_waitcnt lgkmcnt(4)
	v_lshl_or_b32 v3, v9, 16, v8
	s_waitcnt lgkmcnt(2)
	v_lshl_or_b32 v4, v11, 16, v10
	s_waitcnt lgkmcnt(0)
	v_lshl_or_b32 v5, v13, 16, v12
	ds_read_u16 v6, v138 offset:8192
	ds_read_u16 v7, v138 offset:8720
	ds_read_u16 v8, v138 offset:9248
	ds_read_u16 v9, v138 offset:9776
	ds_read_u16 v10, v138 offset:10304
	ds_read_u16 v11, v138 offset:10832
	ds_read_u16 v12, v138 offset:11360
	ds_read_u16 v13, v138 offset:11888
	global_store_dwordx4 v140, v[2:5], s[54:55]
	s_waitcnt lgkmcnt(6)
	s_nop 0
	v_lshl_or_b32 v2, v7, 16, v6
	s_waitcnt lgkmcnt(4)
	v_lshl_or_b32 v3, v9, 16, v8
	s_waitcnt lgkmcnt(2)
	v_lshl_or_b32 v4, v11, 16, v10
	s_waitcnt lgkmcnt(0)
	v_lshl_or_b32 v5, v13, 16, v12
	ds_read_u16 v6, v139 offset:8192
	ds_read_u16 v7, v139 offset:8720
	ds_read_u16 v8, v139 offset:9248
	ds_read_u16 v9, v139 offset:9776
	ds_read_u16 v10, v139 offset:10304
	ds_read_u16 v11, v139 offset:10832
	ds_read_u16 v12, v139 offset:11360
	ds_read_u16 v13, v139 offset:11888
	global_store_dwordx4 v141, v[2:5], s[54:55]
	s_waitcnt lgkmcnt(6)
	s_nop 0
	v_lshl_or_b32 v2, v7, 16, v6
	s_waitcnt lgkmcnt(4)
	v_lshl_or_b32 v3, v9, 16, v8
	s_waitcnt lgkmcnt(2)
	v_lshl_or_b32 v4, v11, 16, v10
	s_waitcnt lgkmcnt(0)
	v_lshl_or_b32 v5, v13, 16, v12
	global_store_dwordx4 v149, v[2:5], s[54:55]
	v_mov_b64_e32 v[6:7], v[54:55]
	v_mov_b64_e32 v[10:11], v[58:59]
	v_mov_b64_e32 v[2:3], v[50:51]
	v_mov_b64_e32 v[4:5], v[52:53]
	v_mov_b64_e32 v[8:9], v[56:57]
	v_mov_b64_e32 v[12:13], v[60:61]
	s_mov_b32 s54, s81
	s_barrier
	s_cbranch_vccz .LBB0_361

; template <int DIR>
; DI float prep_gate_loop(const float* r_s, bf16_t* qt, bf16_t* kt, const float (&w)[16], float bias, int kk) {
;     ...
;     for (int blk = 0; blk < 4; ++blk) {
;         float la[16];
; #pragma unroll
;         for (int i = 0; i < 16; ++i) {
;             const int tt = blk * 16 + i; const int t = DIR ? 63 - tt : tt;
;             const f32x4* rr = (const f32x4*)(r_s + t * 32 + DIR * 16);
;             const f32x4 r0 = rr[0], r1 = rr[1], r2 = rr[2], r3 = rr[3];
;             float s0 = __builtin_fmaf(r0[0], w[0], bias), s1 = r0[1] * w[1], s2 = r0[2] * w[2], s3 = r0[3] * w[3];
;             s0 = __builtin_fmaf(r1[0], w[4], s0); s1 = __builtin_fmaf(r1[1], w[5], s1); s2 = __builtin_fmaf(r1[2], w[6], s2); s3 = __builtin_fmaf(r1[3], w[7], s3);
;             s0 = __builtin_fmaf(r2[0], w[8], s0); s1 = __builtin_fmaf(r2[1], w[9], s1); s2 = __builtin_fmaf(r2[2], w[10], s2); s3 = __builtin_fmaf(r2[3], w[11], s3);
;             s0 = __builtin_fmaf(r3[0], w[12], s0); s1 = __builtin_fmaf(r3[1], w[13], s1); s2 = __builtin_fmaf(r3[2], w[14], s2); s3 = __builtin_fmaf(r3[3], w[15], s3);
;             const float pre = (s0 + s1) + (s2 + s3);
;             const float ex = __builtin_amdgcn_exp2f(-fabsf(pre) * LOG2E);
;             la[i] = (fminf(pre, 0.f) * LOG2E - __builtin_amdgcn_logf(1.f + ex)) * 0.0625f;
;         }
.LBB0_356:
	v_mov_b32_e32 v32, s55
	ds_read_b128 v[18:21], v32 offset:1920
	ds_read_b128 v[22:25], v32 offset:1936
	ds_read_b128 v[26:29], v32 offset:1952
	ds_read_b128 v[34:37], v32 offset:1968
	s_addk_i32 s55, 0xf800
	s_waitcnt lgkmcnt(3)
	v_fma_f32 v18, v18, v85, v123
	v_mul_f32_e32 v19, v76, v19
	v_mul_f32_e32 v20, v83, v20
	v_mul_f32_e32 v21, v77, v21
	s_waitcnt lgkmcnt(2)
	v_fmac_f32_e32 v18, v22, v74
	v_fmac_f32_e32 v19, v23, v78
	v_fmac_f32_e32 v20, v24, v75
	v_fmac_f32_e32 v21, v25, v79
	s_waitcnt lgkmcnt(1)
	v_fmac_f32_e32 v18, v26, v80
	v_fmac_f32_e32 v19, v27, v90
	v_fmac_f32_e32 v20, v28, v81
	v_fmac_f32_e32 v21, v29, v91
	s_waitcnt lgkmcnt(0)
	v_fmac_f32_e32 v18, v34, v88
	v_fmac_f32_e32 v19, v35, v92
	v_fmac_f32_e32 v20, v36, v89
	v_fmac_f32_e32 v21, v37, v93
	v_add_f32_e32 v18, v18, v19
	v_add_f32_e32 v19, v20, v21
	v_add_f32_e32 v18, v18, v19
	v_mul_f32_e64 v19, |v18|, s79
	v_exp_f32_e32 v19, v19
	v_min_f32_e32 v18, 0, v18
	v_add_f32_e32 v19, 1.0, v19
	v_log_f32_e32 v19, v19
	s_nop 0
	v_fma_f32 v38, v18, s80, -v19
	ds_read_b128 v[18:21], v32 offset:1792
	ds_read_b128 v[22:25], v32 offset:1808
	ds_read_b128 v[26:29], v32 offset:1824
	ds_read_b128 v[34:37], v32 offset:1840
	v_fmac_f32_e32 v33, 0x3d800000, v38
	s_waitcnt lgkmcnt(3)
	v_fma_f32 v18, v18, v85, v123
	v_mul_f32_e32 v19, v76, v19
	v_mul_f32_e32 v20, v83, v20
	v_mul_f32_e32 v21, v77, v21
	s_waitcnt lgkmcnt(2)
	v_fmac_f32_e32 v18, v22, v74
	v_fmac_f32_e32 v19, v23, v78
	v_fmac_f32_e32 v20, v24, v75
	v_fmac_f32_e32 v21, v25, v79
	s_waitcnt lgkmcnt(1)
	v_fmac_f32_e32 v18, v26, v80
	v_fmac_f32_e32 v19, v27, v90
	v_fmac_f32_e32 v20, v28, v81
	v_fmac_f32_e32 v21, v29, v91
	s_waitcnt lgkmcnt(0)
	v_fmac_f32_e32 v18, v34, v88
	v_fmac_f32_e32 v19, v35, v92
	v_fmac_f32_e32 v20, v36, v89
	v_fmac_f32_e32 v21, v37, v93
	v_add_f32_e32 v18, v18, v19
	v_add_f32_e32 v19, v20, v21
	v_add_f32_e32 v18, v18, v19
	v_mul_f32_e64 v19, |v18|, s79
	v_exp_f32_e32 v19, v19
	v_min_f32_e32 v18, 0, v18
	v_add_f32_e32 v19, 1.0, v19
	v_log_f32_e32 v19, v19
	s_nop 0
	v_fma_f32 v39, v18, s80, -v19
	ds_read_b128 v[18:21], v32 offset:1664
	ds_read_b128 v[22:25], v32 offset:1680
	ds_read_b128 v[26:29], v32 offset:1696
	ds_read_b128 v[34:37], v32 offset:1712
	s_waitcnt lgkmcnt(3)
	v_fma_f32 v18, v18, v85, v123
	v_mul_f32_e32 v19, v76, v19
	v_mul_f32_e32 v20, v83, v20
	v_mul_f32_e32 v21, v77, v21
	s_waitcnt lgkmcnt(2)
	v_fmac_f32_e32 v18, v22, v74
	v_fmac_f32_e32 v19, v23, v78
	v_fmac_f32_e32 v20, v24, v75
	v_fmac_f32_e32 v21, v25, v79
	s_waitcnt lgkmcnt(1)
	v_fmac_f32_e32 v18, v26, v80
	v_fmac_f32_e32 v19, v27, v90
	v_fmac_f32_e32 v20, v28, v81
	v_fmac_f32_e32 v21, v29, v91
	s_waitcnt lgkmcnt(0)
	v_fmac_f32_e32 v18, v34, v88
	v_fmac_f32_e32 v19, v35, v92
	v_fmac_f32_e32 v20, v36, v89
	v_fmac_f32_e32 v21, v37, v93
	v_add_f32_e32 v18, v18, v19
	v_add_f32_e32 v19, v20, v21
	v_add_f32_e32 v18, v18, v19
	v_mul_f32_e64 v19, |v18|, s79
	v_exp_f32_e32 v19, v19
	v_min_f32_e32 v18, 0, v18
	v_add_f32_e32 v19, 1.0, v19
	v_log_f32_e32 v19, v19
	s_nop 0
	v_fma_f32 v40, v18, s80, -v19
	ds_read_b128 v[18:21], v32 offset:1536
	ds_read_b128 v[22:25], v32 offset:1552
	ds_read_b128 v[26:29], v32 offset:1568
	ds_read_b128 v[34:37], v32 offset:1584
	s_waitcnt lgkmcnt(3)
	v_fma_f32 v18, v18, v85, v123
	v_mul_f32_e32 v19, v76, v19
	v_mul_f32_e32 v20, v83, v20
	v_mul_f32_e32 v21, v77, v21
	s_waitcnt lgkmcnt(2)
	v_fmac_f32_e32 v18, v22, v74
	v_fmac_f32_e32 v19, v23, v78
	v_fmac_f32_e32 v20, v24, v75
	v_fmac_f32_e32 v21, v25, v79
	s_waitcnt lgkmcnt(1)
	v_fmac_f32_e32 v18, v26, v80
	v_fmac_f32_e32 v19, v27, v90
	v_fmac_f32_e32 v20, v28, v81
	v_fmac_f32_e32 v21, v29, v91
	s_waitcnt lgkmcnt(0)
	v_fmac_f32_e32 v18, v34, v88
	v_fmac_f32_e32 v19, v35, v92
	v_fmac_f32_e32 v20, v36, v89
	v_fmac_f32_e32 v21, v37, v93
	v_add_f32_e32 v18, v18, v19
	v_add_f32_e32 v19, v20, v21
	v_add_f32_e32 v18, v18, v19
	v_mul_f32_e64 v19, |v18|, s79
	v_exp_f32_e32 v19, v19
	v_min_f32_e32 v18, 0, v18
	v_add_f32_e32 v19, 1.0, v19
	v_log_f32_e32 v19, v19
	s_nop 0
	v_fma_f32 v41, v18, s80, -v19
	ds_read_b128 v[18:21], v32 offset:1408
	ds_read_b128 v[22:25], v32 offset:1424
	ds_read_b128 v[26:29], v32 offset:1440
	ds_read_b128 v[34:37], v32 offset:1456
	s_waitcnt lgkmcnt(3)
	v_fma_f32 v18, v18, v85, v123
	v_mul_f32_e32 v19, v76, v19
	v_mul_f32_e32 v20, v83, v20
	v_mul_f32_e32 v21, v77, v21
	s_waitcnt lgkmcnt(2)
	v_fmac_f32_e32 v18, v22, v74
	v_fmac_f32_e32 v19, v23, v78
	v_fmac_f32_e32 v20, v24, v75
	v_fmac_f32_e32 v21, v25, v79
	s_waitcnt lgkmcnt(1)
	v_fmac_f32_e32 v18, v26, v80
	v_fmac_f32_e32 v19, v27, v90
	v_fmac_f32_e32 v20, v28, v81
	v_fmac_f32_e32 v21, v29, v91
	s_waitcnt lgkmcnt(0)
	v_fmac_f32_e32 v18, v34, v88
	v_fmac_f32_e32 v19, v35, v92
	v_fmac_f32_e32 v20, v36, v89
	v_fmac_f32_e32 v21, v37, v93
	v_add_f32_e32 v18, v18, v19
	v_add_f32_e32 v19, v20, v21
	v_add_f32_e32 v18, v18, v19
	v_mul_f32_e64 v19, |v18|, s79
	v_exp_f32_e32 v19, v19
	v_min_f32_e32 v18, 0, v18
	v_add_f32_e32 v19, 1.0, v19
	v_log_f32_e32 v19, v19
	s_nop 0
	v_fma_f32 v42, v18, s80, -v19
	ds_read_b128 v[18:21], v32 offset:1280
	ds_read_b128 v[22:25], v32 offset:1296
	ds_read_b128 v[26:29], v32 offset:1312
	ds_read_b128 v[34:37], v32 offset:1328
	s_waitcnt lgkmcnt(3)
	v_fma_f32 v18, v18, v85, v123
	v_mul_f32_e32 v19, v76, v19
	v_mul_f32_e32 v20, v83, v20
	v_mul_f32_e32 v21, v77, v21
	s_waitcnt lgkmcnt(2)
	v_fmac_f32_e32 v18, v22, v74
	v_fmac_f32_e32 v19, v23, v78
	v_fmac_f32_e32 v20, v24, v75
	v_fmac_f32_e32 v21, v25, v79
	s_waitcnt lgkmcnt(1)
	v_fmac_f32_e32 v18, v26, v80
	v_fmac_f32_e32 v19, v27, v90
	v_fmac_f32_e32 v20, v28, v81
	v_fmac_f32_e32 v21, v29, v91
	s_waitcnt lgkmcnt(0)
; template <int DIR>
; DI float prep_gate_loop(const float* r_s, bf16_t* qt, bf16_t* kt, const float (&w)[16], float bias, int kk) {
;     ...
;     for (int blk = 0; blk < 4; ++blk) {
;         float la[16];
; #pragma unroll
;         for (int i = 0; i < 16; ++i) {
;             const int tt = blk * 16 + i; const int t = DIR ? 63 - tt : tt;
;             const f32x4* rr = (const f32x4*)(r_s + t * 32 + DIR * 16);
;             const f32x4 r0 = rr[0], r1 = rr[1], r2 = rr[2], r3 = rr[3];
;             float s0 = __builtin_fmaf(r0[0], w[0], bias), s1 = r0[1] * w[1], s2 = r0[2] * w[2], s3 = r0[3] * w[3];
;             s0 = __builtin_fmaf(r1[0], w[4], s0); s1 = __builtin_fmaf(r1[1], w[5], s1); s2 = __builtin_fmaf(r1[2], w[6], s2); s3 = __builtin_fmaf(r1[3], w[7], s3);
;             s0 = __builtin_fmaf(r2[0], w[8], s0); s1 = __builtin_fmaf(r2[1], w[9], s1); s2 = __builtin_fmaf(r2[2], w[10], s2); s3 = __builtin_fmaf(r2[3], w[11], s3);
;             s0 = __builtin_fmaf(r3[0], w[12], s0); s1 = __builtin_fmaf(r3[1], w[13], s1); s2 = __builtin_fmaf(r3[2], w[14], s2); s3 = __builtin_fmaf(r3[3], w[15], s3);
;             const float pre = (s0 + s1) + (s2 + s3);
;             const float ex = __builtin_amdgcn_exp2f(-fabsf(pre) * LOG2E);
;             la[i] = (fminf(pre, 0.f) * LOG2E - __builtin_amdgcn_logf(1.f + ex)) * 0.0625f;
;         }
	v_fmac_f32_e32 v18, v34, v88
	v_fmac_f32_e32 v19, v35, v92
	v_fmac_f32_e32 v20, v36, v89
	v_fmac_f32_e32 v21, v37, v93
	v_add_f32_e32 v18, v18, v19
	v_add_f32_e32 v19, v20, v21
	v_add_f32_e32 v18, v18, v19
	v_mul_f32_e64 v19, |v18|, s79
	v_exp_f32_e32 v19, v19
	v_min_f32_e32 v18, 0, v18
	v_add_f32_e32 v19, 1.0, v19
	v_log_f32_e32 v19, v19
	s_nop 0
	v_fma_f32 v43, v18, s80, -v19
	ds_read_b128 v[18:21], v32 offset:1152
	ds_read_b128 v[22:25], v32 offset:1168
	ds_read_b128 v[26:29], v32 offset:1184
	ds_read_b128 v[34:37], v32 offset:1200
	s_waitcnt lgkmcnt(3)
	v_fma_f32 v18, v18, v85, v123
	v_mul_f32_e32 v19, v76, v19
	v_mul_f32_e32 v20, v83, v20
	v_mul_f32_e32 v21, v77, v21
	s_waitcnt lgkmcnt(2)
	v_fmac_f32_e32 v18, v22, v74
	v_fmac_f32_e32 v19, v23, v78
	v_fmac_f32_e32 v20, v24, v75
	v_fmac_f32_e32 v21, v25, v79
	s_waitcnt lgkmcnt(1)
	v_fmac_f32_e32 v18, v26, v80
	v_fmac_f32_e32 v19, v27, v90
	v_fmac_f32_e32 v20, v28, v81
	v_fmac_f32_e32 v21, v29, v91
	s_waitcnt lgkmcnt(0)
	v_fmac_f32_e32 v18, v34, v88
	v_fmac_f32_e32 v19, v35, v92
	v_fmac_f32_e32 v20, v36, v89
	v_fmac_f32_e32 v21, v37, v93
	v_add_f32_e32 v18, v18, v19
	v_add_f32_e32 v19, v20, v21
	v_add_f32_e32 v18, v18, v19
	v_mul_f32_e64 v19, |v18|, s79
	v_exp_f32_e32 v19, v19
	v_min_f32_e32 v18, 0, v18
	v_add_f32_e32 v19, 1.0, v19
	v_log_f32_e32 v19, v19
	s_nop 0
	v_fma_f32 v44, v18, s80, -v19
	ds_read_b128 v[18:21], v32 offset:1024
	ds_read_b128 v[22:25], v32 offset:1040
	ds_read_b128 v[26:29], v32 offset:1056
	ds_read_b128 v[34:37], v32 offset:1072
	s_waitcnt lgkmcnt(3)
	v_fma_f32 v18, v18, v85, v123
	v_mul_f32_e32 v19, v76, v19
	v_mul_f32_e32 v20, v83, v20
	v_mul_f32_e32 v21, v77, v21
	s_waitcnt lgkmcnt(2)
	v_fmac_f32_e32 v18, v22, v74
	v_fmac_f32_e32 v19, v23, v78
	v_fmac_f32_e32 v20, v24, v75
	v_fmac_f32_e32 v21, v25, v79
	s_waitcnt lgkmcnt(1)
	v_fmac_f32_e32 v18, v26, v80
	v_fmac_f32_e32 v19, v27, v90
	v_fmac_f32_e32 v20, v28, v81
	v_fmac_f32_e32 v21, v29, v91
	s_waitcnt lgkmcnt(0)
	v_fmac_f32_e32 v18, v34, v88
	v_fmac_f32_e32 v19, v35, v92
	v_fmac_f32_e32 v20, v36, v89
	v_fmac_f32_e32 v21, v37, v93
	v_add_f32_e32 v18, v18, v19
	v_add_f32_e32 v19, v20, v21
	v_add_f32_e32 v18, v18, v19
	v_mul_f32_e64 v19, |v18|, s79
	v_exp_f32_e32 v19, v19
	v_min_f32_e32 v18, 0, v18
	v_add_f32_e32 v19, 1.0, v19
	v_log_f32_e32 v19, v19
	s_nop 0
	v_fma_f32 v45, v18, s80, -v19
	ds_read_b128 v[18:21], v32 offset:896
	ds_read_b128 v[22:25], v32 offset:912
	ds_read_b128 v[26:29], v32 offset:928
	ds_read_b128 v[34:37], v32 offset:944
	s_waitcnt lgkmcnt(3)
	v_fma_f32 v18, v18, v85, v123
	v_mul_f32_e32 v19, v76, v19
	v_mul_f32_e32 v20, v83, v20
	v_mul_f32_e32 v21, v77, v21
	s_waitcnt lgkmcnt(2)
	v_fmac_f32_e32 v18, v22, v74
	v_fmac_f32_e32 v19, v23, v78
	v_fmac_f32_e32 v20, v24, v75
	v_fmac_f32_e32 v21, v25, v79
	s_waitcnt lgkmcnt(1)
	v_fmac_f32_e32 v18, v26, v80
	v_fmac_f32_e32 v19, v27, v90
	v_fmac_f32_e32 v20, v28, v81
	v_fmac_f32_e32 v21, v29, v91
	s_waitcnt lgkmcnt(0)
	v_fmac_f32_e32 v18, v34, v88
	v_fmac_f32_e32 v19, v35, v92
	v_fmac_f32_e32 v20, v36, v89
	v_fmac_f32_e32 v21, v37, v93
	v_add_f32_e32 v18, v18, v19
	v_add_f32_e32 v19, v20, v21
	v_add_f32_e32 v18, v18, v19
	v_mul_f32_e64 v19, |v18|, s79
	v_exp_f32_e32 v19, v19
	v_min_f32_e32 v18, 0, v18
	v_add_f32_e32 v19, 1.0, v19
	v_log_f32_e32 v19, v19
	s_nop 0
	v_fma_f32 v46, v18, s80, -v19
	ds_read_b128 v[18:21], v32 offset:768
	ds_read_b128 v[22:25], v32 offset:784
	ds_read_b128 v[26:29], v32 offset:800
	ds_read_b128 v[34:37], v32 offset:816
	s_waitcnt lgkmcnt(3)
	v_mul_f32_e32 v31, v83, v20
	v_mov_b32_e32 v20, v19
	v_fma_f32 v30, v18, v85, v123
	v_mul_f32_e32 v18, v76, v20
	v_mul_f32_e32 v19, v77, v21
	s_waitcnt lgkmcnt(2)
	v_mov_b32_e32 v20, v22
	v_mov_b32_e32 v21, v24
	v_mov_b32_e32 v24, v23
	v_fma_f32 v20, v20, v74, v30
	v_fma_f32 v21, v21, v75, v31
	v_fmac_f32_e32 v18, v24, v78
	v_fmac_f32_e32 v19, v25, v79
	s_waitcnt lgkmcnt(1)
	v_mov_b32_e32 v22, v26
	v_mov_b32_e32 v23, v28
	v_mov_b32_e32 v28, v27
	v_fmac_f32_e32 v20, v22, v80
	v_fmac_f32_e32 v21, v23, v81
	v_fmac_f32_e32 v18, v28, v90
	v_fmac_f32_e32 v19, v29, v91
	s_waitcnt lgkmcnt(0)
	v_mov_b32_e32 v22, v34
	v_mov_b32_e32 v23, v36
	v_mov_b32_e32 v36, v35
	v_fmac_f32_e32 v20, v22, v88
	v_fmac_f32_e32 v21, v23, v89
	v_fmac_f32_e32 v18, v36, v92
	v_fmac_f32_e32 v19, v37, v93
	s_nop 0
	v_add_f32_e32 v18, v20, v18
	v_add_f32_e32 v19, v21, v19
	s_nop 0
	v_add_f32_e32 v18, v18, v19
	v_mul_f32_e64 v19, |v18|, s79
	v_exp_f32_e32 v19, v19
	v_min_f32_e32 v18, 0, v18
	v_add_f32_e32 v19, 1.0, v19
	v_log_f32_e32 v19, v19
	s_nop 0
	v_fma_f32 v47, v18, s80, -v19
	ds_read_b128 v[18:21], v32 offset:640
	ds_read_b128 v[22:25], v32 offset:656
	ds_read_b128 v[26:29], v32 offset:672
	ds_read_b128 v[34:37], v32 offset:688
	s_waitcnt lgkmcnt(3)
	v_mul_f32_e32 v31, v83, v20
	v_mov_b32_e32 v20, v19
	v_fma_f32 v30, v18, v85, v123
	v_mul_f32_e32 v18, v76, v20
	v_mul_f32_e32 v19, v77, v21
	s_waitcnt lgkmcnt(2)
	v_mov_b32_e32 v20, v22
	v_mov_b32_e32 v21, v24
	v_mov_b32_e32 v24, v23
	v_fma_f32 v20, v20, v74, v30
	v_fma_f32 v21, v21, v75, v31
	v_fmac_f32_e32 v18, v24, v78
	v_fmac_f32_e32 v19, v25, v79
	s_waitcnt lgkmcnt(1)
	v_mov_b32_e32 v22, v26
	v_mov_b32_e32 v23, v28
	v_mov_b32_e32 v28, v27
	v_fmac_f32_e32 v20, v22, v80
	v_fmac_f32_e32 v21, v23, v81
	v_fmac_f32_e32 v18, v28, v90
	v_fmac_f32_e32 v19, v29, v91
	s_waitcnt lgkmcnt(0)
; template <int DIR>
; DI float prep_gate_loop(const float* r_s, bf16_t* qt, bf16_t* kt, const float (&w)[16], float bias, int kk) {
;     ...
;     for (int blk = 0; blk < 4; ++blk) {
;         float la[16];
; #pragma unroll
;         for (int i = 0; i < 16; ++i) {
;             const int tt = blk * 16 + i; const int t = DIR ? 63 - tt : tt;
;             const f32x4* rr = (const f32x4*)(r_s + t * 32 + DIR * 16);
;             const f32x4 r0 = rr[0], r1 = rr[1], r2 = rr[2], r3 = rr[3];
;             float s0 = __builtin_fmaf(r0[0], w[0], bias), s1 = r0[1] * w[1], s2 = r0[2] * w[2], s3 = r0[3] * w[3];
;             s0 = __builtin_fmaf(r1[0], w[4], s0); s1 = __builtin_fmaf(r1[1], w[5], s1); s2 = __builtin_fmaf(r1[2], w[6], s2); s3 = __builtin_fmaf(r1[3], w[7], s3);
;             s0 = __builtin_fmaf(r2[0], w[8], s0); s1 = __builtin_fmaf(r2[1], w[9], s1); s2 = __builtin_fmaf(r2[2], w[10], s2); s3 = __builtin_fmaf(r2[3], w[11], s3);
;             s0 = __builtin_fmaf(r3[0], w[12], s0); s1 = __builtin_fmaf(r3[1], w[13], s1); s2 = __builtin_fmaf(r3[2], w[14], s2); s3 = __builtin_fmaf(r3[3], w[15], s3);
;             const float pre = (s0 + s1) + (s2 + s3);
;             const float ex = __builtin_amdgcn_exp2f(-fabsf(pre) * LOG2E);
;             la[i] = (fminf(pre, 0.f) * LOG2E - __builtin_amdgcn_logf(1.f + ex)) * 0.0625f;
;         }
	v_mov_b32_e32 v22, v34
	v_mov_b32_e32 v23, v36
	v_mov_b32_e32 v36, v35
	v_fmac_f32_e32 v20, v22, v88
	v_fmac_f32_e32 v21, v23, v89
	v_fmac_f32_e32 v18, v36, v92
	v_fmac_f32_e32 v19, v37, v93
	s_nop 0
	v_add_f32_e32 v18, v20, v18
	v_add_f32_e32 v19, v21, v19
	s_nop 0
	v_add_f32_e32 v18, v18, v19
	v_mul_f32_e64 v19, |v18|, s79
	v_exp_f32_e32 v19, v19
	v_min_f32_e32 v18, 0, v18
	v_add_f32_e32 v19, 1.0, v19
	v_log_f32_e32 v19, v19
	s_nop 0
	v_fma_f32 v48, v18, s80, -v19
	ds_read_b128 v[18:21], v32 offset:512
	ds_read_b128 v[22:25], v32 offset:528
	ds_read_b128 v[26:29], v32 offset:544
	ds_read_b128 v[34:37], v32 offset:560
	s_waitcnt lgkmcnt(3)
	v_mul_f32_e32 v31, v83, v20
	v_mov_b32_e32 v20, v19
	v_fma_f32 v30, v18, v85, v123
	v_mul_f32_e32 v18, v76, v20
	v_mul_f32_e32 v19, v77, v21
	s_waitcnt lgkmcnt(2)
	v_mov_b32_e32 v20, v22
	v_mov_b32_e32 v21, v24
	v_mov_b32_e32 v24, v23
	v_fma_f32 v20, v20, v74, v30
	v_fma_f32 v21, v21, v75, v31
	v_fmac_f32_e32 v18, v24, v78
	v_fmac_f32_e32 v19, v25, v79
	s_waitcnt lgkmcnt(1)
	v_mov_b32_e32 v22, v26
	v_mov_b32_e32 v23, v28
	v_mov_b32_e32 v28, v27
	v_fmac_f32_e32 v20, v22, v80
	v_fmac_f32_e32 v21, v23, v81
	v_fmac_f32_e32 v18, v28, v90
	v_fmac_f32_e32 v19, v29, v91
	s_waitcnt lgkmcnt(0)
	v_mov_b32_e32 v22, v34
	v_mov_b32_e32 v23, v36
	v_mov_b32_e32 v36, v35
	v_fmac_f32_e32 v20, v22, v88
	v_fmac_f32_e32 v21, v23, v89
	v_fmac_f32_e32 v18, v36, v92
	v_fmac_f32_e32 v19, v37, v93
	s_nop 0
	v_add_f32_e32 v18, v20, v18
	v_add_f32_e32 v19, v21, v19
	s_nop 0
	v_add_f32_e32 v18, v18, v19
	v_mul_f32_e64 v19, |v18|, s79
	v_exp_f32_e32 v19, v19
	v_min_f32_e32 v18, 0, v18
	v_add_f32_e32 v19, 1.0, v19
	v_log_f32_e32 v19, v19
	s_nop 0
	v_fma_f32 v49, v18, s80, -v19
	ds_read_b128 v[18:21], v32 offset:384
	ds_read_b128 v[22:25], v32 offset:400
	ds_read_b128 v[26:29], v32 offset:416
	ds_read_b128 v[34:37], v32 offset:432
	s_waitcnt lgkmcnt(3)
	v_mul_f32_e32 v31, v83, v20
	v_mov_b32_e32 v20, v19
	v_fma_f32 v30, v18, v85, v123
	v_mul_f32_e32 v18, v76, v20
	v_mul_f32_e32 v19, v77, v21
	s_waitcnt lgkmcnt(2)
	v_mov_b32_e32 v20, v22
	v_mov_b32_e32 v21, v24
	v_mov_b32_e32 v24, v23
	v_fma_f32 v20, v20, v74, v30
	v_fma_f32 v21, v21, v75, v31
	v_fmac_f32_e32 v18, v24, v78
	v_fmac_f32_e32 v19, v25, v79
	s_waitcnt lgkmcnt(1)
	v_mov_b32_e32 v22, v26
	v_mov_b32_e32 v23, v28
	v_mov_b32_e32 v28, v27
	v_fmac_f32_e32 v20, v22, v80
	v_fmac_f32_e32 v21, v23, v81
	v_fmac_f32_e32 v18, v28, v90
	v_fmac_f32_e32 v19, v29, v91
	s_waitcnt lgkmcnt(0)
	v_mov_b32_e32 v22, v34
	v_mov_b32_e32 v23, v36
	v_mov_b32_e32 v36, v35
	v_fmac_f32_e32 v20, v22, v88
	v_fmac_f32_e32 v21, v23, v89
	v_fmac_f32_e32 v18, v36, v92
	v_fmac_f32_e32 v19, v37, v93
	s_nop 0
	v_add_f32_e32 v18, v20, v18
	v_add_f32_e32 v19, v21, v19
	s_nop 0
	v_add_f32_e32 v18, v18, v19
	v_mul_f32_e64 v19, |v18|, s79
	v_exp_f32_e32 v19, v19
	v_min_f32_e32 v18, 0, v18
	v_add_f32_e32 v19, 1.0, v19
	v_log_f32_e32 v19, v19
	s_nop 0
	v_fma_f32 v50, v18, s80, -v19
	ds_read_b128 v[18:21], v32 offset:256
	ds_read_b128 v[22:25], v32 offset:272
	ds_read_b128 v[26:29], v32 offset:288
	ds_read_b128 v[34:37], v32 offset:304
	s_waitcnt lgkmcnt(3)
	v_mul_f32_e32 v31, v83, v20
	v_mov_b32_e32 v20, v19
	v_fma_f32 v30, v18, v85, v123
	v_mul_f32_e32 v18, v76, v20
	v_mul_f32_e32 v19, v77, v21
	s_waitcnt lgkmcnt(2)
	v_mov_b32_e32 v20, v22
	v_mov_b32_e32 v21, v24
	v_mov_b32_e32 v24, v23
	v_fma_f32 v20, v20, v74, v30
	v_fma_f32 v21, v21, v75, v31
	v_fmac_f32_e32 v18, v24, v78
	v_fmac_f32_e32 v19, v25, v79
	s_waitcnt lgkmcnt(1)
	v_mov_b32_e32 v22, v26
	v_mov_b32_e32 v23, v28
	v_mov_b32_e32 v28, v27
	v_fmac_f32_e32 v20, v22, v80
	v_fmac_f32_e32 v21, v23, v81
	v_fmac_f32_e32 v18, v28, v90
	v_fmac_f32_e32 v19, v29, v91
	s_waitcnt lgkmcnt(0)
	v_mov_b32_e32 v22, v34
	v_mov_b32_e32 v23, v36
	v_mov_b32_e32 v36, v35
	v_fmac_f32_e32 v20, v22, v88
	v_fmac_f32_e32 v21, v23, v89
	v_fmac_f32_e32 v18, v36, v92
	v_fmac_f32_e32 v19, v37, v93
	s_nop 0
	v_add_f32_e32 v18, v20, v18
	v_add_f32_e32 v19, v21, v19
	s_nop 0
	v_add_f32_e32 v18, v18, v19
	v_mul_f32_e64 v19, |v18|, s79
	v_exp_f32_e32 v19, v19
	v_min_f32_e32 v18, 0, v18
	v_add_f32_e32 v19, 1.0, v19
	v_log_f32_e32 v19, v19
	s_nop 0
	v_fma_f32 v51, v18, s80, -v19
	ds_read_b128 v[18:21], v32 offset:128
	ds_read_b128 v[22:25], v32 offset:144
	ds_read_b128 v[26:29], v32 offset:160
	ds_read_b128 v[34:37], v32 offset:176
	s_waitcnt lgkmcnt(3)
	v_mul_f32_e32 v31, v83, v20
	v_mov_b32_e32 v20, v19
	v_fma_f32 v30, v18, v85, v123
	v_mul_f32_e32 v18, v76, v20
	v_mul_f32_e32 v19, v77, v21
	s_waitcnt lgkmcnt(2)
	v_mov_b32_e32 v20, v22
	v_mov_b32_e32 v21, v24
	v_mov_b32_e32 v24, v23
	v_fma_f32 v20, v20, v74, v30
	v_fma_f32 v21, v21, v75, v31
	v_fmac_f32_e32 v18, v24, v78
	v_fmac_f32_e32 v19, v25, v79
	s_waitcnt lgkmcnt(1)
	v_mov_b32_e32 v22, v26
	v_mov_b32_e32 v23, v28
	v_mov_b32_e32 v28, v27
	v_fmac_f32_e32 v20, v22, v80
	v_fmac_f32_e32 v21, v23, v81
	v_fmac_f32_e32 v18, v28, v90
	v_fmac_f32_e32 v19, v29, v91
	s_waitcnt lgkmcnt(0)
	v_mov_b32_e32 v22, v34
	v_mov_b32_e32 v23, v36
	v_mov_b32_e32 v36, v35
	v_fmac_f32_e32 v20, v22, v88
	v_fmac_f32_e32 v21, v23, v89
	v_fmac_f32_e32 v18, v36, v92
	v_fmac_f32_e32 v19, v37, v93
	s_nop 0
	v_add_f32_e32 v18, v20, v18
	v_add_f32_e32 v19, v21, v19
	s_nop 0
	v_add_f32_e32 v18, v18, v19
	v_mul_f32_e64 v19, |v18|, s79
	v_exp_f32_e32 v19, v19
	v_min_f32_e32 v18, 0, v18
	v_add_f32_e32 v19, 1.0, v19
	v_log_f32_e32 v19, v19
	s_nop 0
	v_fma_f32 v52, v18, s80, -v19
	ds_read_b128 v[18:21], v32
	ds_read_b128 v[22:25], v32 offset:16
	ds_read_b128 v[26:29], v32 offset:32
	ds_read_b128 v[34:37], v32 offset:48
	v_fmamk_f32 v32, v39, 0x3d800000, v33
	s_waitcnt lgkmcnt(3)
; DI float bf2f(bf16_t b) { return __uint_as_float(((unsigned)b) << 16); }
; DI bf16_t f2bf(float f) { return (bf16_t)(pk2(f, 0.f) & 0xffffu); }
; template <int DIR>
; DI float prep_gate_loop(const float* r_s, bf16_t* qt, bf16_t* kt, const float (&w)[16], float bias, int kk) {
;     ...
;             float s0 = __builtin_fmaf(r0[0], w[0], bias), s1 = r0[1] * w[1], s2 = r0[2] * w[2], s3 = r0[3] * w[3];
;             s0 = __builtin_fmaf(r1[0], w[4], s0); s1 = __builtin_fmaf(r1[1], w[5], s1); s2 = __builtin_fmaf(r1[2], w[6], s2); s3 = __builtin_fmaf(r1[3], w[7], s3);
;             s0 = __builtin_fmaf(r2[0], w[8], s0); s1 = __builtin_fmaf(r2[1], w[9], s1); s2 = __builtin_fmaf(r2[2], w[10], s2); s3 = __builtin_fmaf(r2[3], w[11], s3);
;             s0 = __builtin_fmaf(r3[0], w[12], s0); s1 = __builtin_fmaf(r3[1], w[13], s1); s2 = __builtin_fmaf(r3[2], w[14], s2); s3 = __builtin_fmaf(r3[3], w[15], s3);
;             const float pre = (s0 + s1) + (s2 + s3);
;             const float ex = __builtin_amdgcn_exp2f(-fabsf(pre) * LOG2E);
;             la[i] = (fminf(pre, 0.f) * LOG2E - __builtin_amdgcn_logf(1.f + ex)) * 0.0625f;
;         }
; #pragma unroll
;         for (int i = 0; i < 16; ++i) { g += la[i]; la[i] = g; }
; #pragma unroll
;         for (int i = 0; i < 16; ++i) {
;             const int tt = blk * 16 + i; const int t = DIR ? 63 - tt : tt;
;             const float e = __builtin_amdgcn_exp2f(la[i]);
;             bf16_t* qp = qt + (DIR * 64 + t) * 264 + kk; bf16_t* kp = kt + (DIR * 64 + t) * 264 + kk;
;             const float qv = bf2f(*qp), kv = bf2f(*kp);
;             *qp = f2bf(qv * 0.0625f * e);
;             *kp = f2bf(kv * __builtin_amdgcn_rcpf(e));
	v_mul_f32_e32 v31, v83, v20
	v_mov_b32_e32 v20, v19
	v_fma_f32 v30, v18, v85, v123
	v_mul_f32_e32 v18, v76, v20
	v_mul_f32_e32 v19, v77, v21
	s_waitcnt lgkmcnt(2)
	v_mov_b32_e32 v20, v22
	v_mov_b32_e32 v21, v24
	v_fma_f32 v20, v20, v74, v30
	v_fma_f32 v21, v21, v75, v31
	v_mov_b32_e32 v24, v23
	s_waitcnt lgkmcnt(1)
	v_mov_b32_e32 v22, v26
	v_mov_b32_e32 v23, v28
	v_fmac_f32_e32 v18, v24, v78
	v_fmac_f32_e32 v19, v25, v79
	v_fmac_f32_e32 v20, v22, v80
	v_fmac_f32_e32 v21, v23, v81
	v_mov_b32_e32 v28, v27
	s_waitcnt lgkmcnt(0)
	v_mov_b32_e32 v22, v34
	v_add_u32_e32 v34, s52, v120
	v_fmac_f32_e32 v18, v28, v90
	v_fmac_f32_e32 v19, v29, v91
	v_mov_b32_e32 v23, v36
	v_mov_b32_e32 v36, v35
	v_add_u32_e32 v35, 0x125f0, v34
	v_fmac_f32_e32 v18, v36, v92
	v_fmac_f32_e32 v19, v37, v93
	ds_read_u16 v37, v35
	v_exp_f32_e32 v33, v33
	v_add_u32_e32 v36, 0x22df0, v34
	ds_read_u16 v38, v36
	v_fmamk_f32 v31, v40, 0x3d800000, v32
	s_waitcnt lgkmcnt(1)
	v_lshlrev_b32_e32 v37, 16, v37
	v_mul_f32_e32 v37, 0x3d800000, v37
	v_mul_f32_e32 v37, v33, v37
	v_rcp_f32_e32 v33, v33
	s_waitcnt lgkmcnt(0)
	v_lshlrev_b32_e32 v38, 16, v38
	v_cvt_pk_bf16_f32 v37, v37, s0
	v_exp_f32_e32 v32, v32
	v_mul_f32_e32 v33, v33, v38
	v_cvt_pk_bf16_f32 v33, v33, s0
	ds_write_b16 v36, v33
	v_add_u32_e32 v33, 0x123e0, v34
	ds_read_u16 v36, v33
	ds_write_b16 v35, v37
	v_add_u32_e32 v35, 0x22be0, v34
	ds_read_u16 v37, v35
	v_fmamk_f32 v30, v41, 0x3d800000, v31
	s_waitcnt lgkmcnt(2)
	v_lshlrev_b32_e32 v36, 16, v36
	v_mul_f32_e32 v36, 0x3d800000, v36
	v_mul_f32_e32 v36, v32, v36
	v_rcp_f32_e32 v32, v32
	s_waitcnt lgkmcnt(0)
	v_lshlrev_b32_e32 v37, 16, v37
	v_cvt_pk_bf16_f32 v36, v36, s0
	v_exp_f32_e32 v31, v31
	v_mul_f32_e32 v32, v32, v37
	v_cvt_pk_bf16_f32 v32, v32, s0
	ds_write_b16 v35, v32
	v_add_u32_e32 v32, 0x121d0, v34
	ds_read_u16 v35, v32
	ds_write_b16 v33, v36
	v_add_u32_e32 v33, 0x229d0, v34
	ds_read_u16 v36, v33
	v_fmamk_f32 v29, v42, 0x3d800000, v30
	s_waitcnt lgkmcnt(2)
	v_lshlrev_b32_e32 v35, 16, v35
	v_mul_f32_e32 v35, 0x3d800000, v35
	v_mul_f32_e32 v35, v31, v35
	v_rcp_f32_e32 v31, v31
	s_waitcnt lgkmcnt(0)
	v_lshlrev_b32_e32 v36, 16, v36
	v_cvt_pk_bf16_f32 v35, v35, s0
	v_exp_f32_e32 v30, v30
	v_mul_f32_e32 v31, v31, v36
	v_cvt_pk_bf16_f32 v31, v31, s0
	ds_write_b16 v33, v31
	v_add_u32_e32 v31, 0x11fc0, v34
	ds_read_u16 v33, v31
	ds_write_b16 v32, v35
	v_add_u32_e32 v32, 0x227c0, v34
	ds_read_u16 v35, v32
	v_fmamk_f32 v28, v43, 0x3d800000, v29
	s_waitcnt lgkmcnt(2)
	v_lshlrev_b32_e32 v33, 16, v33
	v_mul_f32_e32 v33, 0x3d800000, v33
	v_mul_f32_e32 v33, v30, v33
	v_rcp_f32_e32 v30, v30
	s_waitcnt lgkmcnt(0)
	v_lshlrev_b32_e32 v35, 16, v35
	v_cvt_pk_bf16_f32 v33, v33, s0
	v_exp_f32_e32 v29, v29
	v_mul_f32_e32 v30, v30, v35
	v_cvt_pk_bf16_f32 v30, v30, s0
	ds_write_b16 v32, v30
	v_add_u32_e32 v30, 0x11db0, v34
	ds_read_u16 v32, v30
	ds_write_b16 v31, v33
	v_add_u32_e32 v31, 0x225b0, v34
	ds_read_u16 v33, v31
	v_fmamk_f32 v27, v44, 0x3d800000, v28
	s_waitcnt lgkmcnt(2)
	v_lshlrev_b32_e32 v32, 16, v32
	v_mul_f32_e32 v32, 0x3d800000, v32
	v_mul_f32_e32 v32, v29, v32
	v_rcp_f32_e32 v29, v29
	s_waitcnt lgkmcnt(0)
	v_lshlrev_b32_e32 v33, 16, v33
	v_cvt_pk_bf16_f32 v32, v32, s0
	v_exp_f32_e32 v28, v28
	v_mul_f32_e32 v29, v29, v33
	v_cvt_pk_bf16_f32 v29, v29, s0
	ds_write_b16 v31, v29
	v_add_u32_e32 v29, 0x11ba0, v34
	ds_read_u16 v31, v29
	ds_write_b16 v30, v32
	v_add_u32_e32 v30, 0x223a0, v34
	ds_read_u16 v32, v30
	v_fmamk_f32 v26, v45, 0x3d800000, v27
	s_waitcnt lgkmcnt(2)
	v_lshlrev_b32_e32 v31, 16, v31
	v_mul_f32_e32 v31, 0x3d800000, v31
	v_mul_f32_e32 v31, v28, v31
	v_rcp_f32_e32 v28, v28
	s_waitcnt lgkmcnt(0)
	v_lshlrev_b32_e32 v32, 16, v32
	v_cvt_pk_bf16_f32 v31, v31, s0
	v_exp_f32_e32 v27, v27
	v_mul_f32_e32 v28, v28, v32
	v_cvt_pk_bf16_f32 v28, v28, s0
	ds_write_b16 v30, v28
	v_add_u32_e32 v28, 0x11990, v34
	ds_read_u16 v30, v28
	ds_write_b16 v29, v31
	v_add_u32_e32 v29, 0x22190, v34
	ds_read_u16 v31, v29
	v_fmamk_f32 v25, v46, 0x3d800000, v26
	s_waitcnt lgkmcnt(2)
	v_lshlrev_b32_e32 v30, 16, v30
	v_mul_f32_e32 v30, 0x3d800000, v30
	v_mul_f32_e32 v30, v27, v30
	v_rcp_f32_e32 v27, v27
	s_waitcnt lgkmcnt(0)
	v_lshlrev_b32_e32 v31, 16, v31
	v_cvt_pk_bf16_f32 v30, v30, s0
	v_exp_f32_e32 v26, v26
	v_mul_f32_e32 v27, v27, v31
	v_cvt_pk_bf16_f32 v27, v27, s0
	ds_write_b16 v29, v27
	v_add_u32_e32 v27, 0x11780, v34
	ds_read_u16 v29, v27
	ds_write_b16 v28, v30
	v_add_u32_e32 v28, 0x21f80, v34
	ds_read_u16 v30, v28
	v_fmamk_f32 v24, v47, 0x3d800000, v25
	s_waitcnt lgkmcnt(2)
	v_lshlrev_b32_e32 v29, 16, v29
	v_mul_f32_e32 v29, 0x3d800000, v29
	v_mul_f32_e32 v29, v26, v29
	v_rcp_f32_e32 v26, v26
	s_waitcnt lgkmcnt(0)
; DI float bf2f(bf16_t b) { return __uint_as_float(((unsigned)b) << 16); }
; DI bf16_t f2bf(float f) { return (bf16_t)(pk2(f, 0.f) & 0xffffu); }
; template <int DIR>
; DI float prep_gate_loop(const float* r_s, bf16_t* qt, bf16_t* kt, const float (&w)[16], float bias, int kk) {
;     ...
;             const float pre = (s0 + s1) + (s2 + s3);
;             const float ex = __builtin_amdgcn_exp2f(-fabsf(pre) * LOG2E);
;             la[i] = (fminf(pre, 0.f) * LOG2E - __builtin_amdgcn_logf(1.f + ex)) * 0.0625f;
;         }
; #pragma unroll
;         for (int i = 0; i < 16; ++i) { g += la[i]; la[i] = g; }
; #pragma unroll
;         for (int i = 0; i < 16; ++i) {
;             const int tt = blk * 16 + i; const int t = DIR ? 63 - tt : tt;
;             const float e = __builtin_amdgcn_exp2f(la[i]);
;             bf16_t* qp = qt + (DIR * 64 + t) * 264 + kk; bf16_t* kp = kt + (DIR * 64 + t) * 264 + kk;
;             const float qv = bf2f(*qp), kv = bf2f(*kp);
;             *qp = f2bf(qv * 0.0625f * e);
;             *kp = f2bf(kv * __builtin_amdgcn_rcpf(e));
;         }
;     }
;     return __builtin_amdgcn_exp2f(g);
	v_lshlrev_b32_e32 v30, 16, v30
	v_cvt_pk_bf16_f32 v29, v29, s0
	v_exp_f32_e32 v25, v25
	v_mul_f32_e32 v26, v26, v30
	v_cvt_pk_bf16_f32 v26, v26, s0
	ds_write_b16 v28, v26
	v_add_u32_e32 v26, 0x11570, v34
	ds_read_u16 v28, v26
	ds_write_b16 v27, v29
	v_add_u32_e32 v27, 0x21d70, v34
	ds_read_u16 v29, v27
	v_fmac_f32_e32 v20, v22, v88
	v_fmac_f32_e32 v21, v23, v89
	s_waitcnt lgkmcnt(2)
	v_lshlrev_b32_e32 v28, 16, v28
	v_mul_f32_e32 v28, 0x3d800000, v28
	v_mul_f32_e32 v28, v25, v28
	v_rcp_f32_e32 v25, v25
	s_waitcnt lgkmcnt(0)
	v_lshlrev_b32_e32 v29, 16, v29
	v_fmamk_f32 v23, v48, 0x3d800000, v24
	v_cvt_pk_bf16_f32 v28, v28, s0
	v_mul_f32_e32 v25, v25, v29
	v_cvt_pk_bf16_f32 v25, v25, s0
	ds_write_b16 v27, v25
	v_add_u32_e32 v25, 0x11360, v34
	ds_read_u16 v27, v25
	v_exp_f32_e32 v24, v24
	ds_write_b16 v26, v28
	v_add_u32_e32 v26, 0x21b60, v34
	ds_read_u16 v28, v26
	s_waitcnt lgkmcnt(2)
	v_lshlrev_b32_e32 v27, 16, v27
	v_mul_f32_e32 v27, 0x3d800000, v27
	v_mul_f32_e32 v27, v24, v27
	v_rcp_f32_e32 v24, v24
	s_waitcnt lgkmcnt(0)
	v_lshlrev_b32_e32 v28, 16, v28
	v_fmamk_f32 v22, v49, 0x3d800000, v23
	v_cvt_pk_bf16_f32 v27, v27, s0
	v_mul_f32_e32 v24, v24, v28
	v_cvt_pk_bf16_f32 v24, v24, s0
	ds_write_b16 v26, v24
	v_add_u32_e32 v24, 0x11150, v34
	ds_read_u16 v26, v24
	v_exp_f32_e32 v23, v23
	ds_write_b16 v25, v27
	v_add_u32_e32 v25, 0x21950, v34
	ds_read_u16 v27, v25
	s_waitcnt lgkmcnt(2)
	v_lshlrev_b32_e32 v26, 16, v26
	v_mul_f32_e32 v26, 0x3d800000, v26
	v_mul_f32_e32 v26, v23, v26
	v_rcp_f32_e32 v23, v23
	s_waitcnt lgkmcnt(0)
	v_lshlrev_b32_e32 v27, 16, v27
	v_add_f32_e32 v18, v20, v18
	v_add_f32_e32 v19, v21, v19
	v_fmamk_f32 v21, v50, 0x3d800000, v22
	v_mul_f32_e32 v23, v23, v27
	v_cvt_pk_bf16_f32 v23, v23, s0
	ds_write_b16 v25, v23
	v_add_u32_e32 v23, 0x10f40, v34
	ds_read_u16 v25, v23
	v_cvt_pk_bf16_f32 v26, v26, s0
	v_exp_f32_e32 v22, v22
	ds_write_b16 v24, v26
	v_add_u32_e32 v24, 0x21740, v34
	ds_read_u16 v26, v24
	s_waitcnt lgkmcnt(2)
	v_lshlrev_b32_e32 v25, 16, v25
	v_mul_f32_e32 v25, 0x3d800000, v25
	v_mul_f32_e32 v25, v22, v25
	v_rcp_f32_e32 v22, v22
	s_waitcnt lgkmcnt(0)
	v_lshlrev_b32_e32 v26, 16, v26
	v_fmamk_f32 v20, v51, 0x3d800000, v21
	v_cvt_pk_bf16_f32 v25, v25, s0
	v_mul_f32_e32 v22, v22, v26
	v_cvt_pk_bf16_f32 v22, v22, s0
	ds_write_b16 v24, v22
	v_add_u32_e32 v22, 0x10d30, v34
	ds_read_u16 v24, v22
	v_exp_f32_e32 v21, v21
	ds_write_b16 v23, v25
	v_add_u32_e32 v23, 0x21530, v34
	ds_read_u16 v25, v23
	s_waitcnt lgkmcnt(2)
	v_lshlrev_b32_e32 v24, 16, v24
	v_add_f32_e32 v18, v18, v19
	v_mul_f32_e32 v24, 0x3d800000, v24
	v_mul_f32_e64 v19, |v18|, s79
	v_mul_f32_e32 v24, v21, v24
	v_rcp_f32_e32 v21, v21
	v_exp_f32_e32 v19, v19
	s_waitcnt lgkmcnt(0)
	v_lshlrev_b32_e32 v25, 16, v25
	v_min_f32_e32 v18, 0, v18
	v_mul_f32_e32 v21, v21, v25
	v_add_f32_e32 v19, 1.0, v19
	v_cvt_pk_bf16_f32 v21, v21, s0
	v_log_f32_e32 v19, v19
	ds_write_b16 v23, v21
	v_add_u32_e32 v21, 0x10b20, v34
	ds_read_u16 v23, v21
	v_fma_f32 v18, v18, s80, -v19
	v_fmamk_f32 v19, v52, 0x3d800000, v20
	v_cvt_pk_bf16_f32 v24, v24, s0
	v_exp_f32_e32 v20, v20
	ds_write_b16 v22, v24
	v_add_u32_e32 v22, 0x21320, v34
	ds_read_u16 v24, v22
	s_waitcnt lgkmcnt(2)
	v_lshlrev_b32_e32 v23, 16, v23
	v_mul_f32_e32 v23, 0x3d800000, v23
	v_mul_f32_e32 v23, v20, v23
	v_rcp_f32_e32 v20, v20
	s_waitcnt lgkmcnt(0)
	v_lshlrev_b32_e32 v24, 16, v24
	v_fmamk_f32 v18, v18, 0x3d800000, v19
	v_cvt_pk_bf16_f32 v23, v23, s0
	v_mul_f32_e32 v20, v20, v24
	v_cvt_pk_bf16_f32 v20, v20, s0
	ds_write_b16 v22, v20
	v_add_u32_e32 v20, 0x10910, v34
	ds_read_u16 v22, v20
	v_exp_f32_e32 v19, v19
	ds_write_b16 v21, v23
	v_add_u32_e32 v21, 0x21110, v34
	ds_read_u16 v23, v21
	s_waitcnt lgkmcnt(2)
	v_lshlrev_b32_e32 v22, 16, v22
	v_mul_f32_e32 v22, 0x3d800000, v22
	v_mul_f32_e32 v22, v19, v22
	v_rcp_f32_e32 v19, v19
	s_waitcnt lgkmcnt(0)
	v_lshlrev_b32_e32 v23, 16, v23
	v_cvt_pk_bf16_f32 v22, v22, s0
	v_exp_f32_e32 v112, v18
	v_mul_f32_e32 v19, v19, v23
	v_cvt_pk_bf16_f32 v19, v19, s0
	ds_write_b16 v21, v19
	v_add_u32_e32 v19, 0x10700, v34
	ds_read_u16 v21, v19
	ds_write_b16 v20, v22
	v_add_u32_e32 v20, 0x20f00, v34
	ds_read_u16 v22, v20
	s_addk_i32 s52, 0xdf00
	s_waitcnt lgkmcnt(2)
	v_lshlrev_b32_e32 v21, 16, v21
	v_mul_f32_e32 v21, 0x3d800000, v21
	v_mul_f32_e32 v21, v112, v21
	v_cvt_pk_bf16_f32 v21, v21, s0
	ds_write_b16 v19, v21
	v_rcp_f32_e32 v19, v112
	s_waitcnt lgkmcnt(1)
	v_lshlrev_b32_e32 v22, 16, v22
	s_cmp_lg_u32 s52, 0xffff7c00
	v_mov_b32_e32 v33, v18
	v_mul_f32_e32 v19, v19, v22
	v_cvt_pk_bf16_f32 v19, v19, s0
	ds_write_b16 v20, v19
	s_cbranch_scc1 .LBB0_356

; template <int DIR>
; DI float prep_gate_loop(const float* r_s, bf16_t* qt, bf16_t* kt, const float (&w)[16], float bias, int kk) {
;     ...
;     for (int blk = 0; blk < 4; ++blk) {
;         float la[16];
; #pragma unroll
;         for (int i = 0; i < 16; ++i) {
;             const int tt = blk * 16 + i; const int t = DIR ? 63 - tt : tt;
;             const f32x4* rr = (const f32x4*)(r_s + t * 32 + DIR * 16);
;             const f32x4 r0 = rr[0], r1 = rr[1], r2 = rr[2], r3 = rr[3];
;             float s0 = __builtin_fmaf(r0[0], w[0], bias), s1 = r0[1] * w[1], s2 = r0[2] * w[2], s3 = r0[3] * w[3];
;             s0 = __builtin_fmaf(r1[0], w[4], s0); s1 = __builtin_fmaf(r1[1], w[5], s1); s2 = __builtin_fmaf(r1[2], w[6], s2); s3 = __builtin_fmaf(r1[3], w[7], s3);
;             s0 = __builtin_fmaf(r2[0], w[8], s0); s1 = __builtin_fmaf(r2[1], w[9], s1); s2 = __builtin_fmaf(r2[2], w[10], s2); s3 = __builtin_fmaf(r2[3], w[11], s3);
;             s0 = __builtin_fmaf(r3[0], w[12], s0); s1 = __builtin_fmaf(r3[1], w[13], s1); s2 = __builtin_fmaf(r3[2], w[14], s2); s3 = __builtin_fmaf(r3[3], w[15], s3);
;             const float pre = (s0 + s1) + (s2 + s3);
;             const float ex = __builtin_amdgcn_exp2f(-fabsf(pre) * LOG2E);
;             la[i] = (fminf(pre, 0.f) * LOG2E - __builtin_amdgcn_logf(1.f + ex)) * 0.0625f;
;         }
.LBB0_360:
	v_mov_b32_e32 v32, s55
	ds_read_b128 v[18:21], v32
	ds_read_b128 v[22:25], v32 offset:16
	ds_read_b128 v[26:29], v32 offset:32
	ds_read_b128 v[34:37], v32 offset:48
	s_addk_i32 s55, 0x800
	s_waitcnt lgkmcnt(3)
	v_fma_f32 v18, v18, v85, v123
	v_mul_f32_e32 v19, v76, v19
	v_mul_f32_e32 v20, v83, v20
	v_mul_f32_e32 v21, v77, v21
	s_waitcnt lgkmcnt(2)
	v_fmac_f32_e32 v18, v22, v74
	v_fmac_f32_e32 v19, v23, v78
	v_fmac_f32_e32 v20, v24, v75
	v_fmac_f32_e32 v21, v25, v79
	s_waitcnt lgkmcnt(1)
	v_fmac_f32_e32 v18, v26, v80
	v_fmac_f32_e32 v19, v27, v90
	v_fmac_f32_e32 v20, v28, v81
	v_fmac_f32_e32 v21, v29, v91
	s_waitcnt lgkmcnt(0)
	v_fmac_f32_e32 v18, v34, v88
	v_fmac_f32_e32 v19, v35, v92
	v_fmac_f32_e32 v20, v36, v89
	v_fmac_f32_e32 v21, v37, v93
	v_add_f32_e32 v18, v18, v19
	v_add_f32_e32 v19, v20, v21
	v_add_f32_e32 v18, v18, v19
	v_mul_f32_e64 v19, |v18|, s79
	v_exp_f32_e32 v19, v19
	v_min_f32_e32 v18, 0, v18
	v_add_f32_e32 v19, 1.0, v19
	v_log_f32_e32 v19, v19
	s_nop 0
	v_fma_f32 v38, v18, s80, -v19
	ds_read_b128 v[18:21], v32 offset:128
	ds_read_b128 v[22:25], v32 offset:144
	ds_read_b128 v[26:29], v32 offset:160
	ds_read_b128 v[34:37], v32 offset:176
	v_fmac_f32_e32 v33, 0x3d800000, v38
	s_waitcnt lgkmcnt(3)
	v_fma_f32 v18, v18, v85, v123
	v_mul_f32_e32 v19, v76, v19
	v_mul_f32_e32 v20, v83, v20
	v_mul_f32_e32 v21, v77, v21
	s_waitcnt lgkmcnt(2)
	v_fmac_f32_e32 v18, v22, v74
	v_fmac_f32_e32 v19, v23, v78
	v_fmac_f32_e32 v20, v24, v75
	v_fmac_f32_e32 v21, v25, v79
	s_waitcnt lgkmcnt(1)
	v_fmac_f32_e32 v18, v26, v80
	v_fmac_f32_e32 v19, v27, v90
	v_fmac_f32_e32 v20, v28, v81
	v_fmac_f32_e32 v21, v29, v91
	s_waitcnt lgkmcnt(0)
	v_fmac_f32_e32 v18, v34, v88
	v_fmac_f32_e32 v19, v35, v92
	v_fmac_f32_e32 v20, v36, v89
	v_fmac_f32_e32 v21, v37, v93
	v_add_f32_e32 v18, v18, v19
	v_add_f32_e32 v19, v20, v21
	v_add_f32_e32 v18, v18, v19
	v_mul_f32_e64 v19, |v18|, s79
	v_exp_f32_e32 v19, v19
	v_min_f32_e32 v18, 0, v18
	v_add_f32_e32 v19, 1.0, v19
	v_log_f32_e32 v19, v19
	s_nop 0
	v_fma_f32 v39, v18, s80, -v19
	ds_read_b128 v[18:21], v32 offset:256
	ds_read_b128 v[22:25], v32 offset:272
	ds_read_b128 v[26:29], v32 offset:288
	ds_read_b128 v[34:37], v32 offset:304
	s_waitcnt lgkmcnt(3)
	v_fma_f32 v18, v18, v85, v123
	v_mul_f32_e32 v19, v76, v19
	v_mul_f32_e32 v20, v83, v20
	v_mul_f32_e32 v21, v77, v21
	s_waitcnt lgkmcnt(2)
	v_fmac_f32_e32 v18, v22, v74
	v_fmac_f32_e32 v19, v23, v78
	v_fmac_f32_e32 v20, v24, v75
	v_fmac_f32_e32 v21, v25, v79
	s_waitcnt lgkmcnt(1)
	v_fmac_f32_e32 v18, v26, v80
	v_fmac_f32_e32 v19, v27, v90
	v_fmac_f32_e32 v20, v28, v81
	v_fmac_f32_e32 v21, v29, v91
	s_waitcnt lgkmcnt(0)
	v_fmac_f32_e32 v18, v34, v88
	v_fmac_f32_e32 v19, v35, v92
	v_fmac_f32_e32 v20, v36, v89
	v_fmac_f32_e32 v21, v37, v93
	v_add_f32_e32 v18, v18, v19
	v_add_f32_e32 v19, v20, v21
	v_add_f32_e32 v18, v18, v19
	v_mul_f32_e64 v19, |v18|, s79
	v_exp_f32_e32 v19, v19
	v_min_f32_e32 v18, 0, v18
	v_add_f32_e32 v19, 1.0, v19
	v_log_f32_e32 v19, v19
	s_nop 0
	v_fma_f32 v40, v18, s80, -v19
	ds_read_b128 v[18:21], v32 offset:384
	ds_read_b128 v[22:25], v32 offset:400
	ds_read_b128 v[26:29], v32 offset:416
	ds_read_b128 v[34:37], v32 offset:432
	s_waitcnt lgkmcnt(3)
	v_fma_f32 v18, v18, v85, v123
	v_mul_f32_e32 v19, v76, v19
	v_mul_f32_e32 v20, v83, v20
	v_mul_f32_e32 v21, v77, v21
	s_waitcnt lgkmcnt(2)
	v_fmac_f32_e32 v18, v22, v74
	v_fmac_f32_e32 v19, v23, v78
	v_fmac_f32_e32 v20, v24, v75
	v_fmac_f32_e32 v21, v25, v79
	s_waitcnt lgkmcnt(1)
	v_fmac_f32_e32 v18, v26, v80
	v_fmac_f32_e32 v19, v27, v90
	v_fmac_f32_e32 v20, v28, v81
	v_fmac_f32_e32 v21, v29, v91
	s_waitcnt lgkmcnt(0)
	v_fmac_f32_e32 v18, v34, v88
	v_fmac_f32_e32 v19, v35, v92
	v_fmac_f32_e32 v20, v36, v89
	v_fmac_f32_e32 v21, v37, v93
	v_add_f32_e32 v18, v18, v19
	v_add_f32_e32 v19, v20, v21
	v_add_f32_e32 v18, v18, v19
	v_mul_f32_e64 v19, |v18|, s79
	v_exp_f32_e32 v19, v19
	v_min_f32_e32 v18, 0, v18
	v_add_f32_e32 v19, 1.0, v19
	v_log_f32_e32 v19, v19
	s_nop 0
	v_fma_f32 v41, v18, s80, -v19
	ds_read_b128 v[18:21], v32 offset:512
	ds_read_b128 v[22:25], v32 offset:528
	ds_read_b128 v[26:29], v32 offset:544
	ds_read_b128 v[34:37], v32 offset:560
	s_waitcnt lgkmcnt(3)
	v_fma_f32 v18, v18, v85, v123
	v_mul_f32_e32 v19, v76, v19
	v_mul_f32_e32 v20, v83, v20
	v_mul_f32_e32 v21, v77, v21
	s_waitcnt lgkmcnt(2)
	v_fmac_f32_e32 v18, v22, v74
	v_fmac_f32_e32 v19, v23, v78
	v_fmac_f32_e32 v20, v24, v75
	v_fmac_f32_e32 v21, v25, v79
	s_waitcnt lgkmcnt(1)
	v_fmac_f32_e32 v18, v26, v80
	v_fmac_f32_e32 v19, v27, v90
	v_fmac_f32_e32 v20, v28, v81
	v_fmac_f32_e32 v21, v29, v91
	s_waitcnt lgkmcnt(0)
	v_fmac_f32_e32 v18, v34, v88
	v_fmac_f32_e32 v19, v35, v92
	v_fmac_f32_e32 v20, v36, v89
	v_fmac_f32_e32 v21, v37, v93
	v_add_f32_e32 v18, v18, v19
	v_add_f32_e32 v19, v20, v21
	v_add_f32_e32 v18, v18, v19
	v_mul_f32_e64 v19, |v18|, s79
	v_exp_f32_e32 v19, v19
	v_min_f32_e32 v18, 0, v18
	v_add_f32_e32 v19, 1.0, v19
	v_log_f32_e32 v19, v19
	s_nop 0
	v_fma_f32 v42, v18, s80, -v19
	ds_read_b128 v[18:21], v32 offset:640
	ds_read_b128 v[22:25], v32 offset:656
	ds_read_b128 v[26:29], v32 offset:672
	ds_read_b128 v[34:37], v32 offset:688
	s_waitcnt lgkmcnt(3)
	v_fma_f32 v18, v18, v85, v123
	v_mul_f32_e32 v19, v76, v19
	v_mul_f32_e32 v20, v83, v20
	v_mul_f32_e32 v21, v77, v21
	s_waitcnt lgkmcnt(2)
	v_fmac_f32_e32 v18, v22, v74
	v_fmac_f32_e32 v19, v23, v78
	v_fmac_f32_e32 v20, v24, v75
	v_fmac_f32_e32 v21, v25, v79
	s_waitcnt lgkmcnt(1)
	v_fmac_f32_e32 v18, v26, v80
	v_fmac_f32_e32 v19, v27, v90
	v_fmac_f32_e32 v20, v28, v81
	v_fmac_f32_e32 v21, v29, v91
	s_waitcnt lgkmcnt(0)
; template <int DIR>
; DI float prep_gate_loop(const float* r_s, bf16_t* qt, bf16_t* kt, const float (&w)[16], float bias, int kk) {
;     ...
;     for (int blk = 0; blk < 4; ++blk) {
;         float la[16];
; #pragma unroll
;         for (int i = 0; i < 16; ++i) {
;             const int tt = blk * 16 + i; const int t = DIR ? 63 - tt : tt;
;             const f32x4* rr = (const f32x4*)(r_s + t * 32 + DIR * 16);
;             const f32x4 r0 = rr[0], r1 = rr[1], r2 = rr[2], r3 = rr[3];
;             float s0 = __builtin_fmaf(r0[0], w[0], bias), s1 = r0[1] * w[1], s2 = r0[2] * w[2], s3 = r0[3] * w[3];
;             s0 = __builtin_fmaf(r1[0], w[4], s0); s1 = __builtin_fmaf(r1[1], w[5], s1); s2 = __builtin_fmaf(r1[2], w[6], s2); s3 = __builtin_fmaf(r1[3], w[7], s3);
;             s0 = __builtin_fmaf(r2[0], w[8], s0); s1 = __builtin_fmaf(r2[1], w[9], s1); s2 = __builtin_fmaf(r2[2], w[10], s2); s3 = __builtin_fmaf(r2[3], w[11], s3);
;             s0 = __builtin_fmaf(r3[0], w[12], s0); s1 = __builtin_fmaf(r3[1], w[13], s1); s2 = __builtin_fmaf(r3[2], w[14], s2); s3 = __builtin_fmaf(r3[3], w[15], s3);
;             const float pre = (s0 + s1) + (s2 + s3);
;             const float ex = __builtin_amdgcn_exp2f(-fabsf(pre) * LOG2E);
;             la[i] = (fminf(pre, 0.f) * LOG2E - __builtin_amdgcn_logf(1.f + ex)) * 0.0625f;
;         }
	v_fmac_f32_e32 v18, v34, v88
	v_fmac_f32_e32 v19, v35, v92
	v_fmac_f32_e32 v20, v36, v89
	v_fmac_f32_e32 v21, v37, v93
	v_add_f32_e32 v18, v18, v19
	v_add_f32_e32 v19, v20, v21
	v_add_f32_e32 v18, v18, v19
	v_mul_f32_e64 v19, |v18|, s79
	v_exp_f32_e32 v19, v19
	v_min_f32_e32 v18, 0, v18
	v_add_f32_e32 v19, 1.0, v19
	v_log_f32_e32 v19, v19
	s_nop 0
	v_fma_f32 v43, v18, s80, -v19
	ds_read_b128 v[18:21], v32 offset:768
	ds_read_b128 v[22:25], v32 offset:784
	ds_read_b128 v[26:29], v32 offset:800
	ds_read_b128 v[34:37], v32 offset:816
	s_waitcnt lgkmcnt(3)
	v_fma_f32 v18, v18, v85, v123
	v_mul_f32_e32 v19, v76, v19
	v_mul_f32_e32 v20, v83, v20
	v_mul_f32_e32 v21, v77, v21
	s_waitcnt lgkmcnt(2)
	v_fmac_f32_e32 v18, v22, v74
	v_fmac_f32_e32 v19, v23, v78
	v_fmac_f32_e32 v20, v24, v75
	v_fmac_f32_e32 v21, v25, v79
	s_waitcnt lgkmcnt(1)
	v_fmac_f32_e32 v18, v26, v80
	v_fmac_f32_e32 v19, v27, v90
	v_fmac_f32_e32 v20, v28, v81
	v_fmac_f32_e32 v21, v29, v91
	s_waitcnt lgkmcnt(0)
	v_fmac_f32_e32 v18, v34, v88
	v_fmac_f32_e32 v19, v35, v92
	v_fmac_f32_e32 v20, v36, v89
	v_fmac_f32_e32 v21, v37, v93
	v_add_f32_e32 v18, v18, v19
	v_add_f32_e32 v19, v20, v21
	v_add_f32_e32 v18, v18, v19
	v_mul_f32_e64 v19, |v18|, s79
	v_exp_f32_e32 v19, v19
	v_min_f32_e32 v18, 0, v18
	v_add_f32_e32 v19, 1.0, v19
	v_log_f32_e32 v19, v19
	s_nop 0
	v_fma_f32 v44, v18, s80, -v19
	ds_read_b128 v[18:21], v32 offset:896
	ds_read_b128 v[22:25], v32 offset:912
	ds_read_b128 v[26:29], v32 offset:928
	ds_read_b128 v[34:37], v32 offset:944
	s_waitcnt lgkmcnt(3)
	v_fma_f32 v18, v18, v85, v123
	v_mul_f32_e32 v19, v76, v19
	v_mul_f32_e32 v20, v83, v20
	v_mul_f32_e32 v21, v77, v21
	s_waitcnt lgkmcnt(2)
	v_fmac_f32_e32 v18, v22, v74
	v_fmac_f32_e32 v19, v23, v78
	v_fmac_f32_e32 v20, v24, v75
	v_fmac_f32_e32 v21, v25, v79
	s_waitcnt lgkmcnt(1)
	v_fmac_f32_e32 v18, v26, v80
	v_fmac_f32_e32 v19, v27, v90
	v_fmac_f32_e32 v20, v28, v81
	v_fmac_f32_e32 v21, v29, v91
	s_waitcnt lgkmcnt(0)
	v_fmac_f32_e32 v18, v34, v88
	v_fmac_f32_e32 v19, v35, v92
	v_fmac_f32_e32 v20, v36, v89
	v_fmac_f32_e32 v21, v37, v93
	v_add_f32_e32 v18, v18, v19
	v_add_f32_e32 v19, v20, v21
	v_add_f32_e32 v18, v18, v19
	v_mul_f32_e64 v19, |v18|, s79
	v_exp_f32_e32 v19, v19
	v_min_f32_e32 v18, 0, v18
	v_add_f32_e32 v19, 1.0, v19
	v_log_f32_e32 v19, v19
	s_nop 0
	v_fma_f32 v45, v18, s80, -v19
	ds_read_b128 v[18:21], v32 offset:1024
	ds_read_b128 v[22:25], v32 offset:1040
	ds_read_b128 v[26:29], v32 offset:1056
	ds_read_b128 v[34:37], v32 offset:1072
	s_waitcnt lgkmcnt(3)
	v_fma_f32 v18, v18, v85, v123
	v_mul_f32_e32 v19, v76, v19
	v_mul_f32_e32 v20, v83, v20
	v_mul_f32_e32 v21, v77, v21
	s_waitcnt lgkmcnt(2)
	v_fmac_f32_e32 v18, v22, v74
	v_fmac_f32_e32 v19, v23, v78
	v_fmac_f32_e32 v20, v24, v75
	v_fmac_f32_e32 v21, v25, v79
	s_waitcnt lgkmcnt(1)
	v_fmac_f32_e32 v18, v26, v80
	v_fmac_f32_e32 v19, v27, v90
	v_fmac_f32_e32 v20, v28, v81
	v_fmac_f32_e32 v21, v29, v91
	s_waitcnt lgkmcnt(0)
	v_fmac_f32_e32 v18, v34, v88
	v_fmac_f32_e32 v19, v35, v92
	v_fmac_f32_e32 v20, v36, v89
	v_fmac_f32_e32 v21, v37, v93
	v_add_f32_e32 v18, v18, v19
	v_add_f32_e32 v19, v20, v21
	v_add_f32_e32 v18, v18, v19
	v_mul_f32_e64 v19, |v18|, s79
	v_exp_f32_e32 v19, v19
	v_min_f32_e32 v18, 0, v18
	v_add_f32_e32 v19, 1.0, v19
	v_log_f32_e32 v19, v19
	s_nop 0
	v_fma_f32 v46, v18, s80, -v19
	ds_read_b128 v[18:21], v32 offset:1152
	ds_read_b128 v[22:25], v32 offset:1168
	ds_read_b128 v[26:29], v32 offset:1184
	ds_read_b128 v[34:37], v32 offset:1200
	s_waitcnt lgkmcnt(3)
	v_mul_f32_e32 v31, v83, v20
	v_mov_b32_e32 v20, v19
	v_fma_f32 v30, v18, v85, v123
	v_mul_f32_e32 v18, v76, v20
	v_mul_f32_e32 v19, v77, v21
	s_waitcnt lgkmcnt(2)
	v_mov_b32_e32 v20, v22
	v_mov_b32_e32 v21, v24
	v_mov_b32_e32 v24, v23
	v_fma_f32 v20, v20, v74, v30
	v_fma_f32 v21, v21, v75, v31
	v_fmac_f32_e32 v18, v24, v78
	v_fmac_f32_e32 v19, v25, v79
	s_waitcnt lgkmcnt(1)
	v_mov_b32_e32 v22, v26
	v_mov_b32_e32 v23, v28
	v_mov_b32_e32 v28, v27
	v_fmac_f32_e32 v20, v22, v80
	v_fmac_f32_e32 v21, v23, v81
	v_fmac_f32_e32 v18, v28, v90
	v_fmac_f32_e32 v19, v29, v91
	s_waitcnt lgkmcnt(0)
	v_mov_b32_e32 v22, v34
	v_mov_b32_e32 v23, v36
	v_mov_b32_e32 v36, v35
	v_fmac_f32_e32 v20, v22, v88
	v_fmac_f32_e32 v21, v23, v89
	v_fmac_f32_e32 v18, v36, v92
	v_fmac_f32_e32 v19, v37, v93
	s_nop 0
	v_add_f32_e32 v18, v20, v18
	v_add_f32_e32 v19, v21, v19
	s_nop 0
	v_add_f32_e32 v18, v18, v19
	v_mul_f32_e64 v19, |v18|, s79
	v_exp_f32_e32 v19, v19
	v_min_f32_e32 v18, 0, v18
	v_add_f32_e32 v19, 1.0, v19
	v_log_f32_e32 v19, v19
	s_nop 0
	v_fma_f32 v47, v18, s80, -v19
	ds_read_b128 v[18:21], v32 offset:1280
	ds_read_b128 v[22:25], v32 offset:1296
	ds_read_b128 v[26:29], v32 offset:1312
	ds_read_b128 v[34:37], v32 offset:1328
	s_waitcnt lgkmcnt(3)
	v_mul_f32_e32 v31, v83, v20
	v_mov_b32_e32 v20, v19
	v_fma_f32 v30, v18, v85, v123
	v_mul_f32_e32 v18, v76, v20
	v_mul_f32_e32 v19, v77, v21
	s_waitcnt lgkmcnt(2)
	v_mov_b32_e32 v20, v22
	v_mov_b32_e32 v21, v24
	v_mov_b32_e32 v24, v23
	v_fma_f32 v20, v20, v74, v30
	v_fma_f32 v21, v21, v75, v31
	v_fmac_f32_e32 v18, v24, v78
	v_fmac_f32_e32 v19, v25, v79
	s_waitcnt lgkmcnt(1)
	v_mov_b32_e32 v22, v26
	v_mov_b32_e32 v23, v28
	v_mov_b32_e32 v28, v27
	v_fmac_f32_e32 v20, v22, v80
	v_fmac_f32_e32 v21, v23, v81
	v_fmac_f32_e32 v18, v28, v90
	v_fmac_f32_e32 v19, v29, v91
	s_waitcnt lgkmcnt(0)
; template <int DIR>
; DI float prep_gate_loop(const float* r_s, bf16_t* qt, bf16_t* kt, const float (&w)[16], float bias, int kk) {
;     ...
;     for (int blk = 0; blk < 4; ++blk) {
;         float la[16];
; #pragma unroll
;         for (int i = 0; i < 16; ++i) {
;             const int tt = blk * 16 + i; const int t = DIR ? 63 - tt : tt;
;             const f32x4* rr = (const f32x4*)(r_s + t * 32 + DIR * 16);
;             const f32x4 r0 = rr[0], r1 = rr[1], r2 = rr[2], r3 = rr[3];
;             float s0 = __builtin_fmaf(r0[0], w[0], bias), s1 = r0[1] * w[1], s2 = r0[2] * w[2], s3 = r0[3] * w[3];
;             s0 = __builtin_fmaf(r1[0], w[4], s0); s1 = __builtin_fmaf(r1[1], w[5], s1); s2 = __builtin_fmaf(r1[2], w[6], s2); s3 = __builtin_fmaf(r1[3], w[7], s3);
;             s0 = __builtin_fmaf(r2[0], w[8], s0); s1 = __builtin_fmaf(r2[1], w[9], s1); s2 = __builtin_fmaf(r2[2], w[10], s2); s3 = __builtin_fmaf(r2[3], w[11], s3);
;             s0 = __builtin_fmaf(r3[0], w[12], s0); s1 = __builtin_fmaf(r3[1], w[13], s1); s2 = __builtin_fmaf(r3[2], w[14], s2); s3 = __builtin_fmaf(r3[3], w[15], s3);
;             const float pre = (s0 + s1) + (s2 + s3);
;             const float ex = __builtin_amdgcn_exp2f(-fabsf(pre) * LOG2E);
;             la[i] = (fminf(pre, 0.f) * LOG2E - __builtin_amdgcn_logf(1.f + ex)) * 0.0625f;
;         }
	v_mov_b32_e32 v22, v34
	v_mov_b32_e32 v23, v36
	v_mov_b32_e32 v36, v35
	v_fmac_f32_e32 v20, v22, v88
	v_fmac_f32_e32 v21, v23, v89
	v_fmac_f32_e32 v18, v36, v92
	v_fmac_f32_e32 v19, v37, v93
	s_nop 0
	v_add_f32_e32 v18, v20, v18
	v_add_f32_e32 v19, v21, v19
	s_nop 0
	v_add_f32_e32 v18, v18, v19
	v_mul_f32_e64 v19, |v18|, s79
	v_exp_f32_e32 v19, v19
	v_min_f32_e32 v18, 0, v18
	v_add_f32_e32 v19, 1.0, v19
	v_log_f32_e32 v19, v19
	s_nop 0
	v_fma_f32 v48, v18, s80, -v19
	ds_read_b128 v[18:21], v32 offset:1408
	ds_read_b128 v[22:25], v32 offset:1424
	ds_read_b128 v[26:29], v32 offset:1440
	ds_read_b128 v[34:37], v32 offset:1456
	s_waitcnt lgkmcnt(3)
	v_mul_f32_e32 v31, v83, v20
	v_mov_b32_e32 v20, v19
	v_fma_f32 v30, v18, v85, v123
	v_mul_f32_e32 v18, v76, v20
	v_mul_f32_e32 v19, v77, v21
	s_waitcnt lgkmcnt(2)
	v_mov_b32_e32 v20, v22
	v_mov_b32_e32 v21, v24
	v_mov_b32_e32 v24, v23
	v_fma_f32 v20, v20, v74, v30
	v_fma_f32 v21, v21, v75, v31
	v_fmac_f32_e32 v18, v24, v78
	v_fmac_f32_e32 v19, v25, v79
	s_waitcnt lgkmcnt(1)
	v_mov_b32_e32 v22, v26
	v_mov_b32_e32 v23, v28
	v_mov_b32_e32 v28, v27
	v_fmac_f32_e32 v20, v22, v80
	v_fmac_f32_e32 v21, v23, v81
	v_fmac_f32_e32 v18, v28, v90
	v_fmac_f32_e32 v19, v29, v91
	s_waitcnt lgkmcnt(0)
	v_mov_b32_e32 v22, v34
	v_mov_b32_e32 v23, v36
	v_mov_b32_e32 v36, v35
	v_fmac_f32_e32 v20, v22, v88
	v_fmac_f32_e32 v21, v23, v89
	v_fmac_f32_e32 v18, v36, v92
	v_fmac_f32_e32 v19, v37, v93
	s_nop 0
	v_add_f32_e32 v18, v20, v18
	v_add_f32_e32 v19, v21, v19
	s_nop 0
	v_add_f32_e32 v18, v18, v19
	v_mul_f32_e64 v19, |v18|, s79
	v_exp_f32_e32 v19, v19
	v_min_f32_e32 v18, 0, v18
	v_add_f32_e32 v19, 1.0, v19
	v_log_f32_e32 v19, v19
	s_nop 0
	v_fma_f32 v49, v18, s80, -v19
	ds_read_b128 v[18:21], v32 offset:1536
	ds_read_b128 v[22:25], v32 offset:1552
	ds_read_b128 v[26:29], v32 offset:1568
	ds_read_b128 v[34:37], v32 offset:1584
	s_waitcnt lgkmcnt(3)
	v_mul_f32_e32 v31, v83, v20
	v_mov_b32_e32 v20, v19
	v_fma_f32 v30, v18, v85, v123
	v_mul_f32_e32 v18, v76, v20
	v_mul_f32_e32 v19, v77, v21
	s_waitcnt lgkmcnt(2)
	v_mov_b32_e32 v20, v22
	v_mov_b32_e32 v21, v24
	v_mov_b32_e32 v24, v23
	v_fma_f32 v20, v20, v74, v30
	v_fma_f32 v21, v21, v75, v31
	v_fmac_f32_e32 v18, v24, v78
	v_fmac_f32_e32 v19, v25, v79
	s_waitcnt lgkmcnt(1)
	v_mov_b32_e32 v22, v26
	v_mov_b32_e32 v23, v28
	v_mov_b32_e32 v28, v27
	v_fmac_f32_e32 v20, v22, v80
	v_fmac_f32_e32 v21, v23, v81
	v_fmac_f32_e32 v18, v28, v90
	v_fmac_f32_e32 v19, v29, v91
	s_waitcnt lgkmcnt(0)
	v_mov_b32_e32 v22, v34
	v_mov_b32_e32 v23, v36
	v_mov_b32_e32 v36, v35
	v_fmac_f32_e32 v20, v22, v88
	v_fmac_f32_e32 v21, v23, v89
	v_fmac_f32_e32 v18, v36, v92
	v_fmac_f32_e32 v19, v37, v93
	s_nop 0
	v_add_f32_e32 v18, v20, v18
	v_add_f32_e32 v19, v21, v19
	s_nop 0
	v_add_f32_e32 v18, v18, v19
	v_mul_f32_e64 v19, |v18|, s79
	v_exp_f32_e32 v19, v19
	v_min_f32_e32 v18, 0, v18
	v_add_f32_e32 v19, 1.0, v19
	v_log_f32_e32 v19, v19
	s_nop 0
	v_fma_f32 v50, v18, s80, -v19
	ds_read_b128 v[18:21], v32 offset:1664
	ds_read_b128 v[22:25], v32 offset:1680
	ds_read_b128 v[26:29], v32 offset:1696
	ds_read_b128 v[34:37], v32 offset:1712
	s_waitcnt lgkmcnt(3)
	v_mul_f32_e32 v31, v83, v20
	v_mov_b32_e32 v20, v19
	v_fma_f32 v30, v18, v85, v123
	v_mul_f32_e32 v18, v76, v20
	v_mul_f32_e32 v19, v77, v21
	s_waitcnt lgkmcnt(2)
	v_mov_b32_e32 v20, v22
	v_mov_b32_e32 v21, v24
	v_mov_b32_e32 v24, v23
	v_fma_f32 v20, v20, v74, v30
	v_fma_f32 v21, v21, v75, v31
	v_fmac_f32_e32 v18, v24, v78
	v_fmac_f32_e32 v19, v25, v79
	s_waitcnt lgkmcnt(1)
	v_mov_b32_e32 v22, v26
	v_mov_b32_e32 v23, v28
	v_mov_b32_e32 v28, v27
	v_fmac_f32_e32 v20, v22, v80
	v_fmac_f32_e32 v21, v23, v81
	v_fmac_f32_e32 v18, v28, v90
	v_fmac_f32_e32 v19, v29, v91
	s_waitcnt lgkmcnt(0)
	v_mov_b32_e32 v22, v34
	v_mov_b32_e32 v23, v36
	v_mov_b32_e32 v36, v35
	v_fmac_f32_e32 v20, v22, v88
	v_fmac_f32_e32 v21, v23, v89
	v_fmac_f32_e32 v18, v36, v92
	v_fmac_f32_e32 v19, v37, v93
	s_nop 0
	v_add_f32_e32 v18, v20, v18
	v_add_f32_e32 v19, v21, v19
	s_nop 0
	v_add_f32_e32 v18, v18, v19
	v_mul_f32_e64 v19, |v18|, s79
	v_exp_f32_e32 v19, v19
	v_min_f32_e32 v18, 0, v18
	v_add_f32_e32 v19, 1.0, v19
	v_log_f32_e32 v19, v19
	s_nop 0
	v_fma_f32 v51, v18, s80, -v19
	ds_read_b128 v[18:21], v32 offset:1792
	ds_read_b128 v[22:25], v32 offset:1808
	ds_read_b128 v[26:29], v32 offset:1824
	ds_read_b128 v[34:37], v32 offset:1840
	s_waitcnt lgkmcnt(3)
	v_mul_f32_e32 v31, v83, v20
	v_mov_b32_e32 v20, v19
	v_fma_f32 v30, v18, v85, v123
	v_mul_f32_e32 v18, v76, v20
	v_mul_f32_e32 v19, v77, v21
	s_waitcnt lgkmcnt(2)
	v_mov_b32_e32 v20, v22
	v_mov_b32_e32 v21, v24
	v_mov_b32_e32 v24, v23
	v_fma_f32 v20, v20, v74, v30
	v_fma_f32 v21, v21, v75, v31
	v_fmac_f32_e32 v18, v24, v78
	v_fmac_f32_e32 v19, v25, v79
	s_waitcnt lgkmcnt(1)
	v_mov_b32_e32 v22, v26
	v_mov_b32_e32 v23, v28
	v_mov_b32_e32 v28, v27
	v_fmac_f32_e32 v20, v22, v80
	v_fmac_f32_e32 v21, v23, v81
	v_fmac_f32_e32 v18, v28, v90
	v_fmac_f32_e32 v19, v29, v91
	s_waitcnt lgkmcnt(0)
	v_mov_b32_e32 v22, v34
	v_mov_b32_e32 v23, v36
	v_mov_b32_e32 v36, v35
	v_fmac_f32_e32 v20, v22, v88
	v_fmac_f32_e32 v21, v23, v89
	v_fmac_f32_e32 v18, v36, v92
	v_fmac_f32_e32 v19, v37, v93
	s_nop 0
	v_add_f32_e32 v18, v20, v18
	v_add_f32_e32 v19, v21, v19
	s_nop 0
	v_add_f32_e32 v18, v18, v19
	v_mul_f32_e64 v19, |v18|, s79
	v_exp_f32_e32 v19, v19
	v_min_f32_e32 v18, 0, v18
	v_add_f32_e32 v19, 1.0, v19
	v_log_f32_e32 v19, v19
	s_nop 0
	v_fma_f32 v52, v18, s80, -v19
	ds_read_b128 v[18:21], v32 offset:1920
	ds_read_b128 v[22:25], v32 offset:1936
	ds_read_b128 v[26:29], v32 offset:1952
	ds_read_b128 v[34:37], v32 offset:1968
	v_fmamk_f32 v32, v39, 0x3d800000, v33
	s_waitcnt lgkmcnt(3)
; DI float bf2f(bf16_t b) { return __uint_as_float(((unsigned)b) << 16); }
; DI bf16_t f2bf(float f) { return (bf16_t)(pk2(f, 0.f) & 0xffffu); }
; template <int DIR>
; DI float prep_gate_loop(const float* r_s, bf16_t* qt, bf16_t* kt, const float (&w)[16], float bias, int kk) {
;     ...
;             float s0 = __builtin_fmaf(r0[0], w[0], bias), s1 = r0[1] * w[1], s2 = r0[2] * w[2], s3 = r0[3] * w[3];
;             s0 = __builtin_fmaf(r1[0], w[4], s0); s1 = __builtin_fmaf(r1[1], w[5], s1); s2 = __builtin_fmaf(r1[2], w[6], s2); s3 = __builtin_fmaf(r1[3], w[7], s3);
;             s0 = __builtin_fmaf(r2[0], w[8], s0); s1 = __builtin_fmaf(r2[1], w[9], s1); s2 = __builtin_fmaf(r2[2], w[10], s2); s3 = __builtin_fmaf(r2[3], w[11], s3);
;             s0 = __builtin_fmaf(r3[0], w[12], s0); s1 = __builtin_fmaf(r3[1], w[13], s1); s2 = __builtin_fmaf(r3[2], w[14], s2); s3 = __builtin_fmaf(r3[3], w[15], s3);
;             const float pre = (s0 + s1) + (s2 + s3);
;             const float ex = __builtin_amdgcn_exp2f(-fabsf(pre) * LOG2E);
;             la[i] = (fminf(pre, 0.f) * LOG2E - __builtin_amdgcn_logf(1.f + ex)) * 0.0625f;
;         }
; #pragma unroll
;         for (int i = 0; i < 16; ++i) { g += la[i]; la[i] = g; }
; #pragma unroll
;         for (int i = 0; i < 16; ++i) {
;             const int tt = blk * 16 + i; const int t = DIR ? 63 - tt : tt;
;             const float e = __builtin_amdgcn_exp2f(la[i]);
;             bf16_t* qp = qt + (DIR * 64 + t) * 264 + kk; bf16_t* kp = kt + (DIR * 64 + t) * 264 + kk;
;             const float qv = bf2f(*qp), kv = bf2f(*kp);
;             *qp = f2bf(qv * 0.0625f * e);
;             *kp = f2bf(kv * __builtin_amdgcn_rcpf(e));
	v_mul_f32_e32 v31, v83, v20
	v_mov_b32_e32 v20, v19
	v_fma_f32 v30, v18, v85, v123
	v_mul_f32_e32 v18, v76, v20
	v_mul_f32_e32 v19, v77, v21
	s_waitcnt lgkmcnt(2)
	v_mov_b32_e32 v20, v22
	v_mov_b32_e32 v21, v24
	v_mov_b32_e32 v24, v23
	v_fma_f32 v20, v20, v74, v30
	v_fma_f32 v21, v21, v75, v31
	v_fmac_f32_e32 v18, v24, v78
	v_fmac_f32_e32 v19, v25, v79
	s_waitcnt lgkmcnt(1)
	v_mov_b32_e32 v22, v26
	v_mov_b32_e32 v23, v28
	v_mov_b32_e32 v28, v27
	v_fmac_f32_e32 v20, v22, v80
	v_fmac_f32_e32 v21, v23, v81
	v_fmac_f32_e32 v18, v28, v90
	v_fmac_f32_e32 v19, v29, v91
	s_waitcnt lgkmcnt(0)
	v_mov_b32_e32 v22, v34
	v_mov_b32_e32 v23, v36
	v_mov_b32_e32 v36, v35
	v_add_u32_e32 v34, s52, v120
	v_fmac_f32_e32 v18, v36, v92
	v_fmac_f32_e32 v19, v37, v93
	ds_read_u16 v36, v34 offset:8192
	v_exp_f32_e32 v33, v33
	v_add_u32_e32 v35, 0x12800, v34
	ds_read_u16 v37, v35
	v_fmamk_f32 v31, v40, 0x3d800000, v32
	s_waitcnt lgkmcnt(1)
	v_lshlrev_b32_e32 v36, 16, v36
	v_mul_f32_e32 v36, 0x3d800000, v36
	v_mul_f32_e32 v36, v33, v36
	v_rcp_f32_e32 v33, v33
	s_waitcnt lgkmcnt(0)
	v_lshlrev_b32_e32 v37, 16, v37
	v_exp_f32_e32 v32, v32
	v_cvt_pk_bf16_f32 v36, v36, s0
	v_mul_f32_e32 v33, v33, v37
	v_cvt_pk_bf16_f32 v33, v33, s0
	ds_write_b16 v35, v33
	ds_read_u16 v35, v34 offset:8720
	v_add_u32_e32 v33, 0x12a10, v34
	ds_write_b16 v34, v36 offset:8192
	ds_read_u16 v36, v33
	v_fmamk_f32 v30, v41, 0x3d800000, v31
	s_waitcnt lgkmcnt(2)
	v_lshlrev_b32_e32 v35, 16, v35
	v_mul_f32_e32 v35, 0x3d800000, v35
	v_mul_f32_e32 v35, v32, v35
	v_rcp_f32_e32 v32, v32
	s_waitcnt lgkmcnt(0)
	v_lshlrev_b32_e32 v36, 16, v36
	v_exp_f32_e32 v31, v31
	v_cvt_pk_bf16_f32 v35, v35, s0
	v_mul_f32_e32 v32, v32, v36
	v_cvt_pk_bf16_f32 v32, v32, s0
	ds_write_b16 v33, v32
	ds_read_u16 v33, v34 offset:9248
	v_add_u32_e32 v32, 0x12c20, v34
	ds_write_b16 v34, v35 offset:8720
	ds_read_u16 v35, v32
	v_fmamk_f32 v29, v42, 0x3d800000, v30
	s_waitcnt lgkmcnt(2)
	v_lshlrev_b32_e32 v33, 16, v33
	v_mul_f32_e32 v33, 0x3d800000, v33
	v_mul_f32_e32 v33, v31, v33
	v_rcp_f32_e32 v31, v31
	s_waitcnt lgkmcnt(0)
	v_lshlrev_b32_e32 v35, 16, v35
	v_exp_f32_e32 v30, v30
	v_cvt_pk_bf16_f32 v33, v33, s0
	v_mul_f32_e32 v31, v31, v35
	v_cvt_pk_bf16_f32 v31, v31, s0
	ds_write_b16 v32, v31
	ds_read_u16 v32, v34 offset:9776
	v_add_u32_e32 v31, 0x12e30, v34
	ds_write_b16 v34, v33 offset:9248
	ds_read_u16 v33, v31
	v_fmamk_f32 v28, v43, 0x3d800000, v29
	s_waitcnt lgkmcnt(2)
	v_lshlrev_b32_e32 v32, 16, v32
	v_mul_f32_e32 v32, 0x3d800000, v32
	v_mul_f32_e32 v32, v30, v32
	v_rcp_f32_e32 v30, v30
	s_waitcnt lgkmcnt(0)
	v_lshlrev_b32_e32 v33, 16, v33
	v_exp_f32_e32 v29, v29
	v_cvt_pk_bf16_f32 v32, v32, s0
	v_mul_f32_e32 v30, v30, v33
	v_cvt_pk_bf16_f32 v30, v30, s0
	ds_write_b16 v31, v30
	ds_read_u16 v31, v34 offset:10304
	v_add_u32_e32 v30, 0x13040, v34
	ds_write_b16 v34, v32 offset:9776
	ds_read_u16 v32, v30
	v_fmamk_f32 v27, v44, 0x3d800000, v28
	s_waitcnt lgkmcnt(2)
	v_lshlrev_b32_e32 v31, 16, v31
	v_mul_f32_e32 v31, 0x3d800000, v31
	v_mul_f32_e32 v31, v29, v31
	v_rcp_f32_e32 v29, v29
	s_waitcnt lgkmcnt(0)
	v_lshlrev_b32_e32 v32, 16, v32
	v_exp_f32_e32 v28, v28
	v_cvt_pk_bf16_f32 v31, v31, s0
	v_mul_f32_e32 v29, v29, v32
	v_cvt_pk_bf16_f32 v29, v29, s0
	ds_write_b16 v30, v29
	ds_read_u16 v30, v34 offset:10832
	v_add_u32_e32 v29, 0x13250, v34
	ds_write_b16 v34, v31 offset:10304
	ds_read_u16 v31, v29
	v_fmamk_f32 v26, v45, 0x3d800000, v27
	s_waitcnt lgkmcnt(2)
	v_lshlrev_b32_e32 v30, 16, v30
	v_mul_f32_e32 v30, 0x3d800000, v30
	v_mul_f32_e32 v30, v28, v30
	v_rcp_f32_e32 v28, v28
	s_waitcnt lgkmcnt(0)
	v_lshlrev_b32_e32 v31, 16, v31
	v_exp_f32_e32 v27, v27
	v_cvt_pk_bf16_f32 v30, v30, s0
	v_mul_f32_e32 v28, v28, v31
	v_cvt_pk_bf16_f32 v28, v28, s0
	ds_write_b16 v29, v28
	ds_read_u16 v29, v34 offset:11360
	v_add_u32_e32 v28, 0x13460, v34
	ds_write_b16 v34, v30 offset:10832
	ds_read_u16 v30, v28
	v_fmamk_f32 v25, v46, 0x3d800000, v26
	s_waitcnt lgkmcnt(2)
	v_lshlrev_b32_e32 v29, 16, v29
	v_mul_f32_e32 v29, 0x3d800000, v29
	v_mul_f32_e32 v29, v27, v29
	v_rcp_f32_e32 v27, v27
	s_waitcnt lgkmcnt(0)
	v_lshlrev_b32_e32 v30, 16, v30
	v_exp_f32_e32 v26, v26
	v_cvt_pk_bf16_f32 v29, v29, s0
	v_mul_f32_e32 v27, v27, v30
	v_cvt_pk_bf16_f32 v27, v27, s0
	ds_write_b16 v28, v27
	ds_read_u16 v28, v34 offset:11888
	v_add_u32_e32 v27, 0x13670, v34
	ds_write_b16 v34, v29 offset:11360
	ds_read_u16 v29, v27
	v_fmamk_f32 v24, v47, 0x3d800000, v25
	s_waitcnt lgkmcnt(2)
	v_lshlrev_b32_e32 v28, 16, v28
	v_mul_f32_e32 v28, 0x3d800000, v28
	v_mul_f32_e32 v28, v26, v28
	v_rcp_f32_e32 v26, v26
	s_waitcnt lgkmcnt(0)
; DI float bf2f(bf16_t b) { return __uint_as_float(((unsigned)b) << 16); }
; DI bf16_t f2bf(float f) { return (bf16_t)(pk2(f, 0.f) & 0xffffu); }
; template <int DIR>
; DI float prep_gate_loop(const float* r_s, bf16_t* qt, bf16_t* kt, const float (&w)[16], float bias, int kk) {
;     ...
;             const float pre = (s0 + s1) + (s2 + s3);
;             const float ex = __builtin_amdgcn_exp2f(-fabsf(pre) * LOG2E);
;             la[i] = (fminf(pre, 0.f) * LOG2E - __builtin_amdgcn_logf(1.f + ex)) * 0.0625f;
;         }
; #pragma unroll
;         for (int i = 0; i < 16; ++i) { g += la[i]; la[i] = g; }
; #pragma unroll
;         for (int i = 0; i < 16; ++i) {
;             const int tt = blk * 16 + i; const int t = DIR ? 63 - tt : tt;
;             const float e = __builtin_amdgcn_exp2f(la[i]);
;             bf16_t* qp = qt + (DIR * 64 + t) * 264 + kk; bf16_t* kp = kt + (DIR * 64 + t) * 264 + kk;
;             const float qv = bf2f(*qp), kv = bf2f(*kp);
;             *qp = f2bf(qv * 0.0625f * e);
;             *kp = f2bf(kv * __builtin_amdgcn_rcpf(e));
;         }
;     }
;     return __builtin_amdgcn_exp2f(g);
	v_lshlrev_b32_e32 v29, 16, v29
	v_exp_f32_e32 v25, v25
	v_cvt_pk_bf16_f32 v28, v28, s0
	v_mul_f32_e32 v26, v26, v29
	v_cvt_pk_bf16_f32 v26, v26, s0
	ds_write_b16 v27, v26
	ds_read_u16 v27, v34 offset:12416
	v_add_u32_e32 v26, 0x13880, v34
	ds_write_b16 v34, v28 offset:11888
	ds_read_u16 v28, v26
	v_fmac_f32_e32 v20, v22, v88
	v_fmac_f32_e32 v21, v23, v89
	s_waitcnt lgkmcnt(2)
	v_lshlrev_b32_e32 v27, 16, v27
	v_mul_f32_e32 v27, 0x3d800000, v27
	v_mul_f32_e32 v27, v25, v27
	v_rcp_f32_e32 v25, v25
	s_waitcnt lgkmcnt(0)
	v_lshlrev_b32_e32 v28, 16, v28
	v_fmamk_f32 v23, v48, 0x3d800000, v24
	v_exp_f32_e32 v24, v24
	v_mul_f32_e32 v25, v25, v28
	v_cvt_pk_bf16_f32 v25, v25, s0
	ds_write_b16 v26, v25
	ds_read_u16 v26, v34 offset:12944
	v_cvt_pk_bf16_f32 v27, v27, s0
	v_add_u32_e32 v25, 0x13a90, v34
	ds_write_b16 v34, v27 offset:12416
	ds_read_u16 v27, v25
	s_waitcnt lgkmcnt(2)
	v_lshlrev_b32_e32 v26, 16, v26
	v_mul_f32_e32 v26, 0x3d800000, v26
	v_mul_f32_e32 v26, v24, v26
	v_rcp_f32_e32 v24, v24
	s_waitcnt lgkmcnt(0)
	v_lshlrev_b32_e32 v27, 16, v27
	v_fmamk_f32 v22, v49, 0x3d800000, v23
	v_exp_f32_e32 v23, v23
	v_mul_f32_e32 v24, v24, v27
	v_cvt_pk_bf16_f32 v24, v24, s0
	ds_write_b16 v25, v24
	ds_read_u16 v25, v34 offset:13472
	v_cvt_pk_bf16_f32 v26, v26, s0
	v_add_u32_e32 v24, 0x13ca0, v34
	ds_write_b16 v34, v26 offset:12944
	ds_read_u16 v26, v24
	s_waitcnt lgkmcnt(2)
	v_lshlrev_b32_e32 v25, 16, v25
	v_mul_f32_e32 v25, 0x3d800000, v25
	v_mul_f32_e32 v25, v23, v25
	v_rcp_f32_e32 v23, v23
	s_waitcnt lgkmcnt(0)
	v_lshlrev_b32_e32 v26, 16, v26
	v_add_f32_e32 v18, v20, v18
	v_add_f32_e32 v19, v21, v19
	v_fmamk_f32 v21, v50, 0x3d800000, v22
	v_mul_f32_e32 v23, v23, v26
	v_cvt_pk_bf16_f32 v23, v23, s0
	ds_write_b16 v24, v23
	ds_read_u16 v24, v34 offset:14000
	v_exp_f32_e32 v22, v22
	v_cvt_pk_bf16_f32 v25, v25, s0
	v_add_u32_e32 v23, 0x13eb0, v34
	ds_write_b16 v34, v25 offset:13472
	ds_read_u16 v25, v23
	s_waitcnt lgkmcnt(2)
	v_lshlrev_b32_e32 v24, 16, v24
	v_mul_f32_e32 v24, 0x3d800000, v24
	v_mul_f32_e32 v24, v22, v24
	v_rcp_f32_e32 v22, v22
	s_waitcnt lgkmcnt(0)
	v_lshlrev_b32_e32 v25, 16, v25
	v_fmamk_f32 v20, v51, 0x3d800000, v21
	v_exp_f32_e32 v21, v21
	v_mul_f32_e32 v22, v22, v25
	v_cvt_pk_bf16_f32 v22, v22, s0
	ds_write_b16 v23, v22
	ds_read_u16 v23, v34 offset:14528
	v_cvt_pk_bf16_f32 v24, v24, s0
	v_add_u32_e32 v22, 0x140c0, v34
	v_add_f32_e32 v18, v18, v19
	ds_write_b16 v34, v24 offset:14000
	ds_read_u16 v24, v22
	s_waitcnt lgkmcnt(2)
	v_lshlrev_b32_e32 v23, 16, v23
	v_mul_f32_e64 v19, |v18|, s79
	v_mul_f32_e32 v23, 0x3d800000, v23
	v_exp_f32_e32 v19, v19
	v_mul_f32_e32 v23, v21, v23
	v_rcp_f32_e32 v21, v21
	s_waitcnt lgkmcnt(0)
	v_lshlrev_b32_e32 v24, 16, v24
	v_add_f32_e32 v19, 1.0, v19
	v_log_f32_e32 v19, v19
	v_mul_f32_e32 v21, v21, v24
	v_cvt_pk_bf16_f32 v21, v21, s0
	ds_write_b16 v22, v21
	ds_read_u16 v22, v34 offset:15056
	v_min_f32_e32 v18, 0, v18
	v_fma_f32 v18, v18, s80, -v19
	v_fmamk_f32 v19, v52, 0x3d800000, v20
	v_exp_f32_e32 v20, v20
	v_cvt_pk_bf16_f32 v23, v23, s0
	v_add_u32_e32 v21, 0x142d0, v34
	ds_write_b16 v34, v23 offset:14528
	ds_read_u16 v23, v21
	s_waitcnt lgkmcnt(2)
	v_lshlrev_b32_e32 v22, 16, v22
	v_mul_f32_e32 v22, 0x3d800000, v22
	v_mul_f32_e32 v22, v20, v22
	v_rcp_f32_e32 v20, v20
	s_waitcnt lgkmcnt(0)
	v_lshlrev_b32_e32 v23, 16, v23
	v_fmamk_f32 v18, v18, 0x3d800000, v19
	v_exp_f32_e32 v19, v19
	v_mul_f32_e32 v20, v20, v23
	v_cvt_pk_bf16_f32 v20, v20, s0
	ds_write_b16 v21, v20
	ds_read_u16 v21, v34 offset:15584
	v_cvt_pk_bf16_f32 v22, v22, s0
	v_add_u32_e32 v20, 0x144e0, v34
	ds_write_b16 v34, v22 offset:15056
	ds_read_u16 v22, v20
	s_waitcnt lgkmcnt(2)
	v_lshlrev_b32_e32 v21, 16, v21
	v_mul_f32_e32 v21, 0x3d800000, v21
	v_mul_f32_e32 v21, v19, v21
	v_rcp_f32_e32 v19, v19
	s_waitcnt lgkmcnt(0)
	v_lshlrev_b32_e32 v22, 16, v22
	v_exp_f32_e32 v112, v18
	v_cvt_pk_bf16_f32 v21, v21, s0
	v_mul_f32_e32 v19, v19, v22
	v_cvt_pk_bf16_f32 v19, v19, s0
	ds_write_b16 v20, v19
	ds_read_u16 v20, v34 offset:16112
	v_add_u32_e32 v19, 0x146f0, v34
	ds_write_b16 v34, v21 offset:15584
	ds_read_u16 v21, v19
	s_addk_i32 s52, 0x2100
	s_waitcnt lgkmcnt(2)
	v_lshlrev_b32_e32 v20, 16, v20
	v_mul_f32_e32 v20, 0x3d800000, v20
	v_mul_f32_e32 v20, v112, v20
	v_cvt_pk_bf16_f32 v20, v20, s0
	ds_write_b16 v34, v20 offset:16112
	v_rcp_f32_e32 v20, v112
	s_waitcnt lgkmcnt(1)
	v_lshlrev_b32_e32 v21, 16, v21
	s_cmpk_eq_u32 s52, 0x8400
	v_mov_b32_e32 v33, v18
	v_mul_f32_e32 v20, v20, v21
	v_cvt_pk_bf16_f32 v20, v20, s0
	ds_write_b16 v19, v20
	s_cbranch_scc0 .LBB0_360
	s_branch .LBB0_353

; DI float bf2f(bf16_t b) { return __uint_as_float(((unsigned)b) << 16); }
; DI unsigned pk2(float lo, float hi) { f32x2 v = {lo, hi}; bfv2 b = __builtin_convertvector(v, bfv2); return __builtin_bit_cast(unsigned, b); }
; DI void prep_load(PrepIn& I, const Params& p, int j, int item, int tid) {
;     const bf16_t* H = (const bf16_t*)(p.ws + WS_H);
;     const int c = item >> 2, h = item & 3; const size_t row0 = (size_t)c * 64;
;     const int dir = tid >> 8, kk = tid & 255;
;     { const int t = tid >> 3, sg = tid & 7; I.rr = *(const u32x2*)(H + (row0 + t) * HE + 8192 + sg * 4); }
;     const float* wgf = p.in[9]; const float* wgb = p.in[11]; const float* bgf = p.in[10]; const float* bgb = p.in[12];
;     const float* wg = (dir ? wgb : wgf) + (size_t)j * 16 * 1024 + h * 256 + kk;
; #pragma unroll
;     for (int i = 0; i < 16; ++i) I.w[i] = wg[i * 1024];
;     I.bias = (dir ? bgb : bgf)[j * 1024 + h * 256 + kk];
; #pragma unroll
;     for (int it = 0; it < 4; ++it) { const int idx = it * 512 + tid; const int t = idx >> 5, seg = idx & 31;
;         I.q[it] = *(const u32x4*)(H + (row0 + t) * HE + 2048 + h * 256 + seg * 8);
;         I.k[it] = *(const u32x4*)(H + (row0 + t) * HE + h * 256 + seg * 8);
;         I.v[it] = *(const u32x4*)(H + (row0 + t) * HE + 1024 + h * 256 + seg * 8); }
; }
; DI void phase_prep(const Params& p, int j, unsigned char* lds) {
;     ...
;         ((float*)(p.ws + WS_DD))[(size_t)(item * 2 + dir) * 256 + kk] = dlast;
;         { const int nitem = item + (int)gridDim.x; prep_load(I, p, j, nitem < NCH * 4 ? nitem : item, tid); }
;         {
;             bf16_t* KHp = (bf16_t*)(p.ws + WS_KH) + (size_t)(item * 2 + dir) * 16384;
;             const int w8 = kk >> 5, r = kk & 31;
; #pragma unroll
;             for (int tg = 0; tg < 8; ++tg) {
;                 float val[8];
; #pragma unroll
;                 for (int i = 0; i < 8; ++i) val[i] = bf2f(kt[(dir * 64 + 8 * tg + i) * 264 + kk]) * dlast;
;                 u32x4 pk; pk.x = pk2(val[0], val[1]); pk.y = pk2(val[2], val[3]); pk.z = pk2(val[4], val[5]); pk.w = pk2(val[6], val[7]);
;                 const int s = tg >> 1, hh = tg & 1;
;                 *(u32x4*)(KHp + ((w8 * 4 + s) * 64 + hh * 32 + r) * 8) = pk;
.LBB0_1532:
	s_or_b64 exec, exec, s[56:57]
	s_lshl_b32 s58, s54, 1
	s_add_i32 s81, s54, s71
	s_cmpk_lt_i32 s81, 0x820
	s_cselect_b64 s[56:57], -1, 0
	s_and_b64 s[60:61], s[56:57], exec
	v_add_u32_e32 v116, s58, v1
	s_cselect_b32 s52, s81, s54
	v_ashrrev_i32_e32 v117, 31, v116
	s_ashr_i32 s60, s52, 2
	v_lshlrev_b64 v[18:19], 10, v[116:117]
	s_ashr_i32 s61, s60, 31
	v_lshl_add_u64 v[18:19], v[94:95], 0, v[18:19]
	s_lshl_b64 s[60:61], s[60:61], 6
	global_store_dword v[18:19], v112, off
	v_lshl_add_u64 v[18:19], s[60:61], 0, v[66:67]
	v_mov_b64_e32 v[38:39], s[50:51]
	v_mad_u64_u32 v[20:21], s[82:83], v18, s33, v[38:39]
	v_mad_i32_i24 v21, v19, s33, v21
	v_lshl_add_u64 v[18:19], v[20:21], 0, v[68:69]
	s_lshl_b32 s52, s52, 8
	v_add_co_u32_e32 v18, vcc, s62, v18
	s_and_b32 s55, s52, 0x300
	s_nop 0
	v_addc_co_u32_e32 v19, vcc, 0, v19, vcc
	s_lshl_b32 s52, s55, 2
	global_load_dwordx2 v[114:115], v[18:19], off
	v_lshl_add_u64 v[18:19], v[96:97], 0, s[52:53]
	v_add_co_u32_e32 v20, vcc, s64, v18
	s_lshl_b32 s52, s55, 1
	s_nop 0
	v_addc_co_u32_e32 v21, vcc, 0, v19, vcc
	v_add_co_u32_e32 v22, vcc, s62, v18
	v_mov_b32_e32 v101, v69
	s_nop 0
	v_addc_co_u32_e32 v23, vcc, 0, v19, vcc
	v_add_co_u32_e32 v24, vcc, s65, v18
	v_lshlrev_b64 v[116:117], 15, v[116:117]
	s_nop 0
	v_addc_co_u32_e32 v25, vcc, 0, v19, vcc
	v_add_co_u32_e32 v26, vcc, s66, v18
	s_ashr_i32 s59, s58, 31
	s_nop 0
	v_addc_co_u32_e32 v27, vcc, 0, v19, vcc
	global_load_dword v76, v[20:21], off offset:-4096
	global_load_dword v73, v[20:21], off
	global_load_dword v77, v[22:23], off offset:-4096
	global_load_dword v74, v[22:23], off
	global_load_dword v78, v[24:25], off offset:-4096
	global_load_dword v75, v[24:25], off
	global_load_dword v79, v[26:27], off offset:-4096
	global_load_dword v80, v[26:27], off
	v_add_co_u32_e32 v20, vcc, s67, v18
	s_nop 1
	v_addc_co_u32_e32 v21, vcc, 0, v19, vcc
	v_add_co_u32_e32 v22, vcc, s68, v18
	s_nop 1
	v_addc_co_u32_e32 v23, vcc, 0, v19, vcc
	v_add_co_u32_e32 v24, vcc, s69, v18
	s_nop 1
	v_addc_co_u32_e32 v25, vcc, 0, v19, vcc
	global_load_dword v88, v[20:21], off offset:-4096
	global_load_dword v81, v[20:21], off
	global_load_dword v89, v[22:23], off offset:-4096
	global_load_dword v86, v[22:23], off
	global_load_dword v92, v[24:25], off offset:-4096
	global_load_dword v87, v[24:25], off
	v_add_co_u32_e32 v20, vcc, s70, v18
	s_nop 1
	v_addc_co_u32_e32 v21, vcc, 0, v19, vcc
	global_load_dword v85, v[18:19], off
	global_load_dword v93, v[20:21], off
	v_or_b32_sdwa v18, v254, s55 dst_sel:DWORD dst_unused:UNUSED_PAD src0_sel:BYTE_0 src1_sel:DWORD
	v_lshlrev_b32_e32 v18, 2, v18
	v_mov_b32_e32 v19, v69
	v_lshl_add_u64 v[18:19], v[70:71], 0, v[18:19]
	v_add_co_u32_e32 v18, vcc, s63, v18
	s_nop 1
	v_addc_co_u32_e32 v19, vcc, 0, v19, vcc
	global_load_dword v123, v[18:19], off
	v_or_b32_e32 v18, s60, v72
	v_mad_u64_u32 v[18:19], s[82:83], v18, s33, v[38:39]
	v_mad_i32_i24 v19, s61, v83, v19
	v_lshl_add_u64 v[18:19], v[18:19], 0, s[52:53]
	v_lshl_add_u64 v[22:23], v[18:19], 0, v[100:101]
	v_add_co_u32_e32 v24, vcc, s63, v22
	global_load_dwordx4 v[18:21], v[22:23], off
	global_load_dwordx4 v[50:53], v[22:23], off offset:2048
	v_or_b32_e32 v22, s60, v82
	v_addc_co_u32_e32 v25, vcc, 0, v23, vcc
	v_mad_u64_u32 v[22:23], s[82:83], v22, s33, v[38:39]
	v_mad_i32_i24 v23, s61, v83, v23
	v_lshl_add_u64 v[22:23], v[22:23], 0, s[52:53]
	v_lshl_add_u64 v[34:35], v[22:23], 0, v[100:101]
	v_add_co_u32_e32 v30, vcc, s63, v34
	s_nop 1
	v_addc_co_u32_e32 v31, vcc, 0, v35, vcc
	global_load_dwordx4 v[22:25], v[24:25], off
	s_nop 0
	global_load_dwordx4 v[26:29], v[34:35], off
	s_nop 0
	global_load_dwordx4 v[30:33], v[30:31], off
	s_nop 0
	global_load_dwordx4 v[54:57], v[34:35], off offset:2048
	v_or_b32_e32 v34, s60, v84
	v_mad_u64_u32 v[34:35], s[82:83], v34, s33, v[38:39]
	v_mad_i32_i24 v35, s61, v83, v35
	v_lshl_add_u64 v[34:35], v[34:35], 0, s[52:53]
	v_lshl_add_u64 v[40:41], v[34:35], 0, v[100:101]
	v_add_co_u32_e32 v42, vcc, s63, v40
	global_load_dwordx4 v[34:37], v[40:41], off
	global_load_dwordx4 v[58:61], v[40:41], off offset:2048
	v_addc_co_u32_e32 v43, vcc, 0, v41, vcc
	v_lshl_add_u64 v[40:41], s[60:61], 0, v[90:91]
	v_mad_u64_u32 v[38:39], s[60:61], v40, s33, v[38:39]
	v_mad_i32_i24 v39, v41, s33, v39
	v_lshl_add_u64 v[38:39], v[38:39], 0, s[52:53]
	v_lshl_add_u64 v[62:63], v[38:39], 0, v[100:101]
	v_add_co_u32_e32 v46, vcc, s63, v62
	s_lshl_b64 s[60:61], s[58:59], 15
	s_nop 0
	v_addc_co_u32_e32 v47, vcc, 0, v63, vcc
	global_load_dwordx4 v[38:41], v[42:43], off
	s_nop 0
	global_load_dwordx4 v[42:45], v[62:63], off
	s_nop 0
	global_load_dwordx4 v[46:49], v[46:47], off
	s_nop 0
	global_load_dwordx4 v[62:65], v[62:63], off offset:2048
	ds_read_u16 v101, v134
	ds_read_u16 v103, v134 offset:528
	ds_read_u16 v105, v134 offset:1056
	ds_read_u16 v107, v134 offset:1584
	ds_read_u16 v109, v134 offset:2112
	ds_read_u16 v111, v134 offset:2640
	ds_read_u16 v162, v134 offset:3168
	s_waitcnt lgkmcnt(4)
	v_lshlrev_b32_e32 v156, 16, v105
	s_waitcnt lgkmcnt(3)
	v_lshlrev_b32_e32 v157, 16, v107
	v_lshlrev_b32_e32 v119, 16, v103
	ds_read_u16 v103, v134 offset:33264
	v_lshlrev_b32_e32 v118, 16, v101
	v_mul_f32_e32 v159, v112, v157
	v_mul_f32_e32 v158, v112, v156
	s_waitcnt lgkmcnt(2)
	v_lshlrev_b32_e32 v157, 16, v111
	v_lshlrev_b32_e32 v156, 16, v109
	ds_read_u16 v101, v134 offset:3696
	ds_read_u16 v105, v134 offset:4224
	ds_read_u16 v107, v134 offset:4752
	ds_read_u16 v109, v134 offset:5280
	ds_read_u16 v111, v134 offset:5808
	ds_read_u16 v164, v134 offset:6336
	ds_read_u16 v165, v134 offset:6864
	ds_read_u16 v166, v134 offset:7392
	v_mul_f32_e32 v161, v112, v157
	v_mul_f32_e32 v160, v112, v156
	s_waitcnt lgkmcnt(7)
; DI float bf2f(bf16_t b) { return __uint_as_float(((unsigned)b) << 16); }
; DI unsigned pk2(float lo, float hi) { f32x2 v = {lo, hi}; bfv2 b = __builtin_convertvector(v, bfv2); return __builtin_bit_cast(unsigned, b); }
; DI void phase_prep(const Params& p, int j, unsigned char* lds) {
;     ...
;             for (int tg = 0; tg < 8; ++tg) {
;                 float val[8];
; #pragma unroll
;                 for (int i = 0; i < 8; ++i) val[i] = bf2f(kt[(dir * 64 + 8 * tg + i) * 264 + kk]) * dlast;
;                 u32x4 pk; pk.x = pk2(val[0], val[1]); pk.y = pk2(val[2], val[3]); pk.z = pk2(val[4], val[5]); pk.w = pk2(val[6], val[7]);
;                 const int s = tg >> 1, hh = tg & 1;
;                 *(u32x4*)(KHp + ((w8 * 4 + s) * 64 + hh * 32 + r) * 8) = pk;
	v_lshlrev_b32_e32 v157, 16, v101
	v_lshlrev_b32_e32 v156, 16, v162
	v_mul_f32_e32 v119, v112, v119
	v_mul_f32_e32 v118, v112, v118
	v_mul_f32_e32 v163, v112, v157
	v_mul_f32_e32 v162, v112, v156
	v_cvt_pk_bf16_f32 v156, v118, v119
	v_cvt_pk_bf16_f32 v157, v158, v159
	v_cvt_pk_bf16_f32 v158, v160, v161
	v_cvt_pk_bf16_f32 v159, v162, v163
	v_lshl_add_u64 v[160:161], v[98:99], 0, v[116:117]
	global_store_dwordx4 v[160:161], v[156:159], off
	s_waitcnt lgkmcnt(5)
	v_lshlrev_b32_e32 v117, 16, v107
	v_lshlrev_b32_e32 v116, 16, v105
	s_waitcnt lgkmcnt(3)
	v_lshlrev_b32_e32 v119, 16, v111
	v_lshlrev_b32_e32 v118, 16, v109
	s_waitcnt lgkmcnt(1)
	v_lshlrev_b32_e32 v157, 16, v165
	v_lshlrev_b32_e32 v156, 16, v164
	ds_read_u16 v101, v134 offset:7920
	ds_read_u16 v105, v134 offset:8448
	ds_read_u16 v107, v134 offset:8976
	ds_read_u16 v109, v134 offset:9504
	ds_read_u16 v111, v134 offset:10032
	ds_read_u16 v162, v134 offset:10560
	ds_read_u16 v163, v134 offset:11088
	ds_read_u16 v164, v134 offset:11616
	s_waitcnt lgkmcnt(7)
	v_lshlrev_b32_e32 v159, 16, v101
	v_lshlrev_b32_e32 v158, 16, v166
	v_mul_f32_e32 v117, v112, v117
	v_mul_f32_e32 v116, v112, v116
	v_mul_f32_e32 v119, v112, v119
	v_mul_f32_e32 v118, v112, v118
	v_mul_f32_e32 v157, v112, v157
	v_mul_f32_e32 v156, v112, v156
	v_mul_f32_e32 v159, v112, v159
	v_mul_f32_e32 v158, v112, v158
	v_cvt_pk_bf16_f32 v116, v116, v117
	v_cvt_pk_bf16_f32 v117, v118, v119
	v_cvt_pk_bf16_f32 v118, v156, v157
	v_cvt_pk_bf16_f32 v119, v158, v159
	global_store_dwordx4 v[160:161], v[116:119], off offset:512
	s_waitcnt lgkmcnt(1)
	v_lshlrev_b32_e32 v157, 16, v163
	v_lshlrev_b32_e32 v156, 16, v162
	v_lshlrev_b32_e32 v117, 16, v107
	v_lshlrev_b32_e32 v116, 16, v105
	v_lshlrev_b32_e32 v119, 16, v111
	v_lshlrev_b32_e32 v118, 16, v109
	ds_read_u16 v101, v134 offset:12144
	ds_read_u16 v105, v134 offset:12672
	ds_read_u16 v107, v134 offset:13200
	ds_read_u16 v109, v134 offset:13728
	ds_read_u16 v111, v134 offset:14256
	ds_read_u16 v162, v134 offset:14784
	ds_read_u16 v163, v134 offset:15312
	ds_read_u16 v165, v134 offset:15840
	s_waitcnt lgkmcnt(7)
	v_lshlrev_b32_e32 v159, 16, v101
	v_lshlrev_b32_e32 v158, 16, v164
	v_mul_f32_e32 v117, v112, v117
	v_mul_f32_e32 v116, v112, v116
	v_mul_f32_e32 v119, v112, v119
	v_mul_f32_e32 v118, v112, v118
	v_mul_f32_e32 v157, v112, v157
	v_mul_f32_e32 v156, v112, v156
	v_mul_f32_e32 v159, v112, v159
	v_mul_f32_e32 v158, v112, v158
	v_cvt_pk_bf16_f32 v116, v116, v117
	v_cvt_pk_bf16_f32 v117, v118, v119
	v_cvt_pk_bf16_f32 v118, v156, v157
	v_cvt_pk_bf16_f32 v119, v158, v159
	global_store_dwordx4 v[160:161], v[116:119], off offset:1024
	s_waitcnt lgkmcnt(1)
	v_lshlrev_b32_e32 v157, 16, v163
	v_lshlrev_b32_e32 v156, 16, v162
	v_lshlrev_b32_e32 v117, 16, v107
	v_lshlrev_b32_e32 v116, 16, v105
	v_lshlrev_b32_e32 v119, 16, v111
	v_lshlrev_b32_e32 v118, 16, v109
	ds_read_u16 v101, v134 offset:16368
	ds_read_u16 v105, v134 offset:16896
	ds_read_u16 v107, v134 offset:17424
	ds_read_u16 v109, v134 offset:17952
	ds_read_u16 v111, v134 offset:18480
	ds_read_u16 v162, v134 offset:19008
	ds_read_u16 v163, v134 offset:19536
	ds_read_u16 v164, v134 offset:20064
	s_waitcnt lgkmcnt(7)
	v_lshlrev_b32_e32 v159, 16, v101
	v_lshlrev_b32_e32 v158, 16, v165
	v_mul_f32_e32 v117, v112, v117
	v_mul_f32_e32 v116, v112, v116
	v_mul_f32_e32 v119, v112, v119
	v_mul_f32_e32 v118, v112, v118
	v_mul_f32_e32 v157, v112, v157
	v_mul_f32_e32 v156, v112, v156
	v_mul_f32_e32 v159, v112, v159
	v_mul_f32_e32 v158, v112, v158
	v_cvt_pk_bf16_f32 v116, v116, v117
	v_cvt_pk_bf16_f32 v117, v118, v119
	v_cvt_pk_bf16_f32 v118, v156, v157
	v_cvt_pk_bf16_f32 v119, v158, v159
	global_store_dwordx4 v[160:161], v[116:119], off offset:1536
	s_waitcnt lgkmcnt(1)
	v_lshlrev_b32_e32 v157, 16, v163
	v_lshlrev_b32_e32 v156, 16, v162
	v_lshlrev_b32_e32 v117, 16, v107
	v_lshlrev_b32_e32 v116, 16, v105
	v_lshlrev_b32_e32 v119, 16, v111
	v_lshlrev_b32_e32 v118, 16, v109
	ds_read_u16 v101, v134 offset:20592
	ds_read_u16 v105, v134 offset:21120
	ds_read_u16 v107, v134 offset:21648
	ds_read_u16 v109, v134 offset:22176
	ds_read_u16 v111, v134 offset:22704
	ds_read_u16 v162, v134 offset:23232
	ds_read_u16 v163, v134 offset:23760
	ds_read_u16 v165, v134 offset:24288
	s_waitcnt lgkmcnt(7)
	v_lshlrev_b32_e32 v159, 16, v101
	v_lshlrev_b32_e32 v158, 16, v164
	v_mul_f32_e32 v117, v112, v117
	v_mul_f32_e32 v116, v112, v116
	v_mul_f32_e32 v119, v112, v119
	v_mul_f32_e32 v118, v112, v118
	v_mul_f32_e32 v157, v112, v157
	v_mul_f32_e32 v156, v112, v156
	v_mul_f32_e32 v159, v112, v159
	v_mul_f32_e32 v158, v112, v158
	v_cvt_pk_bf16_f32 v116, v116, v117
	v_cvt_pk_bf16_f32 v117, v118, v119
	v_cvt_pk_bf16_f32 v118, v156, v157
	v_cvt_pk_bf16_f32 v119, v158, v159
	global_store_dwordx4 v[160:161], v[116:119], off offset:2048
	s_waitcnt lgkmcnt(1)
	v_lshlrev_b32_e32 v157, 16, v163
	v_lshlrev_b32_e32 v156, 16, v162
	v_lshlrev_b32_e32 v117, 16, v107
	v_lshlrev_b32_e32 v116, 16, v105
	v_lshlrev_b32_e32 v119, 16, v111
	v_lshlrev_b32_e32 v118, 16, v109
	ds_read_u16 v101, v134 offset:24816
	ds_read_u16 v105, v134 offset:25344
	ds_read_u16 v107, v134 offset:25872
	ds_read_u16 v109, v134 offset:26400
	ds_read_u16 v111, v134 offset:26928
	ds_read_u16 v162, v134 offset:27456
	ds_read_u16 v163, v134 offset:27984
	ds_read_u16 v164, v134 offset:28512
	s_waitcnt lgkmcnt(7)
	v_lshlrev_b32_e32 v159, 16, v101
	v_lshlrev_b32_e32 v158, 16, v165
	v_mul_f32_e32 v117, v112, v117
	v_mul_f32_e32 v116, v112, v116
	v_mul_f32_e32 v119, v112, v119
	v_mul_f32_e32 v118, v112, v118
	v_mul_f32_e32 v157, v112, v157
	v_mul_f32_e32 v156, v112, v156
	v_mul_f32_e32 v159, v112, v159
	v_mul_f32_e32 v158, v112, v158
	v_cvt_pk_bf16_f32 v116, v116, v117
	v_cvt_pk_bf16_f32 v117, v118, v119
	v_cvt_pk_bf16_f32 v118, v156, v157
	v_cvt_pk_bf16_f32 v119, v158, v159
	global_store_dwordx4 v[160:161], v[116:119], off offset:2560
	s_waitcnt lgkmcnt(1)
; DI float bf2f(bf16_t b) { return __uint_as_float(((unsigned)b) << 16); }
; DI unsigned pk2(float lo, float hi) { f32x2 v = {lo, hi}; bfv2 b = __builtin_convertvector(v, bfv2); return __builtin_bit_cast(unsigned, b); }
; DI void phase_prep(const Params& p, int j, unsigned char* lds) {
;     ...
;             for (int tg = 0; tg < 8; ++tg) {
;                 float val[8];
; #pragma unroll
;                 for (int i = 0; i < 8; ++i) val[i] = bf2f(kt[(dir * 64 + 8 * tg + i) * 264 + kk]) * dlast;
;                 u32x4 pk; pk.x = pk2(val[0], val[1]); pk.y = pk2(val[2], val[3]); pk.z = pk2(val[4], val[5]); pk.w = pk2(val[6], val[7]);
;                 const int s = tg >> 1, hh = tg & 1;
;                 *(u32x4*)(KHp + ((w8 * 4 + s) * 64 + hh * 32 + r) * 8) = pk;
;     ...
;         {
;             bf16_t* QTp = (bf16_t*)(p.ws + WS_U) + (size_t)(item * 2) * 16384;
; #pragma unroll
;             for (int it = 0; it < 8; ++it) {
;                 const int idx = it * 512 + tid; const int d2 = idx >> 11, f = (idx >> 6) & 31, ln = idx & 63;
;                 const int w8 = f >> 2, mb = (f >> 1) & 1, s = f & 1, rr = ln & 31, hh = ln >> 5;
;                 const bf16_t* sp = qt + (d2 * 64 + 32 * mb + rr) * 264 + 32 * w8 + 16 * s + 4 * hh;
;                 const u32x2 lo = *(const u32x2*)sp, hi = *(const u32x2*)(sp + 8);
;                 u32x4 o; o.x = lo.x; o.y = lo.y; o.z = hi.x; o.w = hi.y;
;                 *(u32x4*)(QTp + (size_t)d2 * 16384 + (f * 64 + ln) * 8) = o;
;             }
;         }
;         float amask[4][4];
;         {
;             const int d2 = wave >> 2, wd = wave & 3, fr = lane & 15, fq = lane >> 4;
;             f32x4 acc[4];
; #pragma unroll
;             for (int nb = 0; nb < 4; ++nb) acc[nb] = (f32x4){0.f, 0.f, 0.f, 0.f};
;             const bf16_t* qb = qt + (d2 * 64 + 16 * wd + fr) * 264 + 8 * fq;
;             const bf16_t* kb = kt + (d2 * 64 + fr) * 264 + 8 * fq;
; #pragma unroll
;             for (int ks = 0; ks < 8; ++ks) {
;                 const bf16x8 a = *(const bf16x8*)(qb + 32 * ks);
; #pragma unroll
;                 for (int nb = 0; nb < 4; ++nb) { const bf16x8 b = *(const bf16x8*)(kb + nb * 16 * 264 + 32 * ks); acc[nb] = __builtin_amdgcn_mfma_f32_16x16x32_bf16(a, b, acc[nb], 0, 0, 0); }
	v_lshlrev_b32_e32 v157, 16, v163
	v_lshlrev_b32_e32 v156, 16, v162
	v_lshlrev_b32_e32 v117, 16, v107
	v_lshlrev_b32_e32 v116, 16, v105
	v_lshlrev_b32_e32 v119, 16, v111
	v_lshlrev_b32_e32 v118, 16, v109
	ds_read_u16 v101, v134 offset:29040
	ds_read_u16 v105, v134 offset:29568
	ds_read_u16 v107, v134 offset:30096
	ds_read_u16 v109, v134 offset:30624
	ds_read_u16 v111, v134 offset:31152
	ds_read_u16 v162, v134 offset:31680
	ds_read_u16 v163, v134 offset:32208
	ds_read_u16 v165, v134 offset:32736
	s_waitcnt lgkmcnt(7)
	v_lshlrev_b32_e32 v159, 16, v101
	v_lshlrev_b32_e32 v158, 16, v164
	v_mul_f32_e32 v117, v112, v117
	v_mul_f32_e32 v116, v112, v116
	v_mul_f32_e32 v119, v112, v119
	v_mul_f32_e32 v118, v112, v118
	v_mul_f32_e32 v157, v112, v157
	v_mul_f32_e32 v156, v112, v156
	v_mul_f32_e32 v159, v112, v159
	v_mul_f32_e32 v158, v112, v158
	v_cvt_pk_bf16_f32 v116, v116, v117
	v_cvt_pk_bf16_f32 v117, v118, v119
	v_cvt_pk_bf16_f32 v118, v156, v157
	v_cvt_pk_bf16_f32 v119, v158, v159
	global_store_dwordx4 v[160:161], v[116:119], off offset:3072
	s_waitcnt lgkmcnt(1)
	v_lshlrev_b32_e32 v157, 16, v163
	v_lshlrev_b32_e32 v156, 16, v162
	v_lshlrev_b32_e32 v117, 16, v107
	v_lshlrev_b32_e32 v116, 16, v105
	v_lshlrev_b32_e32 v119, 16, v111
	v_lshlrev_b32_e32 v118, 16, v109
	v_lshlrev_b32_e32 v159, 16, v103
	s_waitcnt lgkmcnt(0)
	v_lshlrev_b32_e32 v158, 16, v165
	v_mul_f32_e32 v117, v112, v117
	v_mul_f32_e32 v116, v112, v116
	v_mul_f32_e32 v119, v112, v119
	v_mul_f32_e32 v118, v112, v118
	v_mul_f32_e32 v157, v112, v157
	v_mul_f32_e32 v156, v112, v156
	v_mul_f32_e32 v159, v112, v159
	v_mul_f32_e32 v158, v112, v158
	v_cvt_pk_bf16_f32 v116, v116, v117
	v_cvt_pk_bf16_f32 v117, v118, v119
	v_cvt_pk_bf16_f32 v118, v156, v157
	v_cvt_pk_bf16_f32 v119, v158, v159
	global_store_dwordx4 v[160:161], v[116:119], off offset:3584
	s_barrier
	ds_read_b128 v[116:119], v121 offset:8192
	ds_read_b128 v[156:159], v122
	ds_read_b128 v[160:163], v121 offset:8256
	ds_read_b128 v[164:167], v122 offset:64
	ds_read_b128 v[168:171], v122 offset:8448
	ds_read_b128 v[172:175], v122 offset:8512
	s_waitcnt lgkmcnt(4)
	v_mfma_f32_16x16x32_bf16 v[156:159], v[116:119], v[156:159], 0
	ds_read_b128 v[176:179], v122 offset:16896
	ds_read_b128 v[180:183], v122 offset:16960
	ds_read_b128 v[184:187], v122 offset:25344
	ds_read_b128 v[188:191], v122 offset:25408
	v_add_u32_e32 v101, 0x2000, v135
	s_waitcnt lgkmcnt(5)
	v_mfma_f32_16x16x32_bf16 v[168:171], v[116:119], v[168:171], 0
	s_add_u32 s60, s72, s60
	s_addc_u32 s61, s73, s61
	v_mov_b32_e32 v105, v69
	v_mfma_f32_16x16x32_bf16 v[156:159], v[160:163], v[164:167], v[156:159]
	v_mov_b32_e32 v107, v69
	s_add_u32 s82, s60, 0x8000
	s_addc_u32 s83, s61, 0
	s_waitcnt lgkmcnt(4)
	v_mfma_f32_16x16x32_bf16 v[164:167], v[160:163], v[172:175], v[168:171]
	ds_read_b128 v[172:175], v121 offset:8320
	v_mov_b32_e32 v109, v69
	v_mov_b32_e32 v111, v69
	s_waitcnt lgkmcnt(4)
	v_mfma_f32_16x16x32_bf16 v[176:179], v[116:119], v[176:179], 0
	s_lshl_b64 s[58:59], s[58:59], 13
	s_add_u32 s58, s74, s58
	v_mov_b32_e32 v103, v69
	s_waitcnt lgkmcnt(2)
	v_mfma_f32_16x16x32_bf16 v[116:119], v[116:119], v[184:187], 0
	s_addc_u32 s59, s75, s59
	s_ashr_i32 s55, s54, 31
	s_lshl_b64 s[54:55], s[54:55], 15
	v_mfma_f32_16x16x32_bf16 v[168:171], v[160:163], v[180:183], v[176:179]
	s_add_u32 s54, s76, s54
	s_addc_u32 s55, s77, s55
	s_waitcnt lgkmcnt(1)
	v_mfma_f32_16x16x32_bf16 v[116:119], v[160:163], v[188:191], v[116:119]
	ds_read_b128 v[160:163], v122 offset:128
	ds_read_b128 v[176:179], v121 offset:8384
	ds_read_b128 v[180:183], v122 offset:192
	s_waitcnt lgkmcnt(2)
	v_mfma_f32_16x16x32_bf16 v[156:159], v[172:175], v[160:163], v[156:159]
	ds_read_b128 v[160:163], v122 offset:8576
	ds_read_b128 v[184:187], v122 offset:8640
	s_waitcnt lgkmcnt(1)
	v_mfma_f32_16x16x32_bf16 v[160:163], v[172:175], v[160:163], v[164:167]
	s_nop 2
	ds_read_b128 v[164:167], v122 offset:17024
	ds_read_b128 v[188:191], v122 offset:17088
	s_waitcnt lgkmcnt(1)
	v_mfma_f32_16x16x32_bf16 v[164:167], v[172:175], v[164:167], v[168:171]
	s_nop 2
	ds_read_b128 v[168:171], v122 offset:25472
	ds_read_b128 v[192:195], v122 offset:25536
	s_waitcnt lgkmcnt(1)
	v_mfma_f32_16x16x32_bf16 v[116:119], v[172:175], v[168:171], v[116:119]
	ds_read_b128 v[168:171], v121 offset:8448
	ds_read_b128 v[172:175], v122 offset:256
	v_mfma_f32_16x16x32_bf16 v[156:159], v[176:179], v[180:183], v[156:159]
	v_mfma_f32_16x16x32_bf16 v[160:163], v[176:179], v[184:187], v[160:163]
	v_mfma_f32_16x16x32_bf16 v[164:167], v[176:179], v[188:191], v[164:167]
	s_waitcnt lgkmcnt(2)
	v_mfma_f32_16x16x32_bf16 v[116:119], v[176:179], v[192:195], v[116:119]
	ds_read_b128 v[176:179], v122 offset:8704
	ds_read_b128 v[180:183], v121 offset:8512
	ds_read_b128 v[184:187], v122 offset:320
	s_waitcnt lgkmcnt(3)
	v_mfma_f32_16x16x32_bf16 v[156:159], v[168:171], v[172:175], v[156:159]
	ds_read_b128 v[172:175], v122 offset:17152
	ds_read_b128 v[188:191], v122 offset:8768
	s_waitcnt lgkmcnt(4)
	v_mfma_f32_16x16x32_bf16 v[160:163], v[168:171], v[176:179], v[160:163]
	ds_read_b128 v[176:179], v122 offset:25600
	ds_read_b128 v[192:195], v122 offset:17216
	s_waitcnt lgkmcnt(3)
	v_mfma_f32_16x16x32_bf16 v[164:167], v[168:171], v[172:175], v[164:167]
	ds_read2_b64 v[172:175], v101 offset1:2
	ds_read2_b64 v[196:199], v150 offset1:2
	ds_read_b128 v[200:203], v122 offset:25664
	v_add_u32_e32 v101, 0xa000, v135
	s_waitcnt lgkmcnt(2)
	global_store_dwordx4 v102, v[172:175], s[60:61]
	v_mfma_f32_16x16x32_bf16 v[116:119], v[168:171], v[176:179], v[116:119]
	ds_read2_b64 v[168:171], v151 offset1:2
	s_waitcnt lgkmcnt(2)
	global_store_dwordx4 v140, v[196:199], s[60:61]
	s_waitcnt lgkmcnt(0)
; DI void phase_prep(const Params& p, int j, unsigned char* lds) {
;     ...
;         {
;             bf16_t* QTp = (bf16_t*)(p.ws + WS_U) + (size_t)(item * 2) * 16384;
; #pragma unroll
;             for (int it = 0; it < 8; ++it) {
;                 const int idx = it * 512 + tid; const int d2 = idx >> 11, f = (idx >> 6) & 31, ln = idx & 63;
;                 const int w8 = f >> 2, mb = (f >> 1) & 1, s = f & 1, rr = ln & 31, hh = ln >> 5;
;                 const bf16_t* sp = qt + (d2 * 64 + 32 * mb + rr) * 264 + 32 * w8 + 16 * s + 4 * hh;
;                 const u32x2 lo = *(const u32x2*)sp, hi = *(const u32x2*)(sp + 8);
;                 u32x4 o; o.x = lo.x; o.y = lo.y; o.z = hi.x; o.w = hi.y;
;                 *(u32x4*)(QTp + (size_t)d2 * 16384 + (f * 64 + ln) * 8) = o;
;             }
;         }
;         float amask[4][4];
;         {
;             const int d2 = wave >> 2, wd = wave & 3, fr = lane & 15, fq = lane >> 4;
;             f32x4 acc[4];
; #pragma unroll
;             for (int nb = 0; nb < 4; ++nb) acc[nb] = (f32x4){0.f, 0.f, 0.f, 0.f};
;             const bf16_t* qb = qt + (d2 * 64 + 16 * wd + fr) * 264 + 8 * fq;
;             const bf16_t* kb = kt + (d2 * 64 + fr) * 264 + 8 * fq;
; #pragma unroll
;             for (int ks = 0; ks < 8; ++ks) {
;                 const bf16x8 a = *(const bf16x8*)(qb + 32 * ks);
; #pragma unroll
;                 for (int nb = 0; nb < 4; ++nb) { const bf16x8 b = *(const bf16x8*)(kb + nb * 16 * 264 + 32 * ks); acc[nb] = __builtin_amdgcn_mfma_f32_16x16x32_bf16(a, b, acc[nb], 0, 0, 0); }
;             }
; #pragma unroll
;             for (int nb = 0; nb < 4; ++nb)
; #pragma unroll
;                 for (int jx = 0; jx < 4; ++jx) {
;                     const int i = 16 * wd + 4 * fq + jx, jt = 16 * nb + fr;
;                     const bool keep = d2 ? (jt >= i) : (jt <= i);
;                     amask[nb][jx] = keep ? acc[nb][jx] : 0.f;
;                 }
;         }
	global_store_dwordx4 v141, v[168:171], s[60:61]
	ds_read_b128 v[172:175], v121 offset:8576
	ds_read2_b64 v[168:171], v152 offset1:2
	v_lshl_add_u64 v[176:177], s[60:61], 0, v[104:105]
	v_mfma_f32_16x16x32_bf16 v[164:167], v[180:183], v[192:195], v[164:167]
	v_lshl_add_u64 v[192:193], v[176:177], 0, v[106:107]
	ds_read_b128 v[176:179], v122 offset:384
	v_mfma_f32_16x16x32_bf16 v[156:159], v[180:183], v[184:187], v[156:159]
	v_mfma_f32_16x16x32_bf16 v[160:163], v[180:183], v[188:191], v[160:163]
	v_mfma_f32_16x16x32_bf16 v[116:119], v[180:183], v[200:203], v[116:119]
	ds_read_b128 v[180:183], v122 offset:8832
	ds_read_b128 v[184:187], v121 offset:8640
	ds_read_b128 v[188:191], v122 offset:448
	s_waitcnt lgkmcnt(4)
	global_store_dwordx4 v[192:193], v[168:171], off
	s_waitcnt lgkmcnt(3)
	v_mfma_f32_16x16x32_bf16 v[156:159], v[172:175], v[176:179], v[156:159]
	ds_read_b128 v[168:171], v122 offset:17280
	ds_read_b128 v[176:179], v122 offset:8896
	s_waitcnt lgkmcnt(4)
	v_mfma_f32_16x16x32_bf16 v[160:163], v[172:175], v[180:183], v[160:163]
	ds_read_b128 v[180:183], v122 offset:25728
	ds_read_b128 v[192:195], v122 offset:17344
	ds_read_b128 v[196:199], v122 offset:25792
	s_waitcnt lgkmcnt(4)
	v_mfma_f32_16x16x32_bf16 v[164:167], v[172:175], v[168:171], v[164:167]
	ds_read2_b64 v[168:171], v101 offset0:128 offset1:130
	s_waitcnt lgkmcnt(3)
	v_mfma_f32_16x16x32_bf16 v[116:119], v[172:175], v[180:183], v[116:119]
	ds_read2_b64 v[172:175], v153 offset0:128 offset1:130
	ds_read2_b64 v[180:183], v154 offset0:128 offset1:130
	s_waitcnt lgkmcnt(2)
	global_store_dwordx4 v102, v[168:171], s[82:83]
	s_waitcnt lgkmcnt(1)
	global_store_dwordx4 v142, v[172:175], s[82:83]
	s_waitcnt lgkmcnt(0)
	global_store_dwordx4 v143, v[180:183], s[82:83]
	v_mfma_f32_16x16x32_bf16 v[156:159], v[184:187], v[188:191], v[156:159]
	ds_read2_b64 v[168:171], v155 offset1:2
	v_lshl_add_u64 v[172:173], s[60:61], 0, v[108:109]
	v_lshl_add_u64 v[172:173], v[172:173], 0, v[110:111]
	v_mfma_f32_16x16x32_bf16 v[160:163], v[184:187], v[176:179], v[160:163]
	s_waitcnt lgkmcnt(0)
	global_store_dwordx4 v[172:173], v[168:171], off
	s_nop 1
	v_cvt_pk_bf16_f32 v101, v156, s0
	v_mfma_f32_16x16x32_bf16 v[164:167], v[184:187], v[192:195], v[164:167]
	v_cvt_pk_bf16_f32 v105, v157, s0
	v_cvt_pk_bf16_f32 v107, v158, s0
	v_cvt_pk_bf16_f32 v109, v159, s0
	v_mfma_f32_16x16x32_bf16 v[116:119], v[184:187], v[196:199], v[116:119]
	v_cvt_pk_bf16_f32 v111, v160, s0
	v_cvt_pk_bf16_f32 v112, v161, s0
	v_cvt_pk_bf16_f32 v156, v162, s0
	v_cvt_pk_bf16_f32 v157, v163, s0
	v_cvt_pk_bf16_f32 v158, v164, s0
	v_cvt_pk_bf16_f32 v159, v165, s0
	v_cvt_pk_bf16_f32 v160, v166, s0
	v_cvt_pk_bf16_f32 v161, v167, s0
	v_cvt_pk_bf16_f32 v116, v116, s0
	v_cvt_pk_bf16_f32 v117, v117, s0
	v_cvt_pk_bf16_f32 v118, v118, s0
	v_cvt_pk_bf16_f32 v119, v119, s0
	v_cndmask_b32_e64 v101, 0, v101, s[6:7]
	v_cndmask_b32_e64 v105, 0, v105, s[8:9]
	v_cndmask_b32_e64 v107, 0, v107, s[10:11]
	v_cndmask_b32_e64 v109, 0, v109, s[12:13]
	v_cndmask_b32_e64 v111, 0, v111, s[14:15]
	v_cndmask_b32_e64 v112, 0, v112, s[16:17]
	v_cndmask_b32_e64 v156, 0, v156, s[18:19]
	v_cndmask_b32_e64 v157, 0, v157, s[20:21]
	v_cndmask_b32_e64 v158, 0, v158, s[22:23]
	v_cndmask_b32_e64 v159, 0, v159, s[24:25]
	v_cndmask_b32_e64 v160, 0, v160, s[26:27]
	v_cndmask_b32_e64 v161, 0, v161, s[28:29]
	v_cndmask_b32_e64 v116, 0, v116, s[30:31]
	v_cndmask_b32_e64 v117, 0, v117, s[34:35]
	v_cndmask_b32_e64 v118, 0, v118, s[36:37]
	v_cndmask_b32_e64 v119, 0, v119, s[38:39]
	s_barrier
; DI bf16_t f2bf(float f) { return (bf16_t)(pk2(f, 0.f) & 0xffffu); }
; DI void phase_prep(const Params& p, int j, unsigned char* lds) {
;     ...
;         {
; #pragma unroll
;             for (int it = 0; it < 4; ++it) { const int idx = it * 512 + tid; const int t = idx >> 5, seg = idx & 31; *(u32x4*)(qt + t * 264 + seg * 8) = vcur[it]; }
;         }
;         {
;             const int d2 = wave >> 2, wd = wave & 3, fr = lane & 15, fq = lane >> 4;
; #pragma unroll
;             for (int nb = 0; nb < 4; ++nb)
; #pragma unroll
;                 for (int jx = 0; jx < 4; ++jx) {
;                     const int i = 16 * wd + 4 * fq + jx, jt = 16 * nb + fr;
;                     const int mb = i >> 5, r = i & 31, hh = (jt >> 3) & 1, jj = jt & 7;
;                     kt[d2 * 4096 + ((nb * 2 + mb) * 64 + hh * 32 + r) * 8 + jj] = f2bf(amask[nb][jx]);
;                 }
;         }
;         __syncthreads();
;         {
;             bf16_t* AMp = (bf16_t*)(p.ws + WS_AM) + (size_t)(item * 2) * 4096;
;             *(u32x4*)(AMp + tid * 8) = *(const u32x4*)(kt + tid * 8);
;             *(u32x4*)(AMp + 4096 + tid * 8) = *(const u32x4*)(kt + 4096 + tid * 8);
;         }
;         {
;             bf16_t* VTp = (bf16_t*)(p.ws + WS_VT) + (size_t)item * 16384;
; #pragma unroll
;             for (int it = 0; it < 4; ++it) {
;                 const int idx = it * 512 + tid; const int f = idx >> 6, ln = idx & 63; const int sl = f >> 2, s = f & 3, rr = ln & 31, hh = ln >> 5;
;                 const bf16_t* sp = qt + (16 * s + 8 * hh) * 264 + 32 * sl + rr;
;                 unsigned e[8];
; #pragma unroll
;                 for (int jj = 0; jj < 8; ++jj) e[jj] = sp[jj * 264];
;                 u32x4 o; o.x = e[0] | (e[1] << 16); o.y = e[2] | (e[3] << 16); o.z = e[4] | (e[5] << 16); o.w = e[6] | (e[7] << 16);
;                 *(u32x4*)(VTp + (f * 64 + ln) * 8) = o;
;             }
;         }
;         __syncthreads();
	ds_write_b128 v144, v[2:5] offset:8192
	ds_write_b128 v145, v[6:9] offset:8192
	ds_write_b128 v146, v[10:13] offset:8192
	s_waitcnt vmcnt(47)
	ds_write_b128 v147, v[14:17] offset:8192
	ds_write_b16 v148, v101
	ds_write_b16 v148, v105 offset:16
	ds_write_b16 v148, v107 offset:32
	ds_write_b16 v148, v109 offset:48
	ds_write_b16 v148, v111 offset:2048
	ds_write_b16 v148, v112 offset:2064
	ds_write_b16 v148, v156 offset:2080
	ds_write_b16 v148, v157 offset:2096
	ds_write_b16 v148, v158 offset:4096
	ds_write_b16 v148, v159 offset:4112
	ds_write_b16 v148, v160 offset:4128
	ds_write_b16 v148, v161 offset:4144
	ds_write_b16 v148, v116 offset:6144
	ds_write_b16 v148, v117 offset:6160
	ds_write_b16 v148, v118 offset:6176
	ds_write_b16 v148, v119 offset:6192
	s_waitcnt lgkmcnt(0)
	s_barrier
	ds_read_b128 v[2:5], v124
	ds_read_b128 v[6:9], v125
	v_lshl_add_u64 v[10:11], s[58:59], 0, v[102:103]
	s_waitcnt vmcnt(16)
	v_mov_b64_e32 v[14:15], v[62:63]
	v_mov_b64_e32 v[16:17], v[64:65]
	s_waitcnt lgkmcnt(1)
	global_store_dwordx4 v102, v[2:5], s[58:59]
	s_nop 1
	v_add_co_u32_e32 v2, vcc, s64, v10
	s_nop 1
	v_addc_co_u32_e32 v3, vcc, 0, v11, vcc
	s_waitcnt lgkmcnt(0)
	global_store_dwordx4 v[2:3], v[6:9], off
	ds_read_u16 v2, v136 offset:8192
	ds_read_u16 v3, v136 offset:8720
	ds_read_u16 v4, v136 offset:9248
	ds_read_u16 v5, v136 offset:9776
	ds_read_u16 v6, v136 offset:10304
	ds_read_u16 v7, v136 offset:10832
	ds_read_u16 v8, v136 offset:11360
	ds_read_u16 v9, v136 offset:11888
	s_waitcnt lgkmcnt(6)
	v_lshl_or_b32 v2, v3, 16, v2
	s_waitcnt lgkmcnt(4)
	v_lshl_or_b32 v3, v5, 16, v4
	s_waitcnt lgkmcnt(2)
	v_lshl_or_b32 v4, v7, 16, v6
	s_and_b64 vcc, s[56:57], exec
	s_waitcnt lgkmcnt(0)
	v_lshl_or_b32 v5, v9, 16, v8
	ds_read_u16 v6, v137 offset:8192
	ds_read_u16 v7, v137 offset:8720
	ds_read_u16 v8, v137 offset:9248
	ds_read_u16 v9, v137 offset:9776
	ds_read_u16 v10, v137 offset:10304
	ds_read_u16 v11, v137 offset:10832
	ds_read_u16 v12, v137 offset:11360
	ds_read_u16 v13, v137 offset:11888
	global_store_dwordx4 v102, v[2:5], s[54:55]
	s_waitcnt lgkmcnt(6)
	s_nop 0
	v_lshl_or_b32 v2, v7, 16, v6
	s_waitcnt lgkmcnt(4)
	v_lshl_or_b32 v3, v9, 16, v8
	s_waitcnt lgkmcnt(2)
	v_lshl_or_b32 v4, v11, 16, v10
	s_waitcnt lgkmcnt(0)
	v_lshl_or_b32 v5, v13, 16, v12
	ds_read_u16 v6, v138 offset:8192
	ds_read_u16 v7, v138 offset:8720
	ds_read_u16 v8, v138 offset:9248
	ds_read_u16 v9, v138 offset:9776
	ds_read_u16 v10, v138 offset:10304
	ds_read_u16 v11, v138 offset:10832
	ds_read_u16 v12, v138 offset:11360
	ds_read_u16 v13, v138 offset:11888
	global_store_dwordx4 v140, v[2:5], s[54:55]
	s_waitcnt lgkmcnt(6)
	s_nop 0
	v_lshl_or_b32 v2, v7, 16, v6
	s_waitcnt lgkmcnt(4)
	v_lshl_or_b32 v3, v9, 16, v8
	s_waitcnt lgkmcnt(2)
	v_lshl_or_b32 v4, v11, 16, v10
	s_waitcnt lgkmcnt(0)
	v_lshl_or_b32 v5, v13, 16, v12
	ds_read_u16 v6, v139 offset:8192
	ds_read_u16 v7, v139 offset:8720
	ds_read_u16 v8, v139 offset:9248
	ds_read_u16 v9, v139 offset:9776
	ds_read_u16 v10, v139 offset:10304
	ds_read_u16 v11, v139 offset:10832
	ds_read_u16 v12, v139 offset:11360
	ds_read_u16 v13, v139 offset:11888
	global_store_dwordx4 v141, v[2:5], s[54:55]
	s_waitcnt lgkmcnt(6)
	s_nop 0
	v_lshl_or_b32 v2, v7, 16, v6
	s_waitcnt lgkmcnt(4)
	v_lshl_or_b32 v3, v9, 16, v8
	s_waitcnt lgkmcnt(2)
	v_lshl_or_b32 v4, v11, 16, v10
	s_waitcnt lgkmcnt(0)
	v_lshl_or_b32 v5, v13, 16, v12
	global_store_dwordx4 v149, v[2:5], s[54:55]
	v_mov_b64_e32 v[6:7], v[54:55]
	v_mov_b64_e32 v[10:11], v[58:59]
	v_mov_b64_e32 v[2:3], v[50:51]
	v_mov_b64_e32 v[4:5], v[52:53]
	v_mov_b64_e32 v[8:9], v[56:57]
	v_mov_b64_e32 v[12:13], v[60:61]
	s_mov_b32 s54, s81
	s_barrier
	s_cbranch_vccz .LBB0_1540

; template <int DIR>
; DI float prep_gate_loop(const float* r_s, bf16_t* qt, bf16_t* kt, const float (&w)[16], float bias, int kk) {
;     ...
;     for (int blk = 0; blk < 4; ++blk) {
;         float la[16];
; #pragma unroll
;         for (int i = 0; i < 16; ++i) {
;             const int tt = blk * 16 + i; const int t = DIR ? 63 - tt : tt;
;             const f32x4* rr = (const f32x4*)(r_s + t * 32 + DIR * 16);
;             const f32x4 r0 = rr[0], r1 = rr[1], r2 = rr[2], r3 = rr[3];
;             float s0 = __builtin_fmaf(r0[0], w[0], bias), s1 = r0[1] * w[1], s2 = r0[2] * w[2], s3 = r0[3] * w[3];
;             s0 = __builtin_fmaf(r1[0], w[4], s0); s1 = __builtin_fmaf(r1[1], w[5], s1); s2 = __builtin_fmaf(r1[2], w[6], s2); s3 = __builtin_fmaf(r1[3], w[7], s3);
;             s0 = __builtin_fmaf(r2[0], w[8], s0); s1 = __builtin_fmaf(r2[1], w[9], s1); s2 = __builtin_fmaf(r2[2], w[10], s2); s3 = __builtin_fmaf(r2[3], w[11], s3);
;             s0 = __builtin_fmaf(r3[0], w[12], s0); s1 = __builtin_fmaf(r3[1], w[13], s1); s2 = __builtin_fmaf(r3[2], w[14], s2); s3 = __builtin_fmaf(r3[3], w[15], s3);
;             const float pre = (s0 + s1) + (s2 + s3);
;             const float ex = __builtin_amdgcn_exp2f(-fabsf(pre) * LOG2E);
;             la[i] = (fminf(pre, 0.f) * LOG2E - __builtin_amdgcn_logf(1.f + ex)) * 0.0625f;
;         }
.LBB0_1535:
	v_mov_b32_e32 v32, s55
	ds_read_b128 v[18:21], v32 offset:1920
	ds_read_b128 v[22:25], v32 offset:1936
	ds_read_b128 v[26:29], v32 offset:1952
	ds_read_b128 v[34:37], v32 offset:1968
	s_addk_i32 s55, 0xf800
	s_waitcnt lgkmcnt(3)
	v_fma_f32 v18, v18, v85, v123
	v_mul_f32_e32 v19, v76, v19
	v_mul_f32_e32 v20, v73, v20
	v_mul_f32_e32 v21, v77, v21
	s_waitcnt lgkmcnt(2)
	v_fmac_f32_e32 v18, v22, v74
	v_fmac_f32_e32 v19, v23, v78
	v_fmac_f32_e32 v20, v24, v75
	v_fmac_f32_e32 v21, v25, v79
	s_waitcnt lgkmcnt(1)
	v_fmac_f32_e32 v18, v26, v80
	v_fmac_f32_e32 v19, v27, v88
	v_fmac_f32_e32 v20, v28, v81
	v_fmac_f32_e32 v21, v29, v89
	s_waitcnt lgkmcnt(0)
	v_fmac_f32_e32 v18, v34, v86
	v_fmac_f32_e32 v19, v35, v92
	v_fmac_f32_e32 v20, v36, v87
	v_fmac_f32_e32 v21, v37, v93
	v_add_f32_e32 v18, v18, v19
	v_add_f32_e32 v19, v20, v21
	v_add_f32_e32 v18, v18, v19
	v_mul_f32_e64 v19, |v18|, s79
	v_exp_f32_e32 v19, v19
	v_min_f32_e32 v18, 0, v18
	v_add_f32_e32 v19, 1.0, v19
	v_log_f32_e32 v19, v19
	s_nop 0
	v_fma_f32 v38, v18, s80, -v19
	ds_read_b128 v[18:21], v32 offset:1792
	ds_read_b128 v[22:25], v32 offset:1808
	ds_read_b128 v[26:29], v32 offset:1824
	ds_read_b128 v[34:37], v32 offset:1840
	v_fmac_f32_e32 v33, 0x3d800000, v38
	s_waitcnt lgkmcnt(3)
	v_fma_f32 v18, v18, v85, v123
	v_mul_f32_e32 v19, v76, v19
	v_mul_f32_e32 v20, v73, v20
	v_mul_f32_e32 v21, v77, v21
	s_waitcnt lgkmcnt(2)
	v_fmac_f32_e32 v18, v22, v74
	v_fmac_f32_e32 v19, v23, v78
	v_fmac_f32_e32 v20, v24, v75
	v_fmac_f32_e32 v21, v25, v79
	s_waitcnt lgkmcnt(1)
	v_fmac_f32_e32 v18, v26, v80
	v_fmac_f32_e32 v19, v27, v88
	v_fmac_f32_e32 v20, v28, v81
	v_fmac_f32_e32 v21, v29, v89
	s_waitcnt lgkmcnt(0)
	v_fmac_f32_e32 v18, v34, v86
	v_fmac_f32_e32 v19, v35, v92
	v_fmac_f32_e32 v20, v36, v87
	v_fmac_f32_e32 v21, v37, v93
	v_add_f32_e32 v18, v18, v19
	v_add_f32_e32 v19, v20, v21
	v_add_f32_e32 v18, v18, v19
	v_mul_f32_e64 v19, |v18|, s79
	v_exp_f32_e32 v19, v19
	v_min_f32_e32 v18, 0, v18
	v_add_f32_e32 v19, 1.0, v19
	v_log_f32_e32 v19, v19
	s_nop 0
	v_fma_f32 v39, v18, s80, -v19
	ds_read_b128 v[18:21], v32 offset:1664
	ds_read_b128 v[22:25], v32 offset:1680
	ds_read_b128 v[26:29], v32 offset:1696
	ds_read_b128 v[34:37], v32 offset:1712
	s_waitcnt lgkmcnt(3)
	v_fma_f32 v18, v18, v85, v123
	v_mul_f32_e32 v19, v76, v19
	v_mul_f32_e32 v20, v73, v20
	v_mul_f32_e32 v21, v77, v21
	s_waitcnt lgkmcnt(2)
	v_fmac_f32_e32 v18, v22, v74
	v_fmac_f32_e32 v19, v23, v78
	v_fmac_f32_e32 v20, v24, v75
	v_fmac_f32_e32 v21, v25, v79
	s_waitcnt lgkmcnt(1)
	v_fmac_f32_e32 v18, v26, v80
	v_fmac_f32_e32 v19, v27, v88
	v_fmac_f32_e32 v20, v28, v81
	v_fmac_f32_e32 v21, v29, v89
	s_waitcnt lgkmcnt(0)
	v_fmac_f32_e32 v18, v34, v86
	v_fmac_f32_e32 v19, v35, v92
	v_fmac_f32_e32 v20, v36, v87
	v_fmac_f32_e32 v21, v37, v93
	v_add_f32_e32 v18, v18, v19
	v_add_f32_e32 v19, v20, v21
	v_add_f32_e32 v18, v18, v19
	v_mul_f32_e64 v19, |v18|, s79
	v_exp_f32_e32 v19, v19
	v_min_f32_e32 v18, 0, v18
	v_add_f32_e32 v19, 1.0, v19
	v_log_f32_e32 v19, v19
	s_nop 0
	v_fma_f32 v40, v18, s80, -v19
	ds_read_b128 v[18:21], v32 offset:1536
	ds_read_b128 v[22:25], v32 offset:1552
	ds_read_b128 v[26:29], v32 offset:1568
	ds_read_b128 v[34:37], v32 offset:1584
	s_waitcnt lgkmcnt(3)
	v_fma_f32 v18, v18, v85, v123
	v_mul_f32_e32 v19, v76, v19
	v_mul_f32_e32 v20, v73, v20
	v_mul_f32_e32 v21, v77, v21
	s_waitcnt lgkmcnt(2)
	v_fmac_f32_e32 v18, v22, v74
	v_fmac_f32_e32 v19, v23, v78
	v_fmac_f32_e32 v20, v24, v75
	v_fmac_f32_e32 v21, v25, v79
	s_waitcnt lgkmcnt(1)
	v_fmac_f32_e32 v18, v26, v80
	v_fmac_f32_e32 v19, v27, v88
	v_fmac_f32_e32 v20, v28, v81
	v_fmac_f32_e32 v21, v29, v89
	s_waitcnt lgkmcnt(0)
	v_fmac_f32_e32 v18, v34, v86
	v_fmac_f32_e32 v19, v35, v92
	v_fmac_f32_e32 v20, v36, v87
	v_fmac_f32_e32 v21, v37, v93
	v_add_f32_e32 v18, v18, v19
	v_add_f32_e32 v19, v20, v21
	v_add_f32_e32 v18, v18, v19
	v_mul_f32_e64 v19, |v18|, s79
	v_exp_f32_e32 v19, v19
	v_min_f32_e32 v18, 0, v18
	v_add_f32_e32 v19, 1.0, v19
	v_log_f32_e32 v19, v19
	s_nop 0
	v_fma_f32 v41, v18, s80, -v19
	ds_read_b128 v[18:21], v32 offset:1408
	ds_read_b128 v[22:25], v32 offset:1424
	ds_read_b128 v[26:29], v32 offset:1440
	ds_read_b128 v[34:37], v32 offset:1456
	s_waitcnt lgkmcnt(3)
	v_fma_f32 v18, v18, v85, v123
	v_mul_f32_e32 v19, v76, v19
	v_mul_f32_e32 v20, v73, v20
	v_mul_f32_e32 v21, v77, v21
	s_waitcnt lgkmcnt(2)
	v_fmac_f32_e32 v18, v22, v74
	v_fmac_f32_e32 v19, v23, v78
	v_fmac_f32_e32 v20, v24, v75
	v_fmac_f32_e32 v21, v25, v79
	s_waitcnt lgkmcnt(1)
	v_fmac_f32_e32 v18, v26, v80
	v_fmac_f32_e32 v19, v27, v88
	v_fmac_f32_e32 v20, v28, v81
	v_fmac_f32_e32 v21, v29, v89
	s_waitcnt lgkmcnt(0)
	v_fmac_f32_e32 v18, v34, v86
	v_fmac_f32_e32 v19, v35, v92
	v_fmac_f32_e32 v20, v36, v87
	v_fmac_f32_e32 v21, v37, v93
	v_add_f32_e32 v18, v18, v19
	v_add_f32_e32 v19, v20, v21
	v_add_f32_e32 v18, v18, v19
	v_mul_f32_e64 v19, |v18|, s79
	v_exp_f32_e32 v19, v19
	v_min_f32_e32 v18, 0, v18
	v_add_f32_e32 v19, 1.0, v19
	v_log_f32_e32 v19, v19
	s_nop 0
	v_fma_f32 v42, v18, s80, -v19
	ds_read_b128 v[18:21], v32 offset:1280
	ds_read_b128 v[22:25], v32 offset:1296
	ds_read_b128 v[26:29], v32 offset:1312
	ds_read_b128 v[34:37], v32 offset:1328
	s_waitcnt lgkmcnt(3)
	v_fma_f32 v18, v18, v85, v123
	v_mul_f32_e32 v19, v76, v19
	v_mul_f32_e32 v20, v73, v20
	v_mul_f32_e32 v21, v77, v21
	s_waitcnt lgkmcnt(2)
	v_fmac_f32_e32 v18, v22, v74
	v_fmac_f32_e32 v19, v23, v78
	v_fmac_f32_e32 v20, v24, v75
	v_fmac_f32_e32 v21, v25, v79
	s_waitcnt lgkmcnt(1)
	v_fmac_f32_e32 v18, v26, v80
	v_fmac_f32_e32 v19, v27, v88
	v_fmac_f32_e32 v20, v28, v81
	v_fmac_f32_e32 v21, v29, v89
	s_waitcnt lgkmcnt(0)
; template <int DIR>
; DI float prep_gate_loop(const float* r_s, bf16_t* qt, bf16_t* kt, const float (&w)[16], float bias, int kk) {
;     ...
;     for (int blk = 0; blk < 4; ++blk) {
;         float la[16];
; #pragma unroll
;         for (int i = 0; i < 16; ++i) {
;             const int tt = blk * 16 + i; const int t = DIR ? 63 - tt : tt;
;             const f32x4* rr = (const f32x4*)(r_s + t * 32 + DIR * 16);
;             const f32x4 r0 = rr[0], r1 = rr[1], r2 = rr[2], r3 = rr[3];
;             float s0 = __builtin_fmaf(r0[0], w[0], bias), s1 = r0[1] * w[1], s2 = r0[2] * w[2], s3 = r0[3] * w[3];
;             s0 = __builtin_fmaf(r1[0], w[4], s0); s1 = __builtin_fmaf(r1[1], w[5], s1); s2 = __builtin_fmaf(r1[2], w[6], s2); s3 = __builtin_fmaf(r1[3], w[7], s3);
;             s0 = __builtin_fmaf(r2[0], w[8], s0); s1 = __builtin_fmaf(r2[1], w[9], s1); s2 = __builtin_fmaf(r2[2], w[10], s2); s3 = __builtin_fmaf(r2[3], w[11], s3);
;             s0 = __builtin_fmaf(r3[0], w[12], s0); s1 = __builtin_fmaf(r3[1], w[13], s1); s2 = __builtin_fmaf(r3[2], w[14], s2); s3 = __builtin_fmaf(r3[3], w[15], s3);
;             const float pre = (s0 + s1) + (s2 + s3);
;             const float ex = __builtin_amdgcn_exp2f(-fabsf(pre) * LOG2E);
;             la[i] = (fminf(pre, 0.f) * LOG2E - __builtin_amdgcn_logf(1.f + ex)) * 0.0625f;
;         }
	v_fmac_f32_e32 v18, v34, v86
	v_fmac_f32_e32 v19, v35, v92
	v_fmac_f32_e32 v20, v36, v87
	v_fmac_f32_e32 v21, v37, v93
	v_add_f32_e32 v18, v18, v19
	v_add_f32_e32 v19, v20, v21
	v_add_f32_e32 v18, v18, v19
	v_mul_f32_e64 v19, |v18|, s79
	v_exp_f32_e32 v19, v19
	v_min_f32_e32 v18, 0, v18
	v_add_f32_e32 v19, 1.0, v19
	v_log_f32_e32 v19, v19
	s_nop 0
	v_fma_f32 v43, v18, s80, -v19
	ds_read_b128 v[18:21], v32 offset:1152
	ds_read_b128 v[22:25], v32 offset:1168
	ds_read_b128 v[26:29], v32 offset:1184
	ds_read_b128 v[34:37], v32 offset:1200
	s_waitcnt lgkmcnt(3)
	v_fma_f32 v18, v18, v85, v123
	v_mul_f32_e32 v19, v76, v19
	v_mul_f32_e32 v20, v73, v20
	v_mul_f32_e32 v21, v77, v21
	s_waitcnt lgkmcnt(2)
	v_fmac_f32_e32 v18, v22, v74
	v_fmac_f32_e32 v19, v23, v78
	v_fmac_f32_e32 v20, v24, v75
	v_fmac_f32_e32 v21, v25, v79
	s_waitcnt lgkmcnt(1)
	v_fmac_f32_e32 v18, v26, v80
	v_fmac_f32_e32 v19, v27, v88
	v_fmac_f32_e32 v20, v28, v81
	v_fmac_f32_e32 v21, v29, v89
	s_waitcnt lgkmcnt(0)
	v_fmac_f32_e32 v18, v34, v86
	v_fmac_f32_e32 v19, v35, v92
	v_fmac_f32_e32 v20, v36, v87
	v_fmac_f32_e32 v21, v37, v93
	v_add_f32_e32 v18, v18, v19
	v_add_f32_e32 v19, v20, v21
	v_add_f32_e32 v18, v18, v19
	v_mul_f32_e64 v19, |v18|, s79
	v_exp_f32_e32 v19, v19
	v_min_f32_e32 v18, 0, v18
	v_add_f32_e32 v19, 1.0, v19
	v_log_f32_e32 v19, v19
	s_nop 0
	v_fma_f32 v44, v18, s80, -v19
	ds_read_b128 v[18:21], v32 offset:1024
	ds_read_b128 v[22:25], v32 offset:1040
	ds_read_b128 v[26:29], v32 offset:1056
	ds_read_b128 v[34:37], v32 offset:1072
	s_waitcnt lgkmcnt(3)
	v_fma_f32 v18, v18, v85, v123
	v_mul_f32_e32 v19, v76, v19
	v_mul_f32_e32 v20, v73, v20
	v_mul_f32_e32 v21, v77, v21
	s_waitcnt lgkmcnt(2)
	v_fmac_f32_e32 v18, v22, v74
	v_fmac_f32_e32 v19, v23, v78
	v_fmac_f32_e32 v20, v24, v75
	v_fmac_f32_e32 v21, v25, v79
	s_waitcnt lgkmcnt(1)
	v_fmac_f32_e32 v18, v26, v80
	v_fmac_f32_e32 v19, v27, v88
	v_fmac_f32_e32 v20, v28, v81
	v_fmac_f32_e32 v21, v29, v89
	s_waitcnt lgkmcnt(0)
	v_fmac_f32_e32 v18, v34, v86
	v_fmac_f32_e32 v19, v35, v92
	v_fmac_f32_e32 v20, v36, v87
	v_fmac_f32_e32 v21, v37, v93
	v_add_f32_e32 v18, v18, v19
	v_add_f32_e32 v19, v20, v21
	v_add_f32_e32 v18, v18, v19
	v_mul_f32_e64 v19, |v18|, s79
	v_exp_f32_e32 v19, v19
	v_min_f32_e32 v18, 0, v18
	v_add_f32_e32 v19, 1.0, v19
	v_log_f32_e32 v19, v19
	s_nop 0
	v_fma_f32 v45, v18, s80, -v19
	ds_read_b128 v[18:21], v32 offset:896
	ds_read_b128 v[22:25], v32 offset:912
	ds_read_b128 v[26:29], v32 offset:928
	ds_read_b128 v[34:37], v32 offset:944
	s_waitcnt lgkmcnt(3)
	v_fma_f32 v18, v18, v85, v123
	v_mul_f32_e32 v19, v76, v19
	v_mul_f32_e32 v20, v73, v20
	v_mul_f32_e32 v21, v77, v21
	s_waitcnt lgkmcnt(2)
	v_fmac_f32_e32 v18, v22, v74
	v_fmac_f32_e32 v19, v23, v78
	v_fmac_f32_e32 v20, v24, v75
	v_fmac_f32_e32 v21, v25, v79
	s_waitcnt lgkmcnt(1)
	v_fmac_f32_e32 v18, v26, v80
	v_fmac_f32_e32 v19, v27, v88
	v_fmac_f32_e32 v20, v28, v81
	v_fmac_f32_e32 v21, v29, v89
	s_waitcnt lgkmcnt(0)
	v_fmac_f32_e32 v18, v34, v86
	v_fmac_f32_e32 v19, v35, v92
	v_fmac_f32_e32 v20, v36, v87
	v_fmac_f32_e32 v21, v37, v93
	v_add_f32_e32 v18, v18, v19
	v_add_f32_e32 v19, v20, v21
	v_add_f32_e32 v18, v18, v19
	v_mul_f32_e64 v19, |v18|, s79
	v_exp_f32_e32 v19, v19
	v_min_f32_e32 v18, 0, v18
	v_add_f32_e32 v19, 1.0, v19
	v_log_f32_e32 v19, v19
	s_nop 0
	v_fma_f32 v46, v18, s80, -v19
	ds_read_b128 v[18:21], v32 offset:768
	ds_read_b128 v[22:25], v32 offset:784
	ds_read_b128 v[26:29], v32 offset:800
	ds_read_b128 v[34:37], v32 offset:816
	s_waitcnt lgkmcnt(3)
	v_mul_f32_e32 v31, v73, v20
	v_mov_b32_e32 v20, v19
	v_fma_f32 v30, v18, v85, v123
	v_mul_f32_e32 v18, v76, v20
	v_mul_f32_e32 v19, v77, v21
	s_waitcnt lgkmcnt(2)
	v_mov_b32_e32 v20, v22
	v_mov_b32_e32 v21, v24
	v_mov_b32_e32 v24, v23
	v_fma_f32 v20, v20, v74, v30
	v_fma_f32 v21, v21, v75, v31
	v_fmac_f32_e32 v18, v24, v78
	v_fmac_f32_e32 v19, v25, v79
	s_waitcnt lgkmcnt(1)
	v_mov_b32_e32 v22, v26
	v_mov_b32_e32 v23, v28
	v_mov_b32_e32 v28, v27
	v_fmac_f32_e32 v20, v22, v80
	v_fmac_f32_e32 v21, v23, v81
	v_fmac_f32_e32 v18, v28, v88
	v_fmac_f32_e32 v19, v29, v89
	s_waitcnt lgkmcnt(0)
	v_mov_b32_e32 v22, v34
	v_mov_b32_e32 v23, v36
	v_mov_b32_e32 v36, v35
	v_fmac_f32_e32 v20, v22, v86
	v_fmac_f32_e32 v21, v23, v87
	v_fmac_f32_e32 v18, v36, v92
	v_fmac_f32_e32 v19, v37, v93
	s_nop 0
	v_add_f32_e32 v18, v20, v18
	v_add_f32_e32 v19, v21, v19
	s_nop 0
	v_add_f32_e32 v18, v18, v19
	v_mul_f32_e64 v19, |v18|, s79
	v_exp_f32_e32 v19, v19
	v_min_f32_e32 v18, 0, v18
	v_add_f32_e32 v19, 1.0, v19
	v_log_f32_e32 v19, v19
	s_nop 0
	v_fma_f32 v47, v18, s80, -v19
	ds_read_b128 v[18:21], v32 offset:640
	ds_read_b128 v[22:25], v32 offset:656
	ds_read_b128 v[26:29], v32 offset:672
	ds_read_b128 v[34:37], v32 offset:688
	s_waitcnt lgkmcnt(3)
	v_mul_f32_e32 v31, v73, v20
	v_mov_b32_e32 v20, v19
	v_fma_f32 v30, v18, v85, v123
	v_mul_f32_e32 v18, v76, v20
	v_mul_f32_e32 v19, v77, v21
	s_waitcnt lgkmcnt(2)
	v_mov_b32_e32 v20, v22
	v_mov_b32_e32 v21, v24
	v_mov_b32_e32 v24, v23
	v_fma_f32 v20, v20, v74, v30
	v_fma_f32 v21, v21, v75, v31
	v_fmac_f32_e32 v18, v24, v78
	v_fmac_f32_e32 v19, v25, v79
	s_waitcnt lgkmcnt(1)
	v_mov_b32_e32 v22, v26
	v_mov_b32_e32 v23, v28
	v_mov_b32_e32 v28, v27
	v_fmac_f32_e32 v20, v22, v80
	v_fmac_f32_e32 v21, v23, v81
	v_fmac_f32_e32 v18, v28, v88
	v_fmac_f32_e32 v19, v29, v89
	s_waitcnt lgkmcnt(0)
; template <int DIR>
; DI float prep_gate_loop(const float* r_s, bf16_t* qt, bf16_t* kt, const float (&w)[16], float bias, int kk) {
;     ...
;     for (int blk = 0; blk < 4; ++blk) {
;         float la[16];
; #pragma unroll
;         for (int i = 0; i < 16; ++i) {
;             const int tt = blk * 16 + i; const int t = DIR ? 63 - tt : tt;
;             const f32x4* rr = (const f32x4*)(r_s + t * 32 + DIR * 16);
;             const f32x4 r0 = rr[0], r1 = rr[1], r2 = rr[2], r3 = rr[3];
;             float s0 = __builtin_fmaf(r0[0], w[0], bias), s1 = r0[1] * w[1], s2 = r0[2] * w[2], s3 = r0[3] * w[3];
;             s0 = __builtin_fmaf(r1[0], w[4], s0); s1 = __builtin_fmaf(r1[1], w[5], s1); s2 = __builtin_fmaf(r1[2], w[6], s2); s3 = __builtin_fmaf(r1[3], w[7], s3);
;             s0 = __builtin_fmaf(r2[0], w[8], s0); s1 = __builtin_fmaf(r2[1], w[9], s1); s2 = __builtin_fmaf(r2[2], w[10], s2); s3 = __builtin_fmaf(r2[3], w[11], s3);
;             s0 = __builtin_fmaf(r3[0], w[12], s0); s1 = __builtin_fmaf(r3[1], w[13], s1); s2 = __builtin_fmaf(r3[2], w[14], s2); s3 = __builtin_fmaf(r3[3], w[15], s3);
;             const float pre = (s0 + s1) + (s2 + s3);
;             const float ex = __builtin_amdgcn_exp2f(-fabsf(pre) * LOG2E);
;             la[i] = (fminf(pre, 0.f) * LOG2E - __builtin_amdgcn_logf(1.f + ex)) * 0.0625f;
;         }
	v_mov_b32_e32 v22, v34
	v_mov_b32_e32 v23, v36
	v_mov_b32_e32 v36, v35
	v_fmac_f32_e32 v20, v22, v86
	v_fmac_f32_e32 v21, v23, v87
	v_fmac_f32_e32 v18, v36, v92
	v_fmac_f32_e32 v19, v37, v93
	s_nop 0
	v_add_f32_e32 v18, v20, v18
	v_add_f32_e32 v19, v21, v19
	s_nop 0
	v_add_f32_e32 v18, v18, v19
	v_mul_f32_e64 v19, |v18|, s79
	v_exp_f32_e32 v19, v19
	v_min_f32_e32 v18, 0, v18
	v_add_f32_e32 v19, 1.0, v19
	v_log_f32_e32 v19, v19
	s_nop 0
	v_fma_f32 v48, v18, s80, -v19
	ds_read_b128 v[18:21], v32 offset:512
	ds_read_b128 v[22:25], v32 offset:528
	ds_read_b128 v[26:29], v32 offset:544
	ds_read_b128 v[34:37], v32 offset:560
	s_waitcnt lgkmcnt(3)
	v_mul_f32_e32 v31, v73, v20
	v_mov_b32_e32 v20, v19
	v_fma_f32 v30, v18, v85, v123
	v_mul_f32_e32 v18, v76, v20
	v_mul_f32_e32 v19, v77, v21
	s_waitcnt lgkmcnt(2)
	v_mov_b32_e32 v20, v22
	v_mov_b32_e32 v21, v24
	v_mov_b32_e32 v24, v23
	v_fma_f32 v20, v20, v74, v30
	v_fma_f32 v21, v21, v75, v31
	v_fmac_f32_e32 v18, v24, v78
	v_fmac_f32_e32 v19, v25, v79
	s_waitcnt lgkmcnt(1)
	v_mov_b32_e32 v22, v26
	v_mov_b32_e32 v23, v28
	v_mov_b32_e32 v28, v27
	v_fmac_f32_e32 v20, v22, v80
	v_fmac_f32_e32 v21, v23, v81
	v_fmac_f32_e32 v18, v28, v88
	v_fmac_f32_e32 v19, v29, v89
	s_waitcnt lgkmcnt(0)
	v_mov_b32_e32 v22, v34
	v_mov_b32_e32 v23, v36
	v_mov_b32_e32 v36, v35
	v_fmac_f32_e32 v20, v22, v86
	v_fmac_f32_e32 v21, v23, v87
	v_fmac_f32_e32 v18, v36, v92
	v_fmac_f32_e32 v19, v37, v93
	s_nop 0
	v_add_f32_e32 v18, v20, v18
	v_add_f32_e32 v19, v21, v19
	s_nop 0
	v_add_f32_e32 v18, v18, v19
	v_mul_f32_e64 v19, |v18|, s79
	v_exp_f32_e32 v19, v19
	v_min_f32_e32 v18, 0, v18
	v_add_f32_e32 v19, 1.0, v19
	v_log_f32_e32 v19, v19
	s_nop 0
	v_fma_f32 v49, v18, s80, -v19
	ds_read_b128 v[18:21], v32 offset:384
	ds_read_b128 v[22:25], v32 offset:400
	ds_read_b128 v[26:29], v32 offset:416
	ds_read_b128 v[34:37], v32 offset:432
	s_waitcnt lgkmcnt(3)
	v_mul_f32_e32 v31, v73, v20
	v_mov_b32_e32 v20, v19
	v_fma_f32 v30, v18, v85, v123
	v_mul_f32_e32 v18, v76, v20
	v_mul_f32_e32 v19, v77, v21
	s_waitcnt lgkmcnt(2)
	v_mov_b32_e32 v20, v22
	v_mov_b32_e32 v21, v24
	v_mov_b32_e32 v24, v23
	v_fma_f32 v20, v20, v74, v30
	v_fma_f32 v21, v21, v75, v31
	v_fmac_f32_e32 v18, v24, v78
	v_fmac_f32_e32 v19, v25, v79
	s_waitcnt lgkmcnt(1)
	v_mov_b32_e32 v22, v26
	v_mov_b32_e32 v23, v28
	v_mov_b32_e32 v28, v27
	v_fmac_f32_e32 v20, v22, v80
	v_fmac_f32_e32 v21, v23, v81
	v_fmac_f32_e32 v18, v28, v88
	v_fmac_f32_e32 v19, v29, v89
	s_waitcnt lgkmcnt(0)
	v_mov_b32_e32 v22, v34
	v_mov_b32_e32 v23, v36
	v_mov_b32_e32 v36, v35
	v_fmac_f32_e32 v20, v22, v86
	v_fmac_f32_e32 v21, v23, v87
	v_fmac_f32_e32 v18, v36, v92
	v_fmac_f32_e32 v19, v37, v93
	s_nop 0
	v_add_f32_e32 v18, v20, v18
	v_add_f32_e32 v19, v21, v19
	s_nop 0
	v_add_f32_e32 v18, v18, v19
	v_mul_f32_e64 v19, |v18|, s79
	v_exp_f32_e32 v19, v19
	v_min_f32_e32 v18, 0, v18
	v_add_f32_e32 v19, 1.0, v19
	v_log_f32_e32 v19, v19
	s_nop 0
	v_fma_f32 v50, v18, s80, -v19
	ds_read_b128 v[18:21], v32 offset:256
	ds_read_b128 v[22:25], v32 offset:272
	ds_read_b128 v[26:29], v32 offset:288
	ds_read_b128 v[34:37], v32 offset:304
	s_waitcnt lgkmcnt(3)
	v_mul_f32_e32 v31, v73, v20
	v_mov_b32_e32 v20, v19
	v_fma_f32 v30, v18, v85, v123
	v_mul_f32_e32 v18, v76, v20
	v_mul_f32_e32 v19, v77, v21
	s_waitcnt lgkmcnt(2)
	v_mov_b32_e32 v20, v22
	v_mov_b32_e32 v21, v24
	v_mov_b32_e32 v24, v23
	v_fma_f32 v20, v20, v74, v30
	v_fma_f32 v21, v21, v75, v31
	v_fmac_f32_e32 v18, v24, v78
	v_fmac_f32_e32 v19, v25, v79
	s_waitcnt lgkmcnt(1)
	v_mov_b32_e32 v22, v26
	v_mov_b32_e32 v23, v28
	v_mov_b32_e32 v28, v27
	v_fmac_f32_e32 v20, v22, v80
	v_fmac_f32_e32 v21, v23, v81
	v_fmac_f32_e32 v18, v28, v88
	v_fmac_f32_e32 v19, v29, v89
	s_waitcnt lgkmcnt(0)
	v_mov_b32_e32 v22, v34
	v_mov_b32_e32 v23, v36
	v_mov_b32_e32 v36, v35
	v_fmac_f32_e32 v20, v22, v86
	v_fmac_f32_e32 v21, v23, v87
	v_fmac_f32_e32 v18, v36, v92
	v_fmac_f32_e32 v19, v37, v93
	s_nop 0
	v_add_f32_e32 v18, v20, v18
	v_add_f32_e32 v19, v21, v19
	s_nop 0
	v_add_f32_e32 v18, v18, v19
	v_mul_f32_e64 v19, |v18|, s79
	v_exp_f32_e32 v19, v19
	v_min_f32_e32 v18, 0, v18
	v_add_f32_e32 v19, 1.0, v19
	v_log_f32_e32 v19, v19
	s_nop 0
	v_fma_f32 v51, v18, s80, -v19
	ds_read_b128 v[18:21], v32 offset:128
	ds_read_b128 v[22:25], v32 offset:144
	ds_read_b128 v[26:29], v32 offset:160
	ds_read_b128 v[34:37], v32 offset:176
	s_waitcnt lgkmcnt(3)
	v_mul_f32_e32 v31, v73, v20
	v_mov_b32_e32 v20, v19
	v_fma_f32 v30, v18, v85, v123
	v_mul_f32_e32 v18, v76, v20
	v_mul_f32_e32 v19, v77, v21
	s_waitcnt lgkmcnt(2)
	v_mov_b32_e32 v20, v22
	v_mov_b32_e32 v21, v24
	v_mov_b32_e32 v24, v23
	v_fma_f32 v20, v20, v74, v30
	v_fma_f32 v21, v21, v75, v31
	v_fmac_f32_e32 v18, v24, v78
	v_fmac_f32_e32 v19, v25, v79
	s_waitcnt lgkmcnt(1)
	v_mov_b32_e32 v22, v26
	v_mov_b32_e32 v23, v28
	v_mov_b32_e32 v28, v27
	v_fmac_f32_e32 v20, v22, v80
	v_fmac_f32_e32 v21, v23, v81
	v_fmac_f32_e32 v18, v28, v88
	v_fmac_f32_e32 v19, v29, v89
	s_waitcnt lgkmcnt(0)
	v_mov_b32_e32 v22, v34
	v_mov_b32_e32 v23, v36
	v_mov_b32_e32 v36, v35
	v_fmac_f32_e32 v20, v22, v86
	v_fmac_f32_e32 v21, v23, v87
	v_fmac_f32_e32 v18, v36, v92
	v_fmac_f32_e32 v19, v37, v93
	s_nop 0
	v_add_f32_e32 v18, v20, v18
	v_add_f32_e32 v19, v21, v19
	s_nop 0
	v_add_f32_e32 v18, v18, v19
	v_mul_f32_e64 v19, |v18|, s79
	v_exp_f32_e32 v19, v19
	v_min_f32_e32 v18, 0, v18
	v_add_f32_e32 v19, 1.0, v19
	v_log_f32_e32 v19, v19
	s_nop 0
	v_fma_f32 v52, v18, s80, -v19
	ds_read_b128 v[18:21], v32
	ds_read_b128 v[22:25], v32 offset:16
	ds_read_b128 v[26:29], v32 offset:32
	ds_read_b128 v[34:37], v32 offset:48
	v_fmamk_f32 v32, v39, 0x3d800000, v33
	s_waitcnt lgkmcnt(3)
; DI float bf2f(bf16_t b) { return __uint_as_float(((unsigned)b) << 16); }
; DI bf16_t f2bf(float f) { return (bf16_t)(pk2(f, 0.f) & 0xffffu); }
; template <int DIR>
; DI float prep_gate_loop(const float* r_s, bf16_t* qt, bf16_t* kt, const float (&w)[16], float bias, int kk) {
;     ...
;             float s0 = __builtin_fmaf(r0[0], w[0], bias), s1 = r0[1] * w[1], s2 = r0[2] * w[2], s3 = r0[3] * w[3];
;             s0 = __builtin_fmaf(r1[0], w[4], s0); s1 = __builtin_fmaf(r1[1], w[5], s1); s2 = __builtin_fmaf(r1[2], w[6], s2); s3 = __builtin_fmaf(r1[3], w[7], s3);
;             s0 = __builtin_fmaf(r2[0], w[8], s0); s1 = __builtin_fmaf(r2[1], w[9], s1); s2 = __builtin_fmaf(r2[2], w[10], s2); s3 = __builtin_fmaf(r2[3], w[11], s3);
;             s0 = __builtin_fmaf(r3[0], w[12], s0); s1 = __builtin_fmaf(r3[1], w[13], s1); s2 = __builtin_fmaf(r3[2], w[14], s2); s3 = __builtin_fmaf(r3[3], w[15], s3);
;             const float pre = (s0 + s1) + (s2 + s3);
;             const float ex = __builtin_amdgcn_exp2f(-fabsf(pre) * LOG2E);
;             la[i] = (fminf(pre, 0.f) * LOG2E - __builtin_amdgcn_logf(1.f + ex)) * 0.0625f;
;         }
; #pragma unroll
;         for (int i = 0; i < 16; ++i) { g += la[i]; la[i] = g; }
; #pragma unroll
;         for (int i = 0; i < 16; ++i) {
;             const int tt = blk * 16 + i; const int t = DIR ? 63 - tt : tt;
;             const float e = __builtin_amdgcn_exp2f(la[i]);
;             bf16_t* qp = qt + (DIR * 64 + t) * 264 + kk; bf16_t* kp = kt + (DIR * 64 + t) * 264 + kk;
;             const float qv = bf2f(*qp), kv = bf2f(*kp);
;             *qp = f2bf(qv * 0.0625f * e);
;             *kp = f2bf(kv * __builtin_amdgcn_rcpf(e));
	v_mul_f32_e32 v31, v73, v20
	v_mov_b32_e32 v20, v19
	v_fma_f32 v30, v18, v85, v123
	v_mul_f32_e32 v18, v76, v20
	v_mul_f32_e32 v19, v77, v21
	s_waitcnt lgkmcnt(2)
	v_mov_b32_e32 v20, v22
	v_mov_b32_e32 v21, v24
	v_fma_f32 v20, v20, v74, v30
	v_fma_f32 v21, v21, v75, v31
	v_mov_b32_e32 v24, v23
	s_waitcnt lgkmcnt(1)
	v_mov_b32_e32 v22, v26
	v_mov_b32_e32 v23, v28
	v_fmac_f32_e32 v18, v24, v78
	v_fmac_f32_e32 v19, v25, v79
	v_fmac_f32_e32 v20, v22, v80
	v_fmac_f32_e32 v21, v23, v81
	v_mov_b32_e32 v28, v27
	s_waitcnt lgkmcnt(0)
	v_mov_b32_e32 v22, v34
	v_add_u32_e32 v34, s52, v120
	v_fmac_f32_e32 v18, v28, v88
	v_fmac_f32_e32 v19, v29, v89
	v_mov_b32_e32 v23, v36
	v_mov_b32_e32 v36, v35
	v_add_u32_e32 v35, 0x125f0, v34
	v_fmac_f32_e32 v18, v36, v92
	v_fmac_f32_e32 v19, v37, v93
	ds_read_u16 v37, v35
	v_exp_f32_e32 v33, v33
	v_add_u32_e32 v36, 0x22df0, v34
	ds_read_u16 v38, v36
	v_fmamk_f32 v31, v40, 0x3d800000, v32
	s_waitcnt lgkmcnt(1)
	v_lshlrev_b32_e32 v37, 16, v37
	v_mul_f32_e32 v37, 0x3d800000, v37
	v_mul_f32_e32 v37, v33, v37
	v_rcp_f32_e32 v33, v33
	s_waitcnt lgkmcnt(0)
	v_lshlrev_b32_e32 v38, 16, v38
	v_cvt_pk_bf16_f32 v37, v37, s0
	v_exp_f32_e32 v32, v32
	v_mul_f32_e32 v33, v33, v38
	v_cvt_pk_bf16_f32 v33, v33, s0
	ds_write_b16 v36, v33
	v_add_u32_e32 v33, 0x123e0, v34
	ds_read_u16 v36, v33
	ds_write_b16 v35, v37
	v_add_u32_e32 v35, 0x22be0, v34
	ds_read_u16 v37, v35
	v_fmamk_f32 v30, v41, 0x3d800000, v31
	s_waitcnt lgkmcnt(2)
	v_lshlrev_b32_e32 v36, 16, v36
	v_mul_f32_e32 v36, 0x3d800000, v36
	v_mul_f32_e32 v36, v32, v36
	v_rcp_f32_e32 v32, v32
	s_waitcnt lgkmcnt(0)
	v_lshlrev_b32_e32 v37, 16, v37
	v_cvt_pk_bf16_f32 v36, v36, s0
	v_exp_f32_e32 v31, v31
	v_mul_f32_e32 v32, v32, v37
	v_cvt_pk_bf16_f32 v32, v32, s0
	ds_write_b16 v35, v32
	v_add_u32_e32 v32, 0x121d0, v34
	ds_read_u16 v35, v32
	ds_write_b16 v33, v36
	v_add_u32_e32 v33, 0x229d0, v34
	ds_read_u16 v36, v33
	v_fmamk_f32 v29, v42, 0x3d800000, v30
	s_waitcnt lgkmcnt(2)
	v_lshlrev_b32_e32 v35, 16, v35
	v_mul_f32_e32 v35, 0x3d800000, v35
	v_mul_f32_e32 v35, v31, v35
	v_rcp_f32_e32 v31, v31
	s_waitcnt lgkmcnt(0)
	v_lshlrev_b32_e32 v36, 16, v36
	v_cvt_pk_bf16_f32 v35, v35, s0
	v_exp_f32_e32 v30, v30
	v_mul_f32_e32 v31, v31, v36
	v_cvt_pk_bf16_f32 v31, v31, s0
	ds_write_b16 v33, v31
	v_add_u32_e32 v31, 0x11fc0, v34
	ds_read_u16 v33, v31
	ds_write_b16 v32, v35
	v_add_u32_e32 v32, 0x227c0, v34
	ds_read_u16 v35, v32
	v_fmamk_f32 v28, v43, 0x3d800000, v29
	s_waitcnt lgkmcnt(2)
	v_lshlrev_b32_e32 v33, 16, v33
	v_mul_f32_e32 v33, 0x3d800000, v33
	v_mul_f32_e32 v33, v30, v33
	v_rcp_f32_e32 v30, v30
	s_waitcnt lgkmcnt(0)
	v_lshlrev_b32_e32 v35, 16, v35
	v_cvt_pk_bf16_f32 v33, v33, s0
	v_exp_f32_e32 v29, v29
	v_mul_f32_e32 v30, v30, v35
	v_cvt_pk_bf16_f32 v30, v30, s0
	ds_write_b16 v32, v30
	v_add_u32_e32 v30, 0x11db0, v34
	ds_read_u16 v32, v30
	ds_write_b16 v31, v33
	v_add_u32_e32 v31, 0x225b0, v34
	ds_read_u16 v33, v31
	v_fmamk_f32 v27, v44, 0x3d800000, v28
	s_waitcnt lgkmcnt(2)
	v_lshlrev_b32_e32 v32, 16, v32
	v_mul_f32_e32 v32, 0x3d800000, v32
	v_mul_f32_e32 v32, v29, v32
	v_rcp_f32_e32 v29, v29
	s_waitcnt lgkmcnt(0)
	v_lshlrev_b32_e32 v33, 16, v33
	v_cvt_pk_bf16_f32 v32, v32, s0
	v_exp_f32_e32 v28, v28
	v_mul_f32_e32 v29, v29, v33
	v_cvt_pk_bf16_f32 v29, v29, s0
	ds_write_b16 v31, v29
	v_add_u32_e32 v29, 0x11ba0, v34
	ds_read_u16 v31, v29
	ds_write_b16 v30, v32
	v_add_u32_e32 v30, 0x223a0, v34
	ds_read_u16 v32, v30
	v_fmamk_f32 v26, v45, 0x3d800000, v27
	s_waitcnt lgkmcnt(2)
	v_lshlrev_b32_e32 v31, 16, v31
	v_mul_f32_e32 v31, 0x3d800000, v31
	v_mul_f32_e32 v31, v28, v31
	v_rcp_f32_e32 v28, v28
	s_waitcnt lgkmcnt(0)
	v_lshlrev_b32_e32 v32, 16, v32
	v_cvt_pk_bf16_f32 v31, v31, s0
	v_exp_f32_e32 v27, v27
	v_mul_f32_e32 v28, v28, v32
	v_cvt_pk_bf16_f32 v28, v28, s0
	ds_write_b16 v30, v28
	v_add_u32_e32 v28, 0x11990, v34
	ds_read_u16 v30, v28
	ds_write_b16 v29, v31
	v_add_u32_e32 v29, 0x22190, v34
	ds_read_u16 v31, v29
	v_fmamk_f32 v25, v46, 0x3d800000, v26
	s_waitcnt lgkmcnt(2)
	v_lshlrev_b32_e32 v30, 16, v30
	v_mul_f32_e32 v30, 0x3d800000, v30
	v_mul_f32_e32 v30, v27, v30
	v_rcp_f32_e32 v27, v27
	s_waitcnt lgkmcnt(0)
	v_lshlrev_b32_e32 v31, 16, v31
	v_cvt_pk_bf16_f32 v30, v30, s0
	v_exp_f32_e32 v26, v26
	v_mul_f32_e32 v27, v27, v31
	v_cvt_pk_bf16_f32 v27, v27, s0
	ds_write_b16 v29, v27
	v_add_u32_e32 v27, 0x11780, v34
	ds_read_u16 v29, v27
	ds_write_b16 v28, v30
	v_add_u32_e32 v28, 0x21f80, v34
	ds_read_u16 v30, v28
	v_fmamk_f32 v24, v47, 0x3d800000, v25
	s_waitcnt lgkmcnt(2)
	v_lshlrev_b32_e32 v29, 16, v29
	v_mul_f32_e32 v29, 0x3d800000, v29
	v_mul_f32_e32 v29, v26, v29
	v_rcp_f32_e32 v26, v26
	s_waitcnt lgkmcnt(0)
; DI float bf2f(bf16_t b) { return __uint_as_float(((unsigned)b) << 16); }
; DI bf16_t f2bf(float f) { return (bf16_t)(pk2(f, 0.f) & 0xffffu); }
; template <int DIR>
; DI float prep_gate_loop(const float* r_s, bf16_t* qt, bf16_t* kt, const float (&w)[16], float bias, int kk) {
;     ...
;         for (int i = 0; i < 16; ++i) {
;             const int tt = blk * 16 + i; const int t = DIR ? 63 - tt : tt;
;             const f32x4* rr = (const f32x4*)(r_s + t * 32 + DIR * 16);
;             const f32x4 r0 = rr[0], r1 = rr[1], r2 = rr[2], r3 = rr[3];
;             float s0 = __builtin_fmaf(r0[0], w[0], bias), s1 = r0[1] * w[1], s2 = r0[2] * w[2], s3 = r0[3] * w[3];
;             s0 = __builtin_fmaf(r1[0], w[4], s0); s1 = __builtin_fmaf(r1[1], w[5], s1); s2 = __builtin_fmaf(r1[2], w[6], s2); s3 = __builtin_fmaf(r1[3], w[7], s3);
;             s0 = __builtin_fmaf(r2[0], w[8], s0); s1 = __builtin_fmaf(r2[1], w[9], s1); s2 = __builtin_fmaf(r2[2], w[10], s2); s3 = __builtin_fmaf(r2[3], w[11], s3);
;             s0 = __builtin_fmaf(r3[0], w[12], s0); s1 = __builtin_fmaf(r3[1], w[13], s1); s2 = __builtin_fmaf(r3[2], w[14], s2); s3 = __builtin_fmaf(r3[3], w[15], s3);
;             const float pre = (s0 + s1) + (s2 + s3);
;             const float ex = __builtin_amdgcn_exp2f(-fabsf(pre) * LOG2E);
;             la[i] = (fminf(pre, 0.f) * LOG2E - __builtin_amdgcn_logf(1.f + ex)) * 0.0625f;
;         }
; #pragma unroll
;         for (int i = 0; i < 16; ++i) { g += la[i]; la[i] = g; }
; #pragma unroll
;         for (int i = 0; i < 16; ++i) {
;             const int tt = blk * 16 + i; const int t = DIR ? 63 - tt : tt;
;             const float e = __builtin_amdgcn_exp2f(la[i]);
;             bf16_t* qp = qt + (DIR * 64 + t) * 264 + kk; bf16_t* kp = kt + (DIR * 64 + t) * 264 + kk;
;             const float qv = bf2f(*qp), kv = bf2f(*kp);
;             *qp = f2bf(qv * 0.0625f * e);
;             *kp = f2bf(kv * __builtin_amdgcn_rcpf(e));
;         }
	v_lshlrev_b32_e32 v30, 16, v30
	v_cvt_pk_bf16_f32 v29, v29, s0
	v_exp_f32_e32 v25, v25
	v_mul_f32_e32 v26, v26, v30
	v_cvt_pk_bf16_f32 v26, v26, s0
	ds_write_b16 v28, v26
	v_add_u32_e32 v26, 0x11570, v34
	ds_read_u16 v28, v26
	ds_write_b16 v27, v29
	v_add_u32_e32 v27, 0x21d70, v34
	ds_read_u16 v29, v27
	v_fmac_f32_e32 v20, v22, v86
	v_fmac_f32_e32 v21, v23, v87
	s_waitcnt lgkmcnt(2)
	v_lshlrev_b32_e32 v28, 16, v28
	v_mul_f32_e32 v28, 0x3d800000, v28
	v_mul_f32_e32 v28, v25, v28
	v_rcp_f32_e32 v25, v25
	s_waitcnt lgkmcnt(0)
	v_lshlrev_b32_e32 v29, 16, v29
	v_fmamk_f32 v23, v48, 0x3d800000, v24
	v_cvt_pk_bf16_f32 v28, v28, s0
	v_mul_f32_e32 v25, v25, v29
	v_cvt_pk_bf16_f32 v25, v25, s0
	ds_write_b16 v27, v25
	v_add_u32_e32 v25, 0x11360, v34
	ds_read_u16 v27, v25
	v_exp_f32_e32 v24, v24
	ds_write_b16 v26, v28
	v_add_u32_e32 v26, 0x21b60, v34
	ds_read_u16 v28, v26
	s_waitcnt lgkmcnt(2)
	v_lshlrev_b32_e32 v27, 16, v27
	v_mul_f32_e32 v27, 0x3d800000, v27
	v_mul_f32_e32 v27, v24, v27
	v_rcp_f32_e32 v24, v24
	s_waitcnt lgkmcnt(0)
	v_lshlrev_b32_e32 v28, 16, v28
	v_fmamk_f32 v22, v49, 0x3d800000, v23
	v_cvt_pk_bf16_f32 v27, v27, s0
	v_mul_f32_e32 v24, v24, v28
	v_cvt_pk_bf16_f32 v24, v24, s0
	ds_write_b16 v26, v24
	v_add_u32_e32 v24, 0x11150, v34
	ds_read_u16 v26, v24
	v_exp_f32_e32 v23, v23
	ds_write_b16 v25, v27
	v_add_u32_e32 v25, 0x21950, v34
	ds_read_u16 v27, v25
	s_waitcnt lgkmcnt(2)
	v_lshlrev_b32_e32 v26, 16, v26
	v_mul_f32_e32 v26, 0x3d800000, v26
	v_mul_f32_e32 v26, v23, v26
	v_rcp_f32_e32 v23, v23
	s_waitcnt lgkmcnt(0)
	v_lshlrev_b32_e32 v27, 16, v27
	v_add_f32_e32 v18, v20, v18
	v_add_f32_e32 v19, v21, v19
	v_fmamk_f32 v21, v50, 0x3d800000, v22
	v_mul_f32_e32 v23, v23, v27
	v_cvt_pk_bf16_f32 v23, v23, s0
	ds_write_b16 v25, v23
	v_add_u32_e32 v23, 0x10f40, v34
	ds_read_u16 v25, v23
	v_cvt_pk_bf16_f32 v26, v26, s0
	v_exp_f32_e32 v22, v22
	ds_write_b16 v24, v26
	v_add_u32_e32 v24, 0x21740, v34
	ds_read_u16 v26, v24
	s_waitcnt lgkmcnt(2)
	v_lshlrev_b32_e32 v25, 16, v25
	v_mul_f32_e32 v25, 0x3d800000, v25
	v_mul_f32_e32 v25, v22, v25
	v_rcp_f32_e32 v22, v22
	s_waitcnt lgkmcnt(0)
	v_lshlrev_b32_e32 v26, 16, v26
	v_fmamk_f32 v20, v51, 0x3d800000, v21
	v_cvt_pk_bf16_f32 v25, v25, s0
	v_mul_f32_e32 v22, v22, v26
	v_cvt_pk_bf16_f32 v22, v22, s0
	ds_write_b16 v24, v22
	v_add_u32_e32 v22, 0x10d30, v34
	ds_read_u16 v24, v22
	v_exp_f32_e32 v21, v21
	ds_write_b16 v23, v25
	v_add_u32_e32 v23, 0x21530, v34
	ds_read_u16 v25, v23
	s_waitcnt lgkmcnt(2)
	v_lshlrev_b32_e32 v24, 16, v24
	v_add_f32_e32 v18, v18, v19
	v_mul_f32_e32 v24, 0x3d800000, v24
	v_mul_f32_e64 v19, |v18|, s79
	v_mul_f32_e32 v24, v21, v24
	v_rcp_f32_e32 v21, v21
	v_exp_f32_e32 v19, v19
	s_waitcnt lgkmcnt(0)
	v_lshlrev_b32_e32 v25, 16, v25
	v_min_f32_e32 v18, 0, v18
	v_mul_f32_e32 v21, v21, v25
	v_add_f32_e32 v19, 1.0, v19
	v_cvt_pk_bf16_f32 v21, v21, s0
	v_log_f32_e32 v19, v19
	ds_write_b16 v23, v21
	v_add_u32_e32 v21, 0x10b20, v34
	ds_read_u16 v23, v21
	v_fma_f32 v18, v18, s80, -v19
	v_fmamk_f32 v19, v52, 0x3d800000, v20
	v_cvt_pk_bf16_f32 v24, v24, s0
	v_exp_f32_e32 v20, v20
	ds_write_b16 v22, v24
	v_add_u32_e32 v22, 0x21320, v34
	ds_read_u16 v24, v22
	s_waitcnt lgkmcnt(2)
	v_lshlrev_b32_e32 v23, 16, v23
	v_mul_f32_e32 v23, 0x3d800000, v23
	v_mul_f32_e32 v23, v20, v23
	v_rcp_f32_e32 v20, v20
	s_waitcnt lgkmcnt(0)
	v_lshlrev_b32_e32 v24, 16, v24
	v_fmamk_f32 v18, v18, 0x3d800000, v19
	v_cvt_pk_bf16_f32 v23, v23, s0
	v_mul_f32_e32 v20, v20, v24
	v_cvt_pk_bf16_f32 v20, v20, s0
	ds_write_b16 v22, v20
	v_add_u32_e32 v20, 0x10910, v34
	ds_read_u16 v22, v20
	v_exp_f32_e32 v19, v19
	ds_write_b16 v21, v23
	v_add_u32_e32 v21, 0x21110, v34
	ds_read_u16 v23, v21
	s_waitcnt lgkmcnt(2)
	v_lshlrev_b32_e32 v22, 16, v22
	v_mul_f32_e32 v22, 0x3d800000, v22
	v_mul_f32_e32 v22, v19, v22
	v_rcp_f32_e32 v19, v19
	s_waitcnt lgkmcnt(0)
	v_lshlrev_b32_e32 v23, 16, v23
	v_cvt_pk_bf16_f32 v22, v22, s0
	v_exp_f32_e32 v112, v18
	v_mul_f32_e32 v19, v19, v23
	v_cvt_pk_bf16_f32 v19, v19, s0
	ds_write_b16 v21, v19
	v_add_u32_e32 v19, 0x10700, v34
	ds_read_u16 v21, v19
	ds_write_b16 v20, v22
	v_add_u32_e32 v20, 0x20f00, v34
	ds_read_u16 v22, v20
	s_addk_i32 s52, 0xdf00
	s_waitcnt lgkmcnt(2)
	v_lshlrev_b32_e32 v21, 16, v21
	v_mul_f32_e32 v21, 0x3d800000, v21
	v_mul_f32_e32 v21, v112, v21
	v_cvt_pk_bf16_f32 v21, v21, s0
	ds_write_b16 v19, v21
	v_rcp_f32_e32 v19, v112
	s_waitcnt lgkmcnt(1)
	v_lshlrev_b32_e32 v22, 16, v22
	s_cmp_lg_u32 s52, 0xffff7c00
	v_mov_b32_e32 v33, v18
	v_mul_f32_e32 v19, v19, v22
	v_cvt_pk_bf16_f32 v19, v19, s0
	ds_write_b16 v20, v19
	s_cbranch_scc1 .LBB0_1535

; template <int DIR>
; DI float prep_gate_loop(const float* r_s, bf16_t* qt, bf16_t* kt, const float (&w)[16], float bias, int kk) {
;     ...
;         for (int i = 0; i < 16; ++i) {
;             const int tt = blk * 16 + i; const int t = DIR ? 63 - tt : tt;
;             const f32x4* rr = (const f32x4*)(r_s + t * 32 + DIR * 16);
;             const f32x4 r0 = rr[0], r1 = rr[1], r2 = rr[2], r3 = rr[3];
;             float s0 = __builtin_fmaf(r0[0], w[0], bias), s1 = r0[1] * w[1], s2 = r0[2] * w[2], s3 = r0[3] * w[3];
;             s0 = __builtin_fmaf(r1[0], w[4], s0); s1 = __builtin_fmaf(r1[1], w[5], s1); s2 = __builtin_fmaf(r1[2], w[6], s2); s3 = __builtin_fmaf(r1[3], w[7], s3);
;             s0 = __builtin_fmaf(r2[0], w[8], s0); s1 = __builtin_fmaf(r2[1], w[9], s1); s2 = __builtin_fmaf(r2[2], w[10], s2); s3 = __builtin_fmaf(r2[3], w[11], s3);
;             s0 = __builtin_fmaf(r3[0], w[12], s0); s1 = __builtin_fmaf(r3[1], w[13], s1); s2 = __builtin_fmaf(r3[2], w[14], s2); s3 = __builtin_fmaf(r3[3], w[15], s3);
;             const float pre = (s0 + s1) + (s2 + s3);
;             const float ex = __builtin_amdgcn_exp2f(-fabsf(pre) * LOG2E);
;             la[i] = (fminf(pre, 0.f) * LOG2E - __builtin_amdgcn_logf(1.f + ex)) * 0.0625f;
;         }
.LBB0_1539:
	v_mov_b32_e32 v32, s55
	ds_read_b128 v[18:21], v32
	ds_read_b128 v[22:25], v32 offset:16
	ds_read_b128 v[26:29], v32 offset:32
	ds_read_b128 v[34:37], v32 offset:48
	s_addk_i32 s55, 0x800
	s_waitcnt lgkmcnt(3)
	v_fma_f32 v18, v18, v85, v123
	v_mul_f32_e32 v19, v76, v19
	v_mul_f32_e32 v20, v73, v20
	v_mul_f32_e32 v21, v77, v21
	s_waitcnt lgkmcnt(2)
	v_fmac_f32_e32 v18, v22, v74
	v_fmac_f32_e32 v19, v23, v78
	v_fmac_f32_e32 v20, v24, v75
	v_fmac_f32_e32 v21, v25, v79
	s_waitcnt lgkmcnt(1)
	v_fmac_f32_e32 v18, v26, v80
	v_fmac_f32_e32 v19, v27, v88
	v_fmac_f32_e32 v20, v28, v81
	v_fmac_f32_e32 v21, v29, v89
	s_waitcnt lgkmcnt(0)
	v_fmac_f32_e32 v18, v34, v86
	v_fmac_f32_e32 v19, v35, v92
	v_fmac_f32_e32 v20, v36, v87
	v_fmac_f32_e32 v21, v37, v93
	v_add_f32_e32 v18, v18, v19
	v_add_f32_e32 v19, v20, v21
	v_add_f32_e32 v18, v18, v19
	v_mul_f32_e64 v19, |v18|, s79
	v_exp_f32_e32 v19, v19
	v_min_f32_e32 v18, 0, v18
	v_add_f32_e32 v19, 1.0, v19
	v_log_f32_e32 v19, v19
	s_nop 0
	v_fma_f32 v38, v18, s80, -v19
	ds_read_b128 v[18:21], v32 offset:128
	ds_read_b128 v[22:25], v32 offset:144
	ds_read_b128 v[26:29], v32 offset:160
	ds_read_b128 v[34:37], v32 offset:176
	v_fmac_f32_e32 v33, 0x3d800000, v38
	s_waitcnt lgkmcnt(3)
	v_fma_f32 v18, v18, v85, v123
	v_mul_f32_e32 v19, v76, v19
	v_mul_f32_e32 v20, v73, v20
	v_mul_f32_e32 v21, v77, v21
	s_waitcnt lgkmcnt(2)
	v_fmac_f32_e32 v18, v22, v74
	v_fmac_f32_e32 v19, v23, v78
	v_fmac_f32_e32 v20, v24, v75
	v_fmac_f32_e32 v21, v25, v79
	s_waitcnt lgkmcnt(1)
	v_fmac_f32_e32 v18, v26, v80
	v_fmac_f32_e32 v19, v27, v88
	v_fmac_f32_e32 v20, v28, v81
	v_fmac_f32_e32 v21, v29, v89
	s_waitcnt lgkmcnt(0)
	v_fmac_f32_e32 v18, v34, v86
	v_fmac_f32_e32 v19, v35, v92
	v_fmac_f32_e32 v20, v36, v87
	v_fmac_f32_e32 v21, v37, v93
	v_add_f32_e32 v18, v18, v19
	v_add_f32_e32 v19, v20, v21
	v_add_f32_e32 v18, v18, v19
	v_mul_f32_e64 v19, |v18|, s79
	v_exp_f32_e32 v19, v19
	v_min_f32_e32 v18, 0, v18
	v_add_f32_e32 v19, 1.0, v19
	v_log_f32_e32 v19, v19
	s_nop 0
	v_fma_f32 v39, v18, s80, -v19
	ds_read_b128 v[18:21], v32 offset:256
	ds_read_b128 v[22:25], v32 offset:272
	ds_read_b128 v[26:29], v32 offset:288
	ds_read_b128 v[34:37], v32 offset:304
	s_waitcnt lgkmcnt(3)
	v_fma_f32 v18, v18, v85, v123
	v_mul_f32_e32 v19, v76, v19
	v_mul_f32_e32 v20, v73, v20
	v_mul_f32_e32 v21, v77, v21
	s_waitcnt lgkmcnt(2)
	v_fmac_f32_e32 v18, v22, v74
	v_fmac_f32_e32 v19, v23, v78
	v_fmac_f32_e32 v20, v24, v75
	v_fmac_f32_e32 v21, v25, v79
	s_waitcnt lgkmcnt(1)
	v_fmac_f32_e32 v18, v26, v80
	v_fmac_f32_e32 v19, v27, v88
	v_fmac_f32_e32 v20, v28, v81
	v_fmac_f32_e32 v21, v29, v89
	s_waitcnt lgkmcnt(0)
	v_fmac_f32_e32 v18, v34, v86
	v_fmac_f32_e32 v19, v35, v92
	v_fmac_f32_e32 v20, v36, v87
	v_fmac_f32_e32 v21, v37, v93
	v_add_f32_e32 v18, v18, v19
	v_add_f32_e32 v19, v20, v21
	v_add_f32_e32 v18, v18, v19
	v_mul_f32_e64 v19, |v18|, s79
	v_exp_f32_e32 v19, v19
	v_min_f32_e32 v18, 0, v18
	v_add_f32_e32 v19, 1.0, v19
	v_log_f32_e32 v19, v19
	s_nop 0
	v_fma_f32 v40, v18, s80, -v19
	ds_read_b128 v[18:21], v32 offset:384
	ds_read_b128 v[22:25], v32 offset:400
	ds_read_b128 v[26:29], v32 offset:416
	ds_read_b128 v[34:37], v32 offset:432
	s_waitcnt lgkmcnt(3)
	v_fma_f32 v18, v18, v85, v123
	v_mul_f32_e32 v19, v76, v19
	v_mul_f32_e32 v20, v73, v20
	v_mul_f32_e32 v21, v77, v21
	s_waitcnt lgkmcnt(2)
	v_fmac_f32_e32 v18, v22, v74
	v_fmac_f32_e32 v19, v23, v78
	v_fmac_f32_e32 v20, v24, v75
	v_fmac_f32_e32 v21, v25, v79
	s_waitcnt lgkmcnt(1)
	v_fmac_f32_e32 v18, v26, v80
	v_fmac_f32_e32 v19, v27, v88
	v_fmac_f32_e32 v20, v28, v81
	v_fmac_f32_e32 v21, v29, v89
	s_waitcnt lgkmcnt(0)
	v_fmac_f32_e32 v18, v34, v86
	v_fmac_f32_e32 v19, v35, v92
	v_fmac_f32_e32 v20, v36, v87
	v_fmac_f32_e32 v21, v37, v93
	v_add_f32_e32 v18, v18, v19
	v_add_f32_e32 v19, v20, v21
	v_add_f32_e32 v18, v18, v19
	v_mul_f32_e64 v19, |v18|, s79
	v_exp_f32_e32 v19, v19
	v_min_f32_e32 v18, 0, v18
	v_add_f32_e32 v19, 1.0, v19
	v_log_f32_e32 v19, v19
	s_nop 0
	v_fma_f32 v41, v18, s80, -v19
	ds_read_b128 v[18:21], v32 offset:512
	ds_read_b128 v[22:25], v32 offset:528
	ds_read_b128 v[26:29], v32 offset:544
	ds_read_b128 v[34:37], v32 offset:560
	s_waitcnt lgkmcnt(3)
	v_fma_f32 v18, v18, v85, v123
	v_mul_f32_e32 v19, v76, v19
	v_mul_f32_e32 v20, v73, v20
	v_mul_f32_e32 v21, v77, v21
	s_waitcnt lgkmcnt(2)
	v_fmac_f32_e32 v18, v22, v74
	v_fmac_f32_e32 v19, v23, v78
	v_fmac_f32_e32 v20, v24, v75
	v_fmac_f32_e32 v21, v25, v79
	s_waitcnt lgkmcnt(1)
	v_fmac_f32_e32 v18, v26, v80
	v_fmac_f32_e32 v19, v27, v88
	v_fmac_f32_e32 v20, v28, v81
	v_fmac_f32_e32 v21, v29, v89
	s_waitcnt lgkmcnt(0)
	v_fmac_f32_e32 v18, v34, v86
	v_fmac_f32_e32 v19, v35, v92
	v_fmac_f32_e32 v20, v36, v87
	v_fmac_f32_e32 v21, v37, v93
	v_add_f32_e32 v18, v18, v19
	v_add_f32_e32 v19, v20, v21
	v_add_f32_e32 v18, v18, v19
	v_mul_f32_e64 v19, |v18|, s79
	v_exp_f32_e32 v19, v19
	v_min_f32_e32 v18, 0, v18
	v_add_f32_e32 v19, 1.0, v19
	v_log_f32_e32 v19, v19
	s_nop 0
	v_fma_f32 v42, v18, s80, -v19
	ds_read_b128 v[18:21], v32 offset:640
	ds_read_b128 v[22:25], v32 offset:656
	ds_read_b128 v[26:29], v32 offset:672
	ds_read_b128 v[34:37], v32 offset:688
	s_waitcnt lgkmcnt(3)
	v_fma_f32 v18, v18, v85, v123
	v_mul_f32_e32 v19, v76, v19
	v_mul_f32_e32 v20, v73, v20
	v_mul_f32_e32 v21, v77, v21
	s_waitcnt lgkmcnt(2)
	v_fmac_f32_e32 v18, v22, v74
	v_fmac_f32_e32 v19, v23, v78
	v_fmac_f32_e32 v20, v24, v75
	v_fmac_f32_e32 v21, v25, v79
	s_waitcnt lgkmcnt(1)
	v_fmac_f32_e32 v18, v26, v80
	v_fmac_f32_e32 v19, v27, v88
	v_fmac_f32_e32 v20, v28, v81
	v_fmac_f32_e32 v21, v29, v89
	s_waitcnt lgkmcnt(0)
; template <int DIR>
; DI float prep_gate_loop(const float* r_s, bf16_t* qt, bf16_t* kt, const float (&w)[16], float bias, int kk) {
;     ...
;         for (int i = 0; i < 16; ++i) {
;             const int tt = blk * 16 + i; const int t = DIR ? 63 - tt : tt;
;             const f32x4* rr = (const f32x4*)(r_s + t * 32 + DIR * 16);
;             const f32x4 r0 = rr[0], r1 = rr[1], r2 = rr[2], r3 = rr[3];
;             float s0 = __builtin_fmaf(r0[0], w[0], bias), s1 = r0[1] * w[1], s2 = r0[2] * w[2], s3 = r0[3] * w[3];
;             s0 = __builtin_fmaf(r1[0], w[4], s0); s1 = __builtin_fmaf(r1[1], w[5], s1); s2 = __builtin_fmaf(r1[2], w[6], s2); s3 = __builtin_fmaf(r1[3], w[7], s3);
;             s0 = __builtin_fmaf(r2[0], w[8], s0); s1 = __builtin_fmaf(r2[1], w[9], s1); s2 = __builtin_fmaf(r2[2], w[10], s2); s3 = __builtin_fmaf(r2[3], w[11], s3);
;             s0 = __builtin_fmaf(r3[0], w[12], s0); s1 = __builtin_fmaf(r3[1], w[13], s1); s2 = __builtin_fmaf(r3[2], w[14], s2); s3 = __builtin_fmaf(r3[3], w[15], s3);
;             const float pre = (s0 + s1) + (s2 + s3);
;             const float ex = __builtin_amdgcn_exp2f(-fabsf(pre) * LOG2E);
;             la[i] = (fminf(pre, 0.f) * LOG2E - __builtin_amdgcn_logf(1.f + ex)) * 0.0625f;
;         }
	v_fmac_f32_e32 v18, v34, v86
	v_fmac_f32_e32 v19, v35, v92
	v_fmac_f32_e32 v20, v36, v87
	v_fmac_f32_e32 v21, v37, v93
	v_add_f32_e32 v18, v18, v19
	v_add_f32_e32 v19, v20, v21
	v_add_f32_e32 v18, v18, v19
	v_mul_f32_e64 v19, |v18|, s79
	v_exp_f32_e32 v19, v19
	v_min_f32_e32 v18, 0, v18
	v_add_f32_e32 v19, 1.0, v19
	v_log_f32_e32 v19, v19
	s_nop 0
	v_fma_f32 v43, v18, s80, -v19
	ds_read_b128 v[18:21], v32 offset:768
	ds_read_b128 v[22:25], v32 offset:784
	ds_read_b128 v[26:29], v32 offset:800
	ds_read_b128 v[34:37], v32 offset:816
	s_waitcnt lgkmcnt(3)
	v_fma_f32 v18, v18, v85, v123
	v_mul_f32_e32 v19, v76, v19
	v_mul_f32_e32 v20, v73, v20
	v_mul_f32_e32 v21, v77, v21
	s_waitcnt lgkmcnt(2)
	v_fmac_f32_e32 v18, v22, v74
	v_fmac_f32_e32 v19, v23, v78
	v_fmac_f32_e32 v20, v24, v75
	v_fmac_f32_e32 v21, v25, v79
	s_waitcnt lgkmcnt(1)
	v_fmac_f32_e32 v18, v26, v80
	v_fmac_f32_e32 v19, v27, v88
	v_fmac_f32_e32 v20, v28, v81
	v_fmac_f32_e32 v21, v29, v89
	s_waitcnt lgkmcnt(0)
	v_fmac_f32_e32 v18, v34, v86
	v_fmac_f32_e32 v19, v35, v92
	v_fmac_f32_e32 v20, v36, v87
	v_fmac_f32_e32 v21, v37, v93
	v_add_f32_e32 v18, v18, v19
	v_add_f32_e32 v19, v20, v21
	v_add_f32_e32 v18, v18, v19
	v_mul_f32_e64 v19, |v18|, s79
	v_exp_f32_e32 v19, v19
	v_min_f32_e32 v18, 0, v18
	v_add_f32_e32 v19, 1.0, v19
	v_log_f32_e32 v19, v19
	s_nop 0
	v_fma_f32 v44, v18, s80, -v19
	ds_read_b128 v[18:21], v32 offset:896
	ds_read_b128 v[22:25], v32 offset:912
	ds_read_b128 v[26:29], v32 offset:928
	ds_read_b128 v[34:37], v32 offset:944
	s_waitcnt lgkmcnt(3)
	v_fma_f32 v18, v18, v85, v123
	v_mul_f32_e32 v19, v76, v19
	v_mul_f32_e32 v20, v73, v20
	v_mul_f32_e32 v21, v77, v21
	s_waitcnt lgkmcnt(2)
	v_fmac_f32_e32 v18, v22, v74
	v_fmac_f32_e32 v19, v23, v78
	v_fmac_f32_e32 v20, v24, v75
	v_fmac_f32_e32 v21, v25, v79
	s_waitcnt lgkmcnt(1)
	v_fmac_f32_e32 v18, v26, v80
	v_fmac_f32_e32 v19, v27, v88
	v_fmac_f32_e32 v20, v28, v81
	v_fmac_f32_e32 v21, v29, v89
	s_waitcnt lgkmcnt(0)
	v_fmac_f32_e32 v18, v34, v86
	v_fmac_f32_e32 v19, v35, v92
	v_fmac_f32_e32 v20, v36, v87
	v_fmac_f32_e32 v21, v37, v93
	v_add_f32_e32 v18, v18, v19
	v_add_f32_e32 v19, v20, v21
	v_add_f32_e32 v18, v18, v19
	v_mul_f32_e64 v19, |v18|, s79
	v_exp_f32_e32 v19, v19
	v_min_f32_e32 v18, 0, v18
	v_add_f32_e32 v19, 1.0, v19
	v_log_f32_e32 v19, v19
	s_nop 0
	v_fma_f32 v45, v18, s80, -v19
	ds_read_b128 v[18:21], v32 offset:1024
	ds_read_b128 v[22:25], v32 offset:1040
	ds_read_b128 v[26:29], v32 offset:1056
	ds_read_b128 v[34:37], v32 offset:1072
	s_waitcnt lgkmcnt(3)
	v_fma_f32 v18, v18, v85, v123
	v_mul_f32_e32 v19, v76, v19
	v_mul_f32_e32 v20, v73, v20
	v_mul_f32_e32 v21, v77, v21
	s_waitcnt lgkmcnt(2)
	v_fmac_f32_e32 v18, v22, v74
	v_fmac_f32_e32 v19, v23, v78
	v_fmac_f32_e32 v20, v24, v75
	v_fmac_f32_e32 v21, v25, v79
	s_waitcnt lgkmcnt(1)
	v_fmac_f32_e32 v18, v26, v80
	v_fmac_f32_e32 v19, v27, v88
	v_fmac_f32_e32 v20, v28, v81
	v_fmac_f32_e32 v21, v29, v89
	s_waitcnt lgkmcnt(0)
	v_fmac_f32_e32 v18, v34, v86
	v_fmac_f32_e32 v19, v35, v92
	v_fmac_f32_e32 v20, v36, v87
	v_fmac_f32_e32 v21, v37, v93
	v_add_f32_e32 v18, v18, v19
	v_add_f32_e32 v19, v20, v21
	v_add_f32_e32 v18, v18, v19
	v_mul_f32_e64 v19, |v18|, s79
	v_exp_f32_e32 v19, v19
	v_min_f32_e32 v18, 0, v18
	v_add_f32_e32 v19, 1.0, v19
	v_log_f32_e32 v19, v19
	s_nop 0
	v_fma_f32 v46, v18, s80, -v19
	ds_read_b128 v[18:21], v32 offset:1152
	ds_read_b128 v[22:25], v32 offset:1168
	ds_read_b128 v[26:29], v32 offset:1184
	ds_read_b128 v[34:37], v32 offset:1200
	s_waitcnt lgkmcnt(3)
	v_mul_f32_e32 v31, v73, v20
	v_mov_b32_e32 v20, v19
	v_fma_f32 v30, v18, v85, v123
	v_mul_f32_e32 v18, v76, v20
	v_mul_f32_e32 v19, v77, v21
	s_waitcnt lgkmcnt(2)
	v_mov_b32_e32 v20, v22
	v_mov_b32_e32 v21, v24
	v_mov_b32_e32 v24, v23
	v_fma_f32 v20, v20, v74, v30
	v_fma_f32 v21, v21, v75, v31
	v_fmac_f32_e32 v18, v24, v78
	v_fmac_f32_e32 v19, v25, v79
	s_waitcnt lgkmcnt(1)
	v_mov_b32_e32 v22, v26
	v_mov_b32_e32 v23, v28
	v_mov_b32_e32 v28, v27
	v_fmac_f32_e32 v20, v22, v80
	v_fmac_f32_e32 v21, v23, v81
	v_fmac_f32_e32 v18, v28, v88
	v_fmac_f32_e32 v19, v29, v89
	s_waitcnt lgkmcnt(0)
	v_mov_b32_e32 v22, v34
	v_mov_b32_e32 v23, v36
	v_mov_b32_e32 v36, v35
	v_fmac_f32_e32 v20, v22, v86
	v_fmac_f32_e32 v21, v23, v87
	v_fmac_f32_e32 v18, v36, v92
	v_fmac_f32_e32 v19, v37, v93
	s_nop 0
	v_add_f32_e32 v18, v20, v18
	v_add_f32_e32 v19, v21, v19
	s_nop 0
	v_add_f32_e32 v18, v18, v19
	v_mul_f32_e64 v19, |v18|, s79
	v_exp_f32_e32 v19, v19
	v_min_f32_e32 v18, 0, v18
	v_add_f32_e32 v19, 1.0, v19
	v_log_f32_e32 v19, v19
	s_nop 0
	v_fma_f32 v47, v18, s80, -v19
	ds_read_b128 v[18:21], v32 offset:1280
	ds_read_b128 v[22:25], v32 offset:1296
	ds_read_b128 v[26:29], v32 offset:1312
	ds_read_b128 v[34:37], v32 offset:1328
	s_waitcnt lgkmcnt(3)
	v_mul_f32_e32 v31, v73, v20
	v_mov_b32_e32 v20, v19
	v_fma_f32 v30, v18, v85, v123
	v_mul_f32_e32 v18, v76, v20
	v_mul_f32_e32 v19, v77, v21
	s_waitcnt lgkmcnt(2)
	v_mov_b32_e32 v20, v22
	v_mov_b32_e32 v21, v24
	v_mov_b32_e32 v24, v23
	v_fma_f32 v20, v20, v74, v30
	v_fma_f32 v21, v21, v75, v31
	v_fmac_f32_e32 v18, v24, v78
	v_fmac_f32_e32 v19, v25, v79
	s_waitcnt lgkmcnt(1)
	v_mov_b32_e32 v22, v26
	v_mov_b32_e32 v23, v28
	v_mov_b32_e32 v28, v27
	v_fmac_f32_e32 v20, v22, v80
	v_fmac_f32_e32 v21, v23, v81
	v_fmac_f32_e32 v18, v28, v88
	v_fmac_f32_e32 v19, v29, v89
	s_waitcnt lgkmcnt(0)
; template <int DIR>
; DI float prep_gate_loop(const float* r_s, bf16_t* qt, bf16_t* kt, const float (&w)[16], float bias, int kk) {
;     ...
;         for (int i = 0; i < 16; ++i) {
;             const int tt = blk * 16 + i; const int t = DIR ? 63 - tt : tt;
;             const f32x4* rr = (const f32x4*)(r_s + t * 32 + DIR * 16);
;             const f32x4 r0 = rr[0], r1 = rr[1], r2 = rr[2], r3 = rr[3];
;             float s0 = __builtin_fmaf(r0[0], w[0], bias), s1 = r0[1] * w[1], s2 = r0[2] * w[2], s3 = r0[3] * w[3];
;             s0 = __builtin_fmaf(r1[0], w[4], s0); s1 = __builtin_fmaf(r1[1], w[5], s1); s2 = __builtin_fmaf(r1[2], w[6], s2); s3 = __builtin_fmaf(r1[3], w[7], s3);
;             s0 = __builtin_fmaf(r2[0], w[8], s0); s1 = __builtin_fmaf(r2[1], w[9], s1); s2 = __builtin_fmaf(r2[2], w[10], s2); s3 = __builtin_fmaf(r2[3], w[11], s3);
;             s0 = __builtin_fmaf(r3[0], w[12], s0); s1 = __builtin_fmaf(r3[1], w[13], s1); s2 = __builtin_fmaf(r3[2], w[14], s2); s3 = __builtin_fmaf(r3[3], w[15], s3);
;             const float pre = (s0 + s1) + (s2 + s3);
;             const float ex = __builtin_amdgcn_exp2f(-fabsf(pre) * LOG2E);
;             la[i] = (fminf(pre, 0.f) * LOG2E - __builtin_amdgcn_logf(1.f + ex)) * 0.0625f;
;         }
	v_mov_b32_e32 v22, v34
	v_mov_b32_e32 v23, v36
	v_mov_b32_e32 v36, v35
	v_fmac_f32_e32 v20, v22, v86
	v_fmac_f32_e32 v21, v23, v87
	v_fmac_f32_e32 v18, v36, v92
	v_fmac_f32_e32 v19, v37, v93
	s_nop 0
	v_add_f32_e32 v18, v20, v18
	v_add_f32_e32 v19, v21, v19
	s_nop 0
	v_add_f32_e32 v18, v18, v19
	v_mul_f32_e64 v19, |v18|, s79
	v_exp_f32_e32 v19, v19
	v_min_f32_e32 v18, 0, v18
	v_add_f32_e32 v19, 1.0, v19
	v_log_f32_e32 v19, v19
	s_nop 0
	v_fma_f32 v48, v18, s80, -v19
	ds_read_b128 v[18:21], v32 offset:1408
	ds_read_b128 v[22:25], v32 offset:1424
	ds_read_b128 v[26:29], v32 offset:1440
	ds_read_b128 v[34:37], v32 offset:1456
	s_waitcnt lgkmcnt(3)
	v_mul_f32_e32 v31, v73, v20
	v_mov_b32_e32 v20, v19
	v_fma_f32 v30, v18, v85, v123
	v_mul_f32_e32 v18, v76, v20
	v_mul_f32_e32 v19, v77, v21
	s_waitcnt lgkmcnt(2)
	v_mov_b32_e32 v20, v22
	v_mov_b32_e32 v21, v24
	v_mov_b32_e32 v24, v23
	v_fma_f32 v20, v20, v74, v30
	v_fma_f32 v21, v21, v75, v31
	v_fmac_f32_e32 v18, v24, v78
	v_fmac_f32_e32 v19, v25, v79
	s_waitcnt lgkmcnt(1)
	v_mov_b32_e32 v22, v26
	v_mov_b32_e32 v23, v28
	v_mov_b32_e32 v28, v27
	v_fmac_f32_e32 v20, v22, v80
	v_fmac_f32_e32 v21, v23, v81
	v_fmac_f32_e32 v18, v28, v88
	v_fmac_f32_e32 v19, v29, v89
	s_waitcnt lgkmcnt(0)
	v_mov_b32_e32 v22, v34
	v_mov_b32_e32 v23, v36
	v_mov_b32_e32 v36, v35
	v_fmac_f32_e32 v20, v22, v86
	v_fmac_f32_e32 v21, v23, v87
	v_fmac_f32_e32 v18, v36, v92
	v_fmac_f32_e32 v19, v37, v93
	s_nop 0
	v_add_f32_e32 v18, v20, v18
	v_add_f32_e32 v19, v21, v19
	s_nop 0
	v_add_f32_e32 v18, v18, v19
	v_mul_f32_e64 v19, |v18|, s79
	v_exp_f32_e32 v19, v19
	v_min_f32_e32 v18, 0, v18
	v_add_f32_e32 v19, 1.0, v19
	v_log_f32_e32 v19, v19
	s_nop 0
	v_fma_f32 v49, v18, s80, -v19
	ds_read_b128 v[18:21], v32 offset:1536
	ds_read_b128 v[22:25], v32 offset:1552
	ds_read_b128 v[26:29], v32 offset:1568
	ds_read_b128 v[34:37], v32 offset:1584
	s_waitcnt lgkmcnt(3)
	v_mul_f32_e32 v31, v73, v20
	v_mov_b32_e32 v20, v19
	v_fma_f32 v30, v18, v85, v123
	v_mul_f32_e32 v18, v76, v20
	v_mul_f32_e32 v19, v77, v21
	s_waitcnt lgkmcnt(2)
	v_mov_b32_e32 v20, v22
	v_mov_b32_e32 v21, v24
	v_mov_b32_e32 v24, v23
	v_fma_f32 v20, v20, v74, v30
	v_fma_f32 v21, v21, v75, v31
	v_fmac_f32_e32 v18, v24, v78
	v_fmac_f32_e32 v19, v25, v79
	s_waitcnt lgkmcnt(1)
	v_mov_b32_e32 v22, v26
	v_mov_b32_e32 v23, v28
	v_mov_b32_e32 v28, v27
	v_fmac_f32_e32 v20, v22, v80
	v_fmac_f32_e32 v21, v23, v81
	v_fmac_f32_e32 v18, v28, v88
	v_fmac_f32_e32 v19, v29, v89
	s_waitcnt lgkmcnt(0)
	v_mov_b32_e32 v22, v34
	v_mov_b32_e32 v23, v36
	v_mov_b32_e32 v36, v35
	v_fmac_f32_e32 v20, v22, v86
	v_fmac_f32_e32 v21, v23, v87
	v_fmac_f32_e32 v18, v36, v92
	v_fmac_f32_e32 v19, v37, v93
	s_nop 0
	v_add_f32_e32 v18, v20, v18
	v_add_f32_e32 v19, v21, v19
	s_nop 0
	v_add_f32_e32 v18, v18, v19
	v_mul_f32_e64 v19, |v18|, s79
	v_exp_f32_e32 v19, v19
	v_min_f32_e32 v18, 0, v18
	v_add_f32_e32 v19, 1.0, v19
	v_log_f32_e32 v19, v19
	s_nop 0
	v_fma_f32 v50, v18, s80, -v19
	ds_read_b128 v[18:21], v32 offset:1664
	ds_read_b128 v[22:25], v32 offset:1680
	ds_read_b128 v[26:29], v32 offset:1696
	ds_read_b128 v[34:37], v32 offset:1712
	s_waitcnt lgkmcnt(3)
	v_mul_f32_e32 v31, v73, v20
	v_mov_b32_e32 v20, v19
	v_fma_f32 v30, v18, v85, v123
	v_mul_f32_e32 v18, v76, v20
	v_mul_f32_e32 v19, v77, v21
	s_waitcnt lgkmcnt(2)
	v_mov_b32_e32 v20, v22
	v_mov_b32_e32 v21, v24
	v_mov_b32_e32 v24, v23
	v_fma_f32 v20, v20, v74, v30
	v_fma_f32 v21, v21, v75, v31
	v_fmac_f32_e32 v18, v24, v78
	v_fmac_f32_e32 v19, v25, v79
	s_waitcnt lgkmcnt(1)
	v_mov_b32_e32 v22, v26
	v_mov_b32_e32 v23, v28
	v_mov_b32_e32 v28, v27
	v_fmac_f32_e32 v20, v22, v80
	v_fmac_f32_e32 v21, v23, v81
	v_fmac_f32_e32 v18, v28, v88
	v_fmac_f32_e32 v19, v29, v89
	s_waitcnt lgkmcnt(0)
	v_mov_b32_e32 v22, v34
	v_mov_b32_e32 v23, v36
	v_mov_b32_e32 v36, v35
	v_fmac_f32_e32 v20, v22, v86
	v_fmac_f32_e32 v21, v23, v87
	v_fmac_f32_e32 v18, v36, v92
	v_fmac_f32_e32 v19, v37, v93
	s_nop 0
	v_add_f32_e32 v18, v20, v18
	v_add_f32_e32 v19, v21, v19
	s_nop 0
	v_add_f32_e32 v18, v18, v19
	v_mul_f32_e64 v19, |v18|, s79
	v_exp_f32_e32 v19, v19
	v_min_f32_e32 v18, 0, v18
	v_add_f32_e32 v19, 1.0, v19
	v_log_f32_e32 v19, v19
	s_nop 0
	v_fma_f32 v51, v18, s80, -v19
	ds_read_b128 v[18:21], v32 offset:1792
	ds_read_b128 v[22:25], v32 offset:1808
	ds_read_b128 v[26:29], v32 offset:1824
	ds_read_b128 v[34:37], v32 offset:1840
	s_waitcnt lgkmcnt(3)
	v_mul_f32_e32 v31, v73, v20
	v_mov_b32_e32 v20, v19
	v_fma_f32 v30, v18, v85, v123
	v_mul_f32_e32 v18, v76, v20
	v_mul_f32_e32 v19, v77, v21
	s_waitcnt lgkmcnt(2)
	v_mov_b32_e32 v20, v22
	v_mov_b32_e32 v21, v24
	v_mov_b32_e32 v24, v23
	v_fma_f32 v20, v20, v74, v30
	v_fma_f32 v21, v21, v75, v31
	v_fmac_f32_e32 v18, v24, v78
	v_fmac_f32_e32 v19, v25, v79
	s_waitcnt lgkmcnt(1)
	v_mov_b32_e32 v22, v26
	v_mov_b32_e32 v23, v28
	v_mov_b32_e32 v28, v27
	v_fmac_f32_e32 v20, v22, v80
	v_fmac_f32_e32 v21, v23, v81
	v_fmac_f32_e32 v18, v28, v88
	v_fmac_f32_e32 v19, v29, v89
	s_waitcnt lgkmcnt(0)
	v_mov_b32_e32 v22, v34
	v_mov_b32_e32 v23, v36
	v_mov_b32_e32 v36, v35
	v_fmac_f32_e32 v20, v22, v86
	v_fmac_f32_e32 v21, v23, v87
	v_fmac_f32_e32 v18, v36, v92
	v_fmac_f32_e32 v19, v37, v93
	s_nop 0
	v_add_f32_e32 v18, v20, v18
	v_add_f32_e32 v19, v21, v19
	s_nop 0
	v_add_f32_e32 v18, v18, v19
	v_mul_f32_e64 v19, |v18|, s79
	v_exp_f32_e32 v19, v19
	v_min_f32_e32 v18, 0, v18
	v_add_f32_e32 v19, 1.0, v19
	v_log_f32_e32 v19, v19
	s_nop 0
	v_fma_f32 v52, v18, s80, -v19
	ds_read_b128 v[18:21], v32 offset:1920
	ds_read_b128 v[22:25], v32 offset:1936
	ds_read_b128 v[26:29], v32 offset:1952
	ds_read_b128 v[34:37], v32 offset:1968
	v_fmamk_f32 v32, v39, 0x3d800000, v33
	s_waitcnt lgkmcnt(3)
; DI float bf2f(bf16_t b) { return __uint_as_float(((unsigned)b) << 16); }
; DI bf16_t f2bf(float f) { return (bf16_t)(pk2(f, 0.f) & 0xffffu); }
; template <int DIR>
; DI float prep_gate_loop(const float* r_s, bf16_t* qt, bf16_t* kt, const float (&w)[16], float bias, int kk) {
;     ...
;             const int tt = blk * 16 + i; const int t = DIR ? 63 - tt : tt;
;             const f32x4* rr = (const f32x4*)(r_s + t * 32 + DIR * 16);
;             const f32x4 r0 = rr[0], r1 = rr[1], r2 = rr[2], r3 = rr[3];
;             float s0 = __builtin_fmaf(r0[0], w[0], bias), s1 = r0[1] * w[1], s2 = r0[2] * w[2], s3 = r0[3] * w[3];
;             s0 = __builtin_fmaf(r1[0], w[4], s0); s1 = __builtin_fmaf(r1[1], w[5], s1); s2 = __builtin_fmaf(r1[2], w[6], s2); s3 = __builtin_fmaf(r1[3], w[7], s3);
;             s0 = __builtin_fmaf(r2[0], w[8], s0); s1 = __builtin_fmaf(r2[1], w[9], s1); s2 = __builtin_fmaf(r2[2], w[10], s2); s3 = __builtin_fmaf(r2[3], w[11], s3);
;             s0 = __builtin_fmaf(r3[0], w[12], s0); s1 = __builtin_fmaf(r3[1], w[13], s1); s2 = __builtin_fmaf(r3[2], w[14], s2); s3 = __builtin_fmaf(r3[3], w[15], s3);
;             const float pre = (s0 + s1) + (s2 + s3);
;             const float ex = __builtin_amdgcn_exp2f(-fabsf(pre) * LOG2E);
;             la[i] = (fminf(pre, 0.f) * LOG2E - __builtin_amdgcn_logf(1.f + ex)) * 0.0625f;
;         }
; #pragma unroll
;         for (int i = 0; i < 16; ++i) { g += la[i]; la[i] = g; }
; #pragma unroll
;         for (int i = 0; i < 16; ++i) {
;             const int tt = blk * 16 + i; const int t = DIR ? 63 - tt : tt;
;             const float e = __builtin_amdgcn_exp2f(la[i]);
;             bf16_t* qp = qt + (DIR * 64 + t) * 264 + kk; bf16_t* kp = kt + (DIR * 64 + t) * 264 + kk;
;             const float qv = bf2f(*qp), kv = bf2f(*kp);
;             *qp = f2bf(qv * 0.0625f * e);
;             *kp = f2bf(kv * __builtin_amdgcn_rcpf(e));
;         }
	v_mul_f32_e32 v31, v73, v20
	v_mov_b32_e32 v20, v19
	v_fma_f32 v30, v18, v85, v123
	v_mul_f32_e32 v18, v76, v20
	v_mul_f32_e32 v19, v77, v21
	s_waitcnt lgkmcnt(2)
	v_mov_b32_e32 v20, v22
	v_mov_b32_e32 v21, v24
	v_mov_b32_e32 v24, v23
	v_fma_f32 v20, v20, v74, v30
	v_fma_f32 v21, v21, v75, v31
	v_fmac_f32_e32 v18, v24, v78
	v_fmac_f32_e32 v19, v25, v79
	s_waitcnt lgkmcnt(1)
	v_mov_b32_e32 v22, v26
	v_mov_b32_e32 v23, v28
	v_mov_b32_e32 v28, v27
	v_fmac_f32_e32 v20, v22, v80
	v_fmac_f32_e32 v21, v23, v81
	v_fmac_f32_e32 v18, v28, v88
	v_fmac_f32_e32 v19, v29, v89
	s_waitcnt lgkmcnt(0)
	v_mov_b32_e32 v22, v34
	v_mov_b32_e32 v23, v36
	v_mov_b32_e32 v36, v35
	v_add_u32_e32 v34, s52, v120
	v_fmac_f32_e32 v18, v36, v92
	v_fmac_f32_e32 v19, v37, v93
	ds_read_u16 v36, v34 offset:8192
	v_exp_f32_e32 v33, v33
	v_add_u32_e32 v35, 0x12800, v34
	ds_read_u16 v37, v35
	v_fmamk_f32 v31, v40, 0x3d800000, v32
	s_waitcnt lgkmcnt(1)
	v_lshlrev_b32_e32 v36, 16, v36
	v_mul_f32_e32 v36, 0x3d800000, v36
	v_mul_f32_e32 v36, v33, v36
	v_rcp_f32_e32 v33, v33
	s_waitcnt lgkmcnt(0)
	v_lshlrev_b32_e32 v37, 16, v37
	v_exp_f32_e32 v32, v32
	v_cvt_pk_bf16_f32 v36, v36, s0
	v_mul_f32_e32 v33, v33, v37
	v_cvt_pk_bf16_f32 v33, v33, s0
	ds_write_b16 v35, v33
	ds_read_u16 v35, v34 offset:8720
	v_add_u32_e32 v33, 0x12a10, v34
	ds_write_b16 v34, v36 offset:8192
	ds_read_u16 v36, v33
	v_fmamk_f32 v30, v41, 0x3d800000, v31
	s_waitcnt lgkmcnt(2)
	v_lshlrev_b32_e32 v35, 16, v35
	v_mul_f32_e32 v35, 0x3d800000, v35
	v_mul_f32_e32 v35, v32, v35
	v_rcp_f32_e32 v32, v32
	s_waitcnt lgkmcnt(0)
	v_lshlrev_b32_e32 v36, 16, v36
	v_exp_f32_e32 v31, v31
	v_cvt_pk_bf16_f32 v35, v35, s0
	v_mul_f32_e32 v32, v32, v36
	v_cvt_pk_bf16_f32 v32, v32, s0
	ds_write_b16 v33, v32
	ds_read_u16 v33, v34 offset:9248
	v_add_u32_e32 v32, 0x12c20, v34
	ds_write_b16 v34, v35 offset:8720
	ds_read_u16 v35, v32
	v_fmamk_f32 v29, v42, 0x3d800000, v30
	s_waitcnt lgkmcnt(2)
	v_lshlrev_b32_e32 v33, 16, v33
	v_mul_f32_e32 v33, 0x3d800000, v33
	v_mul_f32_e32 v33, v31, v33
	v_rcp_f32_e32 v31, v31
	s_waitcnt lgkmcnt(0)
	v_lshlrev_b32_e32 v35, 16, v35
	v_exp_f32_e32 v30, v30
	v_cvt_pk_bf16_f32 v33, v33, s0
	v_mul_f32_e32 v31, v31, v35
	v_cvt_pk_bf16_f32 v31, v31, s0
	ds_write_b16 v32, v31
	ds_read_u16 v32, v34 offset:9776
	v_add_u32_e32 v31, 0x12e30, v34
	ds_write_b16 v34, v33 offset:9248
	ds_read_u16 v33, v31
	v_fmamk_f32 v28, v43, 0x3d800000, v29
	s_waitcnt lgkmcnt(2)
	v_lshlrev_b32_e32 v32, 16, v32
	v_mul_f32_e32 v32, 0x3d800000, v32
	v_mul_f32_e32 v32, v30, v32
	v_rcp_f32_e32 v30, v30
	s_waitcnt lgkmcnt(0)
	v_lshlrev_b32_e32 v33, 16, v33
	v_exp_f32_e32 v29, v29
	v_cvt_pk_bf16_f32 v32, v32, s0
	v_mul_f32_e32 v30, v30, v33
	v_cvt_pk_bf16_f32 v30, v30, s0
	ds_write_b16 v31, v30
	ds_read_u16 v31, v34 offset:10304
	v_add_u32_e32 v30, 0x13040, v34
	ds_write_b16 v34, v32 offset:9776
	ds_read_u16 v32, v30
	v_fmamk_f32 v27, v44, 0x3d800000, v28
	s_waitcnt lgkmcnt(2)
	v_lshlrev_b32_e32 v31, 16, v31
	v_mul_f32_e32 v31, 0x3d800000, v31
	v_mul_f32_e32 v31, v29, v31
	v_rcp_f32_e32 v29, v29
	s_waitcnt lgkmcnt(0)
	v_lshlrev_b32_e32 v32, 16, v32
	v_exp_f32_e32 v28, v28
	v_cvt_pk_bf16_f32 v31, v31, s0
	v_mul_f32_e32 v29, v29, v32
	v_cvt_pk_bf16_f32 v29, v29, s0
	ds_write_b16 v30, v29
	ds_read_u16 v30, v34 offset:10832
	v_add_u32_e32 v29, 0x13250, v34
	ds_write_b16 v34, v31 offset:10304
	ds_read_u16 v31, v29
	v_fmamk_f32 v26, v45, 0x3d800000, v27
	s_waitcnt lgkmcnt(2)
	v_lshlrev_b32_e32 v30, 16, v30
	v_mul_f32_e32 v30, 0x3d800000, v30
	v_mul_f32_e32 v30, v28, v30
	v_rcp_f32_e32 v28, v28
	s_waitcnt lgkmcnt(0)
	v_lshlrev_b32_e32 v31, 16, v31
	v_exp_f32_e32 v27, v27
	v_cvt_pk_bf16_f32 v30, v30, s0
	v_mul_f32_e32 v28, v28, v31
	v_cvt_pk_bf16_f32 v28, v28, s0
	ds_write_b16 v29, v28
	ds_read_u16 v29, v34 offset:11360
	v_add_u32_e32 v28, 0x13460, v34
	ds_write_b16 v34, v30 offset:10832
	ds_read_u16 v30, v28
	v_fmamk_f32 v25, v46, 0x3d800000, v26
	s_waitcnt lgkmcnt(2)
	v_lshlrev_b32_e32 v29, 16, v29
	v_mul_f32_e32 v29, 0x3d800000, v29
	v_mul_f32_e32 v29, v27, v29
	v_rcp_f32_e32 v27, v27
	s_waitcnt lgkmcnt(0)
	v_lshlrev_b32_e32 v30, 16, v30
	v_exp_f32_e32 v26, v26
	v_cvt_pk_bf16_f32 v29, v29, s0
	v_mul_f32_e32 v27, v27, v30
	v_cvt_pk_bf16_f32 v27, v27, s0
	ds_write_b16 v28, v27
	ds_read_u16 v28, v34 offset:11888
	v_add_u32_e32 v27, 0x13670, v34
	ds_write_b16 v34, v29 offset:11360
	ds_read_u16 v29, v27
	v_fmamk_f32 v24, v47, 0x3d800000, v25
	s_waitcnt lgkmcnt(2)
	v_lshlrev_b32_e32 v28, 16, v28
	v_mul_f32_e32 v28, 0x3d800000, v28
	v_mul_f32_e32 v28, v26, v28
	v_rcp_f32_e32 v26, v26
	s_waitcnt lgkmcnt(0)
; DI float bf2f(bf16_t b) { return __uint_as_float(((unsigned)b) << 16); }
; DI bf16_t f2bf(float f) { return (bf16_t)(pk2(f, 0.f) & 0xffffu); }
; template <int DIR>
; DI float prep_gate_loop(const float* r_s, bf16_t* qt, bf16_t* kt, const float (&w)[16], float bias, int kk) {
;     ...
;             const float pre = (s0 + s1) + (s2 + s3);
;             const float ex = __builtin_amdgcn_exp2f(-fabsf(pre) * LOG2E);
;             la[i] = (fminf(pre, 0.f) * LOG2E - __builtin_amdgcn_logf(1.f + ex)) * 0.0625f;
;         }
; #pragma unroll
;         for (int i = 0; i < 16; ++i) { g += la[i]; la[i] = g; }
; #pragma unroll
;         for (int i = 0; i < 16; ++i) {
;             const int tt = blk * 16 + i; const int t = DIR ? 63 - tt : tt;
;             const float e = __builtin_amdgcn_exp2f(la[i]);
;             bf16_t* qp = qt + (DIR * 64 + t) * 264 + kk; bf16_t* kp = kt + (DIR * 64 + t) * 264 + kk;
;             const float qv = bf2f(*qp), kv = bf2f(*kp);
;             *qp = f2bf(qv * 0.0625f * e);
;             *kp = f2bf(kv * __builtin_amdgcn_rcpf(e));
;         }
	v_lshlrev_b32_e32 v29, 16, v29
	v_exp_f32_e32 v25, v25
	v_cvt_pk_bf16_f32 v28, v28, s0
	v_mul_f32_e32 v26, v26, v29
	v_cvt_pk_bf16_f32 v26, v26, s0
	ds_write_b16 v27, v26
	ds_read_u16 v27, v34 offset:12416
	v_add_u32_e32 v26, 0x13880, v34
	ds_write_b16 v34, v28 offset:11888
	ds_read_u16 v28, v26
	v_fmac_f32_e32 v20, v22, v86
	v_fmac_f32_e32 v21, v23, v87
	s_waitcnt lgkmcnt(2)
	v_lshlrev_b32_e32 v27, 16, v27
	v_mul_f32_e32 v27, 0x3d800000, v27
	v_mul_f32_e32 v27, v25, v27
	v_rcp_f32_e32 v25, v25
	s_waitcnt lgkmcnt(0)
	v_lshlrev_b32_e32 v28, 16, v28
	v_fmamk_f32 v23, v48, 0x3d800000, v24
	v_exp_f32_e32 v24, v24
	v_mul_f32_e32 v25, v25, v28
	v_cvt_pk_bf16_f32 v25, v25, s0
	ds_write_b16 v26, v25
	ds_read_u16 v26, v34 offset:12944
	v_cvt_pk_bf16_f32 v27, v27, s0
	v_add_u32_e32 v25, 0x13a90, v34
	ds_write_b16 v34, v27 offset:12416
	ds_read_u16 v27, v25
	s_waitcnt lgkmcnt(2)
	v_lshlrev_b32_e32 v26, 16, v26
	v_mul_f32_e32 v26, 0x3d800000, v26
	v_mul_f32_e32 v26, v24, v26
	v_rcp_f32_e32 v24, v24
	s_waitcnt lgkmcnt(0)
	v_lshlrev_b32_e32 v27, 16, v27
	v_fmamk_f32 v22, v49, 0x3d800000, v23
	v_exp_f32_e32 v23, v23
	v_mul_f32_e32 v24, v24, v27
	v_cvt_pk_bf16_f32 v24, v24, s0
	ds_write_b16 v25, v24
	ds_read_u16 v25, v34 offset:13472
	v_cvt_pk_bf16_f32 v26, v26, s0
	v_add_u32_e32 v24, 0x13ca0, v34
	ds_write_b16 v34, v26 offset:12944
	ds_read_u16 v26, v24
	s_waitcnt lgkmcnt(2)
	v_lshlrev_b32_e32 v25, 16, v25
	v_mul_f32_e32 v25, 0x3d800000, v25
	v_mul_f32_e32 v25, v23, v25
	v_rcp_f32_e32 v23, v23
	s_waitcnt lgkmcnt(0)
	v_lshlrev_b32_e32 v26, 16, v26
	v_add_f32_e32 v18, v20, v18
	v_add_f32_e32 v19, v21, v19
	v_fmamk_f32 v21, v50, 0x3d800000, v22
	v_mul_f32_e32 v23, v23, v26
	v_cvt_pk_bf16_f32 v23, v23, s0
	ds_write_b16 v24, v23
	ds_read_u16 v24, v34 offset:14000
	v_exp_f32_e32 v22, v22
	v_cvt_pk_bf16_f32 v25, v25, s0
	v_add_u32_e32 v23, 0x13eb0, v34
	ds_write_b16 v34, v25 offset:13472
	ds_read_u16 v25, v23
	s_waitcnt lgkmcnt(2)
	v_lshlrev_b32_e32 v24, 16, v24
	v_mul_f32_e32 v24, 0x3d800000, v24
	v_mul_f32_e32 v24, v22, v24
	v_rcp_f32_e32 v22, v22
	s_waitcnt lgkmcnt(0)
	v_lshlrev_b32_e32 v25, 16, v25
	v_fmamk_f32 v20, v51, 0x3d800000, v21
	v_exp_f32_e32 v21, v21
	v_mul_f32_e32 v22, v22, v25
	v_cvt_pk_bf16_f32 v22, v22, s0
	ds_write_b16 v23, v22
	ds_read_u16 v23, v34 offset:14528
	v_cvt_pk_bf16_f32 v24, v24, s0
	v_add_u32_e32 v22, 0x140c0, v34
	v_add_f32_e32 v18, v18, v19
	ds_write_b16 v34, v24 offset:14000
	ds_read_u16 v24, v22
	s_waitcnt lgkmcnt(2)
	v_lshlrev_b32_e32 v23, 16, v23
	v_mul_f32_e64 v19, |v18|, s79
	v_mul_f32_e32 v23, 0x3d800000, v23
	v_exp_f32_e32 v19, v19
	v_mul_f32_e32 v23, v21, v23
	v_rcp_f32_e32 v21, v21
	s_waitcnt lgkmcnt(0)
	v_lshlrev_b32_e32 v24, 16, v24
	v_add_f32_e32 v19, 1.0, v19
	v_log_f32_e32 v19, v19
	v_mul_f32_e32 v21, v21, v24
	v_cvt_pk_bf16_f32 v21, v21, s0
	ds_write_b16 v22, v21
	ds_read_u16 v22, v34 offset:15056
	v_min_f32_e32 v18, 0, v18
	v_fma_f32 v18, v18, s80, -v19
	v_fmamk_f32 v19, v52, 0x3d800000, v20
	v_exp_f32_e32 v20, v20
	v_cvt_pk_bf16_f32 v23, v23, s0
	v_add_u32_e32 v21, 0x142d0, v34
	ds_write_b16 v34, v23 offset:14528
	ds_read_u16 v23, v21
	s_waitcnt lgkmcnt(2)
	v_lshlrev_b32_e32 v22, 16, v22
	v_mul_f32_e32 v22, 0x3d800000, v22
	v_mul_f32_e32 v22, v20, v22
	v_rcp_f32_e32 v20, v20
	s_waitcnt lgkmcnt(0)
	v_lshlrev_b32_e32 v23, 16, v23
	v_fmamk_f32 v18, v18, 0x3d800000, v19
	v_exp_f32_e32 v19, v19
	v_mul_f32_e32 v20, v20, v23
	v_cvt_pk_bf16_f32 v20, v20, s0
	ds_write_b16 v21, v20
	ds_read_u16 v21, v34 offset:15584
	v_cvt_pk_bf16_f32 v22, v22, s0
	v_add_u32_e32 v20, 0x144e0, v34
	ds_write_b16 v34, v22 offset:15056
	ds_read_u16 v22, v20
	s_waitcnt lgkmcnt(2)
	v_lshlrev_b32_e32 v21, 16, v21
	v_mul_f32_e32 v21, 0x3d800000, v21
	v_mul_f32_e32 v21, v19, v21
	v_rcp_f32_e32 v19, v19
	s_waitcnt lgkmcnt(0)
	v_lshlrev_b32_e32 v22, 16, v22
	v_exp_f32_e32 v112, v18
	v_cvt_pk_bf16_f32 v21, v21, s0
	v_mul_f32_e32 v19, v19, v22
	v_cvt_pk_bf16_f32 v19, v19, s0
	ds_write_b16 v20, v19
	ds_read_u16 v20, v34 offset:16112
	v_add_u32_e32 v19, 0x146f0, v34
	ds_write_b16 v34, v21 offset:15584
	ds_read_u16 v21, v19
	s_addk_i32 s52, 0x2100
	s_waitcnt lgkmcnt(2)
	v_lshlrev_b32_e32 v20, 16, v20
	v_mul_f32_e32 v20, 0x3d800000, v20
	v_mul_f32_e32 v20, v112, v20
	v_cvt_pk_bf16_f32 v20, v20, s0
	ds_write_b16 v34, v20 offset:16112
	v_rcp_f32_e32 v20, v112
	s_waitcnt lgkmcnt(1)
	v_lshlrev_b32_e32 v21, 16, v21
	s_cmpk_eq_u32 s52, 0x8400
	v_mov_b32_e32 v33, v18
	v_mul_f32_e32 v20, v20, v21
	v_cvt_pk_bf16_f32 v20, v20, s0
	ds_write_b16 v19, v20
	s_cbranch_scc0 .LBB0_1539
	s_branch .LBB0_1532
